# strategy 6 LDS bank conflicts: FA K tile swizzled by row&15 (was row&7) so ds_read_b128 groups hit 64 banks; second-half fragment reads via xor 0x80
# baseline (speedup 1.0000x reference)
; #define LAS __attribute__((address_space(3)))
; template <int KIND>
; __device__ __forceinline__ void run_unit(LAS char* lds, const UnitArgs& U, int tid_in) {
;     constexpr bool MLA = KIND == K_MLA;
;     int tid = tid_in; asm volatile("" : "+v"(tid));
;     const int wid = __builtin_amdgcn_readfirstlane(tid >> 6), lane = tid & 63, r32 = lane & 31, hi = lane >> 5;
;     const int sr = tid >> 4, sc = (tid & 15) * 8;
;     const int qlo = U.P0 + wid * 32, rowpos = qlo + r32;
;     const float sc_ = MLA ? SC192 : SC128; const float C2 = 1.4426950408889634f * sc_;
;     LAS float* wsf = (LAS float*)(lds + OFF_WS) + wid * 96; LAS float* li_l = wsf; LAS float* al_l = wsf + 32; LAS float* g_l = wsf + 64;
;     half8 qr[MLA ? 12 : 8];
;     { const h16* qp = U.Q + (size_t)(wid * 32 + r32) * U.qld + hi * 8;
; #pragma unroll
;       for (int d0 = 0; d0 < (MLA ? 12 : 8); ++d0) qr[d0] = *(const half8*)(qp + d0 * 16); }
;     unsigned mb0 = 0, mb1 = 0, mb2 = 0, mb3 = 0;
;     if constexpr (KIND == K_MOBA) { const int* s = (const int*)U.mk + (size_t)rowpos * 16;
; #pragma unroll
;         for (int i = 0; i < 3; ++i) { const int b = s[i]; if (b >= 0) mb0 |= 1u << b; } }
;     if constexpr (KIND == K_SLC) { const u32x4 m = *(const u32x4*)((const unsigned*)U.mk + (size_t)rowpos * 4); mb0 = m[0]; mb1 = m[1]; mb2 = m[2]; mb3 = m[3]; }
;     const int nvis_row = rowpos >= 31 ? ((rowpos - 31) >> 4) + 1 : 0;
;     const int NT = U.j_hi - U.j_lo;
;     half8 st_k0, st_k1, st_v0, st_v1, st_kr; unsigned dm_lo = 0, dm_hi = 0, dn_lo = 0, dn_hi = 0;
;     const int kws = FA_KSWZ(sr, sc * 2), vst0 = v_st(sr, sc), vst1 = v_st(32 + sr, sc), krw = FA_KRSWZ(tid >> 3, (tid & 7) * 16);
;     const int vb0 = (int)(unsigned)(size_t)(lds + OFF_V) + v_rd_base(lane);
;     ...
;     float m_reg = -1e30f, l_reg = 0.f; f32x16 o[4];
; #pragma unroll
;     for (int d = 0; d < 4; ++d)
; #pragma unroll
;         for (int r = 0; r < 16; ++r) o[d][r] = 0.f;
;     FA_LOADT(U.j_lo); asm volatile("s_waitcnt vmcnt(0)" ::: "memory"); FA_WRITET(0); dm_lo = dn_lo; dm_hi = dn_hi;
;     __syncthreads();
; __device__ __forceinline__ void fa_mem_phase(Frame& F, int l) {
;     LAS char* lds = (LAS char*)F.lds; unsigned char* ws = F.ws;
;     for (int u = blockIdx.x; u < 128; u += F.G) {
;         const int qb = u >> 2, h = u & 3, P0 = qb * 256;
.LBB0_1024:
	s_and_b32 s0, s17, 3
	s_lshl_b32 s0, s0, 15
	s_add_i32 s2, s16, s0
	s_lshl_b64 s[10:11], s[2:3], 1
	s_and_b32 s2, s22, 3
	s_lshl_b32 s0, s22, 6
	s_and_b32 s8, s0, 0xffffff00
	s_lshl_b32 s0, s2, 21
	v_readlane_b32 s1, v251, 23
	s_add_u32 s12, s1, s0
	v_readlane_b32 s0, v251, 24
	s_addc_u32 s13, s0, 0
	s_ashr_i32 s9, s8, 31
	s_lshl_b64 s[0:1], s[8:9], 8
	s_add_u32 s0, s12, s0
	s_addc_u32 s1, s13, s1
	s_lshl_b32 s12, s16, 1
	s_lshl_b32 s13, s2, 16
	v_mov_b32_e32 v18, v0
	s_or_b32 s14, s13, s12
	v_readlane_b32 s12, v253, 6
	s_add_u32 s12, s12, s14
	v_ashrrev_i32_e32 v4, 4, v18
	v_readlane_b32 s13, v253, 7
	v_lshlrev_b32_e32 v19, 3, v18
	v_add_u32_e32 v8, 32, v4
	v_ashrrev_i32_e32 v5, 31, v4
	s_addc_u32 s13, s13, 0
	v_readlane_b32 s15, v253, 8
	v_and_b32_e32 v1, 0x78, v19
	v_lshlrev_b64 v[10:11], 8, v[4:5]
	v_ashrrev_i32_e32 v9, 31, v8
	s_add_u32 s14, s15, s14
	v_readlane_b32 s15, v253, 9
	v_lshlrev_b32_e32 v6, 1, v1
	v_lshl_add_u64 v[12:13], s[12:13], 0, v[10:11]
	v_mov_b32_e32 v7, v3
	v_lshlrev_b64 v[14:15], 8, v[8:9]
	s_addc_u32 s15, s15, 0
	v_lshl_add_u64 v[12:13], v[12:13], 0, v[6:7]
	v_lshl_add_u64 v[16:17], s[12:13], 0, v[14:15]
	v_readfirstlane_b32 s12, v18
	v_lshl_add_u64 v[16:17], v[16:17], 0, v[6:7]
	global_load_dwordx4 v[114:117], v[12:13], off
	s_waitcnt lgkmcnt(0)
	global_load_dwordx4 v[118:121], v[16:17], off
	v_lshl_add_u64 v[12:13], s[14:15], 0, v[10:11]
	s_ashr_i32 s24, s12, 6
	v_lshl_add_u64 v[12:13], v[12:13], 0, v[6:7]
	v_lshl_add_u64 v[14:15], s[14:15], 0, v[14:15]
	s_waitcnt vmcnt(0)
	v_and_b32_e32 v165, 31, v18
	s_lshl_b32 s23, s24, 5
	v_lshl_add_u64 v[14:15], v[14:15], 0, v[6:7]
	global_load_dwordx4 v[154:157], v[12:13], off
	global_load_dwordx4 v[158:161], v[14:15], off
	v_or_b32_e32 v12, s23, v165
	v_ashrrev_i32_e32 v13, 31, v12
	v_bfe_u32 v164, v18, 5, 1
	v_lshlrev_b64 v[12:13], 8, v[12:13]
	v_lshlrev_b32_e32 v2, 4, v164
	v_lshl_add_u64 v[12:13], s[0:1], 0, v[12:13]
	v_lshl_add_u64 v[12:13], v[12:13], 0, v[2:3]
	global_load_dwordx4 v[122:125], v[12:13], off
	global_load_dwordx4 v[126:129], v[12:13], off offset:32
	global_load_dwordx4 v[130:133], v[12:13], off offset:64
	global_load_dwordx4 v[134:137], v[12:13], off offset:96
	global_load_dwordx4 v[138:141], v[12:13], off offset:128
	global_load_dwordx4 v[142:145], v[12:13], off offset:160
	global_load_dwordx4 v[146:149], v[12:13], off offset:192
	global_load_dwordx4 v[150:153], v[12:13], off offset:224
	v_and_b32_e32 v1, 0xfffff0, v4
	v_lshlrev_b32_e32 v5, 1, v4
	v_lshrrev_b32_e32 v7, 1, v4
	v_and_b32_e32 v12, 3, v4
	v_and_or_b32 v1, v5, 8, v1
	v_and_or_b32 v5, v7, 4, v12
	v_and_b32_e32 v7, 0xfffff0, v8
	v_lshlrev_b32_e32 v8, 1, v8
	v_bfe_u32 v9, v19, 5, 2
	s_movk_i32 s1, 0xf0
	v_lshrrev_b32_e32 v1, 1, v1
	v_and_or_b32 v7, v8, 8, v7
	v_lshlrev_b32_e32 v4, 8, v4
	v_bitop3_b32 v12, v6, v18, s1 bitop3:0x78
	v_or_b32_e32 v1, v1, v9
	v_lshrrev_b32_e32 v7, 1, v7
	v_lshlrev_b32_e32 v5, 6, v5
	v_and_b32_e32 v6, 48, v6
	v_add3_u32 v169, 0, v12, v4
	v_lshlrev_b32_e32 v1, 9, v1
	v_or_b32_e32 v4, v7, v9
	v_lshlrev_b32_e32 v4, 9, v4
	v_or3_b32 v170, v1, v5, v6
	v_or3_b32 v171, v4, v5, v6
	v_add_u32_e32 v1, 0, v170
	s_mul_i32 s0, s24, 0x180
	v_add_u32_e32 v4, 0, v171
	s_add_i32 s0, s0, 0
	s_waitcnt vmcnt(0)
	v_lshlrev_b32_e32 v168, 4, v18
	s_add_i32 s12, s0, 0x14000
	v_lshl_add_u32 v172, v165, 2, s12
	v_and_b32_e32 v5, 0xc0, v168
	v_bitop3_b32 v174, v2, v168, s1 bitop3:0x78
	s_add_u32 s10, s74, s10
	s_addc_u32 s11, s75, s11
	s_waitcnt vmcnt(11)
	ds_write_b128 v169, v[114:117] offset:32768
	s_waitcnt vmcnt(10)
	ds_write_b128 v169, v[118:121] offset:40960
	s_waitcnt vmcnt(9)
	ds_write_b128 v1, v[154:157]
	s_waitcnt vmcnt(8)
	ds_write_b128 v4, v[158:161]
	v_lshlrev_b32_e32 v1, 1, v18
	v_and_b32_e32 v4, 32, v1
	v_and_b32_e32 v1, 0xf0, v168
	v_bitop3_b32 v175, v2, v1, 32 bitop3:0x36
	v_bitop3_b32 v176, v2, v1, 64 bitop3:0x36
	v_bitop3_b32 v177, v2, v1, s77 bitop3:0x36
	v_add_u32_e32 v1, s12, v2
	s_movk_i32 s12, 0x118
	v_and_or_b32 v2, v19, s12, v4
	v_add3_u32 v178, v5, 0, v2
	v_and_b32_e32 v2, 15, v18
	v_lshl_or_b32 v10, v2, 4, v10
	v_mov_b32_e32 v16, v3
	v_mov_b32_e32 v17, v3
	v_and_b32_e32 v166, 63, v18
	v_lshl_add_u64 v[162:163], s[10:11], 0, v[10:11]
	v_mov_b32_e32 v2, v3
	v_mov_b32_e32 v4, v3
	v_mov_b32_e32 v5, v3
	v_mov_b32_e32 v6, v3
	v_mov_b32_e32 v7, v3
	v_mov_b32_e32 v8, v3
	v_mov_b32_e32 v9, v3
	v_mov_b32_e32 v10, v3
	v_mov_b32_e32 v11, v3
	v_mov_b32_e32 v12, v3
	v_mov_b32_e32 v13, v3
	v_mov_b32_e32 v14, v3
	v_mov_b32_e32 v15, v3
	v_mov_b64_e32 v[32:33], v[16:17]
	v_mov_b64_e32 v[48:49], v[16:17]
	v_mov_b64_e32 v[64:65], v[16:17]
	v_mov_b64_e32 v[80:81], v[16:17]
	v_lshl_add_u32 v173, v165, 8, 0
	v_cmp_gt_u32_e64 s[0:1], 32, v166
	v_lshlrev_b32_e32 v167, 2, v164
	s_mov_b32 s25, 0
	v_mov_b32_e32 v180, 0
	v_mov_b32_e32 v179, 0xf149f2ca
	s_mov_b64 s[10:11], 0
	v_mov_b64_e32 v[30:31], v[14:15]
	v_mov_b64_e32 v[28:29], v[12:13]
	v_mov_b64_e32 v[26:27], v[10:11]
	v_mov_b64_e32 v[24:25], v[8:9]
	v_mov_b64_e32 v[22:23], v[6:7]
	v_mov_b64_e32 v[20:21], v[4:5]
	v_mov_b64_e32 v[18:19], v[2:3]
	v_mov_b64_e32 v[46:47], v[14:15]
	v_mov_b64_e32 v[44:45], v[12:13]
	v_mov_b64_e32 v[42:43], v[10:11]
	v_mov_b64_e32 v[40:41], v[8:9]
	v_mov_b64_e32 v[38:39], v[6:7]
	v_mov_b64_e32 v[36:37], v[4:5]
	v_mov_b64_e32 v[34:35], v[2:3]
	v_mov_b64_e32 v[62:63], v[14:15]
	v_mov_b64_e32 v[60:61], v[12:13]
	v_mov_b64_e32 v[58:59], v[10:11]
	v_mov_b64_e32 v[56:57], v[8:9]
	v_mov_b64_e32 v[54:55], v[6:7]
	v_mov_b64_e32 v[52:53], v[4:5]
	v_mov_b64_e32 v[50:51], v[2:3]
	v_mov_b64_e32 v[78:79], v[14:15]
	v_mov_b64_e32 v[76:77], v[12:13]
	v_mov_b64_e32 v[74:75], v[10:11]
	v_mov_b64_e32 v[72:73], v[8:9]
	v_mov_b64_e32 v[70:71], v[6:7]
	v_mov_b64_e32 v[68:69], v[4:5]
	v_mov_b64_e32 v[66:67], v[2:3]
	s_waitcnt lgkmcnt(0)
	s_barrier
	s_cmp_gt_u32 s25, 2
	s_cselect_b64 s[12:13], -1, 0
	s_and_b64 vcc, exec, s[12:13]
	s_cbranch_vccnz .LBB0_1027
	s_branch .LBB0_1026

; #define LAS __attribute__((address_space(3)))
; #define FA_SBAR() __builtin_amdgcn_sched_barrier(0)
; __device__ __forceinline__ float max3f(float a, float b, float c) { return __builtin_fmaxf(__builtin_fmaxf(a, b), c); }
; #define QK_MM(F0, F1, g) do { _Pragma("unroll") for (int e = 0; e < 2; ++e) { const int d0 = 2 * (g) + e; \
;         p0 = __builtin_amdgcn_mfma_f32_32x32x16_f16(F0[e], qr[d0], p0, 0, 0, 0); p1 = __builtin_amdgcn_mfma_f32_32x32x16_f16(F1[e], qr[d0], p1, 0, 0, 0); } } while (0)
; __device__ __forceinline__ void partialSM(f32x16& p0, f32x16& p1, float& m_reg, float& mn, float& alpha, const float sc, const float C2) {
;     float pmax = max3f(p0[0], p0[1], p0[2]);
; #pragma unroll
;     for (int r = 3; r < 15; r += 2) pmax = max3f(pmax, p0[r], p0[r + 1]);
;     pmax = max3f(pmax, p0[15], p1[0]);
; #pragma unroll
;     for (int r = 1; r < 15; r += 2) pmax = max3f(pmax, p1[r], p1[r + 1]);
;     pmax = fmaxf(pmax, p1[15]);
;     { auto rr = __builtin_amdgcn_permlane32_swap(__float_as_uint(pmax), __float_as_uint(pmax), false, false);
;       pmax = fmaxf(__uint_as_float(rr[0]), __uint_as_float(rr[1])); }
;     if (__builtin_expect(__all((pmax - m_reg) * sc <= 8.0f), 1)) { mn = m_reg; alpha = 1.f; }
;     else { mn = fmaxf(m_reg, pmax); alpha = __builtin_amdgcn_exp2f((m_reg - mn) * C2); m_reg = mn; }
; template <bool MLA>
; __device__ __forceinline__ void qkt2(f32x16& p0, f32x16& p1, const LAS char* lds, int kboff, int kroff, int r32, int hi, const half8* qr) {
;     const LAS char* kb[4];
; #pragma unroll
;     for (int dd = 0; dd < 4; ++dd) kb[dd] = lds + OFF_K + kboff + FA_KSWZ(r32, (dd * 16 + hi * 8) * 2);
;     constexpr int NG = MLA ? 6 : 4;
;     half8 fa0[2], fa1[2], fb0[2], fb1[2];
;     ...
; #pragma unroll
;     for (int r = 0; r < 16; ++r) { p0[r] = 0.f; p1[r] = 0.f; }
;     QK_LD(fa0, fa1, 0); FA_SBAR();
;     QK_LD(fb0, fb1, 1); FA_SBAR(); QK_MM(fa0, fa1, 0); FA_SBAR();
;     QK_LD(fa0, fa1, 2); FA_SBAR(); QK_MM(fb0, fb1, 1); FA_SBAR();
;     QK_LD(fb0, fb1, 3); FA_SBAR(); QK_MM(fa0, fa1, 2); FA_SBAR();
;     if constexpr (NG == 6) {
;         QK_LD(fa0, fa1, 4); FA_SBAR(); QK_MM(fb0, fb1, 3); FA_SBAR();
;         QK_LD(fb0, fb1, 5); FA_SBAR(); QK_MM(fa0, fa1, 4); FA_SBAR();
;         QK_MM(fb0, fb1, 5);
;     } else QK_MM(fb0, fb1, 3);
;     ...
; }
.LBB0_1027:
	s_and_b32 s14, s25, 1
	v_mov_b32_e32 v2, s14
	s_nop 0
	v_lshlrev_b32_e32 v6, 14, v2
	v_add_u32_e32 v2, v173, v6
	v_add_u32_e32 v4, v2, v174
	v_add_u32_e32 v5, v2, v175
	ds_read_b128 v[8:11], v4 offset:32768
	ds_read_b128 v[12:15], v4 offset:40960
	ds_read_b128 v[182:185], v5 offset:32768
	ds_read_b128 v[186:189], v5 offset:40960
	v_add_u32_e32 v7, v2, v176
	v_add_u32_e32 v2, v2, v177
	ds_read_b128 v[190:193], v7 offset:32768
	ds_read_b128 v[194:197], v7 offset:40960
	ds_read_b128 v[204:207], v2 offset:32768
	ds_read_b128 v[220:223], v2 offset:40960
	s_waitcnt lgkmcnt(7)
	v_mfma_f32_32x32x16_f16 v[98:113], v[8:11], v[122:125], 0
	s_waitcnt lgkmcnt(6)
	v_mfma_f32_32x32x16_f16 v[82:97], v[12:15], v[122:125], 0
	s_waitcnt lgkmcnt(5)
	v_mfma_f32_32x32x16_f16 v[98:113], v[182:185], v[126:129], v[98:113]
	s_waitcnt lgkmcnt(4)
	v_mfma_f32_32x32x16_f16 v[82:97], v[186:189], v[126:129], v[82:97]
	v_xor_b32_e32 v4, 0x80, v4
	ds_read_b128 v[8:11], v4 offset:32768
	ds_read_b128 v[12:15], v4 offset:40960
	v_xor_b32_e32 v5, 0x80, v5
	ds_read_b128 v[182:185], v5 offset:32768
	ds_read_b128 v[186:189], v5 offset:40960
	s_waitcnt lgkmcnt(7)
	v_mfma_f32_32x32x16_f16 v[98:113], v[190:193], v[130:133], v[98:113]
	s_waitcnt lgkmcnt(6)
	v_mfma_f32_32x32x16_f16 v[82:97], v[194:197], v[130:133], v[82:97]
	s_waitcnt lgkmcnt(5)
	v_mfma_f32_32x32x16_f16 v[98:113], v[204:207], v[134:137], v[98:113]
	s_waitcnt lgkmcnt(4)
	v_mfma_f32_32x32x16_f16 v[82:97], v[220:223], v[134:137], v[82:97]
	v_xor_b32_e32 v7, 0x80, v7
	ds_read_b128 v[190:193], v7 offset:32768
	ds_read_b128 v[194:197], v7 offset:40960
	v_xor_b32_e32 v2, 0x80, v2
	ds_read_b128 v[204:207], v2 offset:32768
	ds_read_b128 v[220:223], v2 offset:40960
	s_waitcnt lgkmcnt(7)
	v_mfma_f32_32x32x16_f16 v[98:113], v[8:11], v[138:141], v[98:113]
	s_waitcnt lgkmcnt(6)
	v_mfma_f32_32x32x16_f16 v[82:97], v[12:15], v[138:141], v[82:97]
	s_waitcnt lgkmcnt(5)
	v_mfma_f32_32x32x16_f16 v[98:113], v[182:185], v[142:145], v[98:113]
	s_waitcnt lgkmcnt(4)
	v_mfma_f32_32x32x16_f16 v[82:97], v[186:189], v[142:145], v[82:97]
	s_waitcnt lgkmcnt(3)
	v_mfma_f32_32x32x16_f16 v[98:113], v[190:193], v[146:149], v[98:113]
	s_waitcnt lgkmcnt(1)
	v_mfma_f32_32x32x16_f16 v[98:113], v[204:207], v[150:153], v[98:113]
	v_mfma_f32_32x32x16_f16 v[82:97], v[194:197], v[146:149], v[82:97]
	s_nop 10
	v_max_f32_e32 v2, v99, v99
	v_max_f32_e32 v4, v98, v98
	v_max_f32_e32 v2, v4, v2
	v_max3_f32 v2, v2, v100, v101
	v_max3_f32 v2, v2, v102, v103
	v_max3_f32 v2, v2, v104, v105
	v_max3_f32 v2, v2, v106, v107
	s_waitcnt lgkmcnt(0)
	v_mfma_f32_32x32x16_f16 v[82:97], v[220:223], v[150:153], v[82:97]
	v_max3_f32 v2, v2, v108, v109
	v_max3_f32 v2, v2, v110, v111
	v_max3_f32 v2, v2, v112, v113
	v_max_f32_e32 v4, v179, v179
	s_nop 7
	v_max3_f32 v2, v2, v82, v83
	v_max3_f32 v2, v2, v84, v85
	v_max3_f32 v2, v2, v86, v87
	v_max3_f32 v2, v2, v88, v89
	v_max3_f32 v2, v2, v90, v91
	v_max3_f32 v2, v2, v92, v93
	v_max3_f32 v2, v2, v94, v95
	v_max3_f32 v2, v2, v96, v97
	v_mov_b32_e32 v5, v2
	s_nop 1
	v_permlane32_swap_b32_e32 v2, v5
	v_max_f32_e32 v5, v5, v5
	v_max_f32_e32 v2, v2, v2
	v_max_f32_e32 v2, v2, v5
	v_sub_f32_e32 v5, v2, v179
	v_max_f32_e32 v4, v4, v2
	v_mul_f32_e32 v2, 0x3db504f3, v5
	v_sub_f32_e32 v5, v179, v4
	v_mul_f32_e32 v5, 0x3e0293ee, v5
	v_exp_f32_e32 v5, v5
	v_cmp_ge_f32_e32 vcc, s87, v2
	s_cmp_eq_u64 vcc, exec
	s_cselect_b64 s[38:39], -1, 0
	v_cndmask_b32_e64 v2, v5, 1.0, s[38:39]
	v_cmp_gt_f32_e32 vcc, 1.0, v2
	s_cbranch_vccz .LBB0_1031
	s_and_saveexec_b64 s[14:15], s[0:1]
	ds_write_b32 v172, v2 offset:128
	s_or_b64 exec, exec, s[14:15]
	s_waitcnt lgkmcnt(0)
	ds_read_b128 v[8:11], v1 offset:224
	ds_read_b128 v[12:15], v1 offset:192
	ds_read_b128 v[182:185], v1 offset:160
	ds_read_b128 v[186:189], v1 offset:128
	s_waitcnt lgkmcnt(3)
	v_pk_mul_f32 v[80:81], v[80:81], v[10:11]
	s_waitcnt lgkmcnt(2)
	v_pk_mul_f32 v[76:77], v[76:77], v[14:15]
	s_waitcnt lgkmcnt(1)
	v_pk_mul_f32 v[72:73], v[72:73], v[184:185]
	s_waitcnt lgkmcnt(0)
	v_pk_mul_f32 v[68:69], v[68:69], v[188:189]
	v_pk_mul_f32 v[78:79], v[78:79], v[8:9]
	v_pk_mul_f32 v[74:75], v[74:75], v[12:13]
	v_pk_mul_f32 v[70:71], v[70:71], v[182:183]
	v_pk_mul_f32 v[66:67], v[66:67], v[186:187]
	v_pk_mul_f32 v[64:65], v[64:65], v[10:11]
	v_pk_mul_f32 v[60:61], v[60:61], v[14:15]
	v_pk_mul_f32 v[56:57], v[56:57], v[184:185]
	v_pk_mul_f32 v[52:53], v[52:53], v[188:189]
	v_pk_mul_f32 v[62:63], v[62:63], v[8:9]
	v_pk_mul_f32 v[58:59], v[58:59], v[12:13]
	v_pk_mul_f32 v[54:55], v[54:55], v[182:183]
	v_pk_mul_f32 v[50:51], v[50:51], v[186:187]
	v_pk_mul_f32 v[48:49], v[48:49], v[10:11]
	v_pk_mul_f32 v[44:45], v[44:45], v[14:15]
	v_pk_mul_f32 v[40:41], v[40:41], v[184:185]
	v_pk_mul_f32 v[36:37], v[36:37], v[188:189]
	v_pk_mul_f32 v[46:47], v[46:47], v[8:9]
	v_pk_mul_f32 v[42:43], v[42:43], v[12:13]
	v_pk_mul_f32 v[38:39], v[38:39], v[182:183]
	v_pk_mul_f32 v[34:35], v[34:35], v[186:187]
	v_pk_mul_f32 v[32:33], v[32:33], v[10:11]
	v_pk_mul_f32 v[28:29], v[28:29], v[14:15]
	v_pk_mul_f32 v[24:25], v[24:25], v[184:185]
	v_pk_mul_f32 v[20:21], v[20:21], v[188:189]
	v_pk_mul_f32 v[30:31], v[30:31], v[8:9]
	v_pk_mul_f32 v[26:27], v[26:27], v[12:13]
	v_pk_mul_f32 v[22:23], v[22:23], v[182:183]
	v_pk_mul_f32 v[18:19], v[18:19], v[186:187]

; __device__ __forceinline__ int v_st(int k, int c) { const int kk = (k & ~0xC) | ((k & 4) << 1) | ((k & 8) >> 1); return ((kk >> 3) * 4 + (c >> 5)) * 512 + ((kk & 7) * 32 + (c & 31)) * 2; }
; template <int KIND>
; __device__ __forceinline__ void run_unit(LAS char* lds, const UnitArgs& U, int tid_in) {
;     ...
;     const int kws = FA_KSWZ(sr, sc * 2), vst0 = v_st(sr, sc), vst1 = v_st(32 + sr, sc), krw = FA_KRSWZ(tid >> 3, (tid & 7) * 16);
.LBB0_4721:
	s_andn2_b64 vcc, exec, s[0:1]
	s_movk_i32 s50, 0xf0
	s_cbranch_vccnz .LBB0_4802
	v_readlane_b32 s0, v253, 28
	v_readlane_b32 s1, v253, 29
	v_mov_b32_e32 v4, v210
	s_andn2_b64 vcc, exec, s[0:1]
	s_cbranch_vccnz .LBB0_4737
	v_readlane_b32 s0, v255, 32
	v_ashrrev_i32_e32 v5, 31, v4
	v_readlane_b32 s6, v253, 30
	v_readlane_b32 s1, v255, 33
	v_lshlrev_b64 v[6:7], 2, v[4:5]
	v_readlane_b32 s7, v253, 31
	s_lshl_b64 s[0:1], s[0:1], 17
	s_lshl_b32 s2, s80, 1
	v_lshl_add_u64 v[8:9], s[6:7], 0, v[6:7]
	v_readlane_b32 s6, v254, 57
	s_add_u32 s0, s6, s0
	v_readlane_b32 s6, v254, 58
	v_add_u32_e32 v12, 64, v4
	s_addc_u32 s1, s6, s1
	v_ashrrev_i32_e32 v13, 31, v12
	v_lshl_add_u64 v[10:11], s[0:1], 0, v[6:7]
	v_readlane_b32 s0, v255, 20
	v_lshl_add_u32 v1, v4, 2, s5
	v_add_u32_e32 v2, 0xfc0, v4
	v_lshlrev_b64 v[12:13], 2, v[12:13]
	s_mov_b32 s14, s0
	v_readlane_b32 s1, v255, 21
	s_branch .LBB0_4725

; #define LAS __attribute__((address_space(3)))
; template <int KIND>
; __device__ __forceinline__ void run_unit(LAS char* lds, const UnitArgs& U, int tid_in) {
;     constexpr bool MLA = KIND == K_MLA;
;     int tid = tid_in; asm volatile("" : "+v"(tid));
;     const int wid = __builtin_amdgcn_readfirstlane(tid >> 6), lane = tid & 63, r32 = lane & 31, hi = lane >> 5;
;     const int sr = tid >> 4, sc = (tid & 15) * 8;
;     const int qlo = U.P0 + wid * 32, rowpos = qlo + r32;
;     const float sc_ = MLA ? SC192 : SC128; const float C2 = 1.4426950408889634f * sc_;
;     LAS float* wsf = (LAS float*)(lds + OFF_WS) + wid * 96; LAS float* li_l = wsf; LAS float* al_l = wsf + 32; LAS float* g_l = wsf + 64;
;     half8 qr[MLA ? 12 : 8];
;     { const h16* qp = U.Q + (size_t)(wid * 32 + r32) * U.qld + hi * 8;
; #pragma unroll
;       for (int d0 = 0; d0 < (MLA ? 12 : 8); ++d0) qr[d0] = *(const half8*)(qp + d0 * 16); }
;     unsigned mb0 = 0, mb1 = 0, mb2 = 0, mb3 = 0;
;     if constexpr (KIND == K_MOBA) { const int* s = (const int*)U.mk + (size_t)rowpos * 16;
; #pragma unroll
;         for (int i = 0; i < 3; ++i) { const int b = s[i]; if (b >= 0) mb0 |= 1u << b; } }
;     if constexpr (KIND == K_SLC) { const u32x4 m = *(const u32x4*)((const unsigned*)U.mk + (size_t)rowpos * 4); mb0 = m[0]; mb1 = m[1]; mb2 = m[2]; mb3 = m[3]; }
;     const int nvis_row = rowpos >= 31 ? ((rowpos - 31) >> 4) + 1 : 0;
;     const int NT = U.j_hi - U.j_lo;
;     half8 st_k0, st_k1, st_v0, st_v1, st_kr; unsigned dm_lo = 0, dm_hi = 0, dn_lo = 0, dn_hi = 0;
;     const int kws = FA_KSWZ(sr, sc * 2), vst0 = v_st(sr, sc), vst1 = v_st(32 + sr, sc), krw = FA_KRSWZ(tid >> 3, (tid & 7) * 16);
;     const int vb0 = (int)(unsigned)(size_t)(lds + OFF_V) + v_rd_base(lane);
;     ...
;     float m_reg = -1e30f, l_reg = 0.f; f32x16 o[4];
; #pragma unroll
;     for (int d = 0; d < 4; ++d)
; #pragma unroll
;         for (int r = 0; r < 16; ++r) o[d][r] = 0.f;
;     FA_LOADT(U.j_lo); asm volatile("s_waitcnt vmcnt(0)" ::: "memory"); FA_WRITET(0); dm_lo = dn_lo; dm_hi = dn_hi;
;     __syncthreads();
; __device__ __forceinline__ void fa_cmp_phase(Frame& F) {
;     LAS char* lds = (LAS char*)F.lds; unsigned char* ws = F.ws;
;     for (int u = blockIdx.x; u < 128; u += F.G) {
;         const int qb = 31 - (u >> 2), h = u & 3, P0 = qb * 256;
.LBB0_4812:
	v_mov_b32_e32 v18, v0
	v_readlane_b32 s0, v253, 40
	v_ashrrev_i32_e32 v4, 4, v18
	v_add_u32_e32 v8, 32, v4
	v_lshlrev_b32_e32 v19, 3, v18
	v_ashrrev_i32_e32 v5, 31, v4
	v_ashrrev_i32_e32 v9, 31, v8
	v_and_b32_e32 v1, 0x78, v19
	v_lshlrev_b64 v[10:11], 8, v[4:5]
	v_readlane_b32 s1, v253, 41
	v_lshlrev_b64 v[14:15], 8, v[8:9]
	v_lshlrev_b32_e32 v6, 1, v1
	v_lshl_add_u64 v[12:13], s[0:1], 0, v[10:11]
	v_mov_b32_e32 v7, v3
	v_lshl_add_u64 v[16:17], s[0:1], 0, v[14:15]
	v_readlane_b32 s0, v253, 42
	v_lshl_add_u64 v[12:13], v[12:13], 0, v[6:7]
	v_readlane_b32 s1, v253, 43
	v_lshl_add_u64 v[16:17], v[16:17], 0, v[6:7]
	global_load_dwordx4 v[114:117], v[12:13], off
	s_waitcnt lgkmcnt(0)
	global_load_dwordx4 v[118:121], v[16:17], off
	v_lshl_add_u64 v[12:13], s[0:1], 0, v[10:11]
	v_lshl_add_u64 v[12:13], v[12:13], 0, v[6:7]
	global_load_dwordx4 v[122:125], v[12:13], off
	v_lshl_add_u64 v[12:13], s[0:1], 0, v[14:15]
	s_and_b32 s0, s12, 0xffffff00
	s_sub_i32 s0, 0x1f00, s0
	s_lshr_b32 s0, s0, 4
	s_add_i32 s0, s0, 64
	s_and_b32 s17, s0, 0x1fffffc0
	s_lshl_b32 s0, s13, 6
	s_and_b32 s0, s0, 0xffffff00
	s_sub_i32 s2, 0x1f00, s0
	s_lshr_b32 s0, s2, 4
	s_and_b32 s14, s13, 3
	s_add_i32 s0, s0, 64
	s_lshr_b32 s22, s0, 6
	s_lshl_b32 s0, s14, 21
	v_readlane_b32 s6, v252, 14
	v_readlane_b32 s7, v252, 15
	s_add_u32 s6, s6, s0
	s_addc_u32 s7, s7, 0
	s_lshl_b64 s[0:1], s[2:3], 8
	s_add_u32 s0, s6, s0
	v_readfirstlane_b32 s6, v18
	s_addc_u32 s1, s7, s1
	s_ashr_i32 s15, s6, 6
	v_lshl_add_u64 v[12:13], v[12:13], 0, v[6:7]
	s_waitcnt vmcnt(0)
	v_and_b32_e32 v167, 31, v18
	s_lshl_b32 s16, s15, 5
	global_load_dwordx4 v[126:129], v[12:13], off
	v_or_b32_e32 v12, s16, v167
	v_ashrrev_i32_e32 v13, 31, v12
	v_bfe_u32 v166, v18, 5, 1
	v_lshlrev_b64 v[12:13], 8, v[12:13]
	v_lshl_add_u64 v[12:13], s[0:1], 0, v[12:13]
	v_lshlrev_b32_e32 v2, 4, v166
	v_lshl_add_u64 v[12:13], v[12:13], 0, v[2:3]
	global_load_dwordx4 v[130:133], v[12:13], off
	global_load_dwordx4 v[134:137], v[12:13], off offset:32
	global_load_dwordx4 v[138:141], v[12:13], off offset:64
	global_load_dwordx4 v[142:145], v[12:13], off offset:96
	global_load_dwordx4 v[146:149], v[12:13], off offset:128
	global_load_dwordx4 v[150:153], v[12:13], off offset:160
	global_load_dwordx4 v[154:157], v[12:13], off offset:192
	global_load_dwordx4 v[158:161], v[12:13], off offset:224
	v_and_b32_e32 v5, 0xfffff0, v4
	v_lshlrev_b32_e32 v7, 1, v4
	v_and_or_b32 v5, v7, 8, v5
	v_lshrrev_b32_e32 v7, 1, v4
	v_and_b32_e32 v12, 3, v4
	v_and_or_b32 v7, v7, 4, v12
	v_and_b32_e32 v12, 0xfffff0, v8
	v_lshlrev_b32_e32 v8, 1, v8
	v_lshrrev_b32_e32 v5, 1, v5
	v_bfe_u32 v9, v19, 5, 2
	v_and_or_b32 v8, v8, 8, v12
	v_or_b32_e32 v5, v5, v9
	v_lshrrev_b32_e32 v8, 1, v8
	v_bitop3_b32 v1, v6, v18, s50 bitop3:0x78
	v_lshlrev_b32_e32 v5, 9, v5
	v_lshlrev_b32_e32 v7, 6, v7
	v_or_b32_e32 v8, v8, v9
	v_and_b32_e32 v6, 48, v6
	v_lshlrev_b32_e32 v8, 9, v8
	v_lshlrev_b32_e32 v4, 8, v4
	v_or3_b32 v163, v5, v7, v6
	v_or3_b32 v172, v8, v7, v6
	v_add3_u32 v173, 0, v1, v4
	v_add_u32_e32 v1, 0, v163
	s_add_i32 s6, s16, s2
	s_waitcnt vmcnt(0)
	s_mul_i32 s7, s15, 0x180
	s_waitcnt vmcnt(0)
	ds_write_b128 v173, v[114:117] offset:32768
	ds_write_b128 v173, v[118:121] offset:40960
	v_or_b32_e32 v162, s6, v167
	s_add_i32 s7, s7, 0
	ds_write_b128 v1, v[122:125]
	v_add_u32_e32 v1, 0, v172
	v_lshlrev_b32_e32 v170, 4, v18
	s_add_i32 s7, s7, 0x14000
	s_ashr_i32 s23, s6, 4
	v_and_b32_e32 v6, 0xf0, v170
	v_cmp_lt_i32_e32 vcc, 30, v162
	s_movk_i32 s6, 0x118
	v_and_b32_e32 v5, 0xc0, v170
	v_bitop3_b32 v175, v2, v170, s50 bitop3:0x78
	v_bitop3_b32 v176, v2, v6, 32 bitop3:0x36
	v_bitop3_b32 v177, v2, v6, 64 bitop3:0x36
	v_bitop3_b32 v178, v2, v6, s77 bitop3:0x36
	v_lshlrev_b32_e32 v169, 2, v166
	v_mov_b32_e32 v16, v3
	v_mov_b32_e32 v17, v3
	v_and_b32_e32 v168, 63, v18
	v_mov_b32_e32 v7, v3
	v_mov_b32_e32 v8, v3
	v_mov_b32_e32 v9, v3
	v_mov_b32_e32 v12, v3
	v_mov_b32_e32 v13, v3
	v_mov_b32_e32 v14, v3
	v_mov_b32_e32 v15, v3
	v_lshl_add_u32 v174, v167, 8, 0
	v_cmp_gt_u32_e64 s[0:1], 32, v168
	v_lshl_add_u32 v171, v167, 2, s7
	ds_write_b128 v1, v[126:129]
	v_lshlrev_b32_e32 v1, 1, v18
	v_and_b32_e32 v4, 32, v1
	v_subrev_u32_e32 v1, 31, v162
	v_ashrrev_i32_e32 v1, 4, v1
	v_cndmask_b32_e32 v6, -1, v1, vcc
	v_add_u32_e32 v1, s7, v2
	v_and_or_b32 v2, v19, s6, v4
	v_add3_u32 v179, v5, 0, v2
	v_and_b32_e32 v2, 15, v18
	v_lshl_or_b32 v10, v2, 4, v10
	v_sub_u32_e32 v180, v6, v169
	v_lshl_add_u64 v[164:165], s[74:75], 0, v[10:11]
	v_mov_b32_e32 v2, v3
	v_mov_b32_e32 v4, v3
	v_mov_b32_e32 v5, v3
	v_mov_b32_e32 v6, v3
	v_mov_b32_e32 v10, v3
	v_mov_b32_e32 v11, v3
	v_mov_b64_e32 v[32:33], v[16:17]
	v_mov_b64_e32 v[48:49], v[16:17]
	v_mov_b64_e32 v[64:65], v[16:17]
	v_mov_b64_e32 v[80:81], v[16:17]
	s_mov_b32 s24, 0
	v_mov_b32_e32 v182, 0
	v_mov_b32_e32 v181, 0xf149f2ca
	s_mov_b64 s[6:7], 0
	s_mov_b32 s25, 0
	v_mov_b64_e32 v[30:31], v[14:15]
	v_mov_b64_e32 v[28:29], v[12:13]
	v_mov_b64_e32 v[26:27], v[10:11]
	v_mov_b64_e32 v[24:25], v[8:9]
	v_mov_b64_e32 v[22:23], v[6:7]
	v_mov_b64_e32 v[20:21], v[4:5]
	v_mov_b64_e32 v[18:19], v[2:3]
	v_mov_b64_e32 v[46:47], v[14:15]
	v_mov_b64_e32 v[44:45], v[12:13]
	v_mov_b64_e32 v[42:43], v[10:11]
	v_mov_b64_e32 v[40:41], v[8:9]
	v_mov_b64_e32 v[38:39], v[6:7]
	v_mov_b64_e32 v[36:37], v[4:5]
	v_mov_b64_e32 v[34:35], v[2:3]
	v_mov_b64_e32 v[62:63], v[14:15]
	v_mov_b64_e32 v[60:61], v[12:13]
	v_mov_b64_e32 v[58:59], v[10:11]
	v_mov_b64_e32 v[56:57], v[8:9]
	v_mov_b64_e32 v[54:55], v[6:7]
	v_mov_b64_e32 v[52:53], v[4:5]
	v_mov_b64_e32 v[50:51], v[2:3]
	v_mov_b64_e32 v[78:79], v[14:15]
	v_mov_b64_e32 v[76:77], v[12:13]
	v_mov_b64_e32 v[74:75], v[10:11]
	v_mov_b64_e32 v[72:73], v[8:9]
	v_mov_b64_e32 v[70:71], v[6:7]
	v_mov_b64_e32 v[68:69], v[4:5]
	v_mov_b64_e32 v[66:67], v[2:3]
	s_mov_b32 s10, 0
	s_waitcnt lgkmcnt(0)
	s_barrier

; #define LAS __attribute__((address_space(3)))
; #define FA_SBAR() __builtin_amdgcn_sched_barrier(0)
; #define QK_MM(F0, F1, g) do { _Pragma("unroll") for (int e = 0; e < 2; ++e) { const int d0 = 2 * (g) + e; \
;         p0 = __builtin_amdgcn_mfma_f32_32x32x16_f16(F0[e], qr[d0], p0, 0, 0, 0); p1 = __builtin_amdgcn_mfma_f32_32x32x16_f16(F1[e], qr[d0], p1, 0, 0, 0); } } while (0)
; template <bool MLA>
; __device__ __forceinline__ void qkt2(f32x16& p0, f32x16& p1, const LAS char* lds, int kboff, int kroff, int r32, int hi, const half8* qr) {
;     const LAS char* kb[4];
; #pragma unroll
;     for (int dd = 0; dd < 4; ++dd) kb[dd] = lds + OFF_K + kboff + FA_KSWZ(r32, (dd * 16 + hi * 8) * 2);
;     constexpr int NG = MLA ? 6 : 4;
;     half8 fa0[2], fa1[2], fb0[2], fb1[2];
;     ...
; #pragma unroll
;     for (int r = 0; r < 16; ++r) { p0[r] = 0.f; p1[r] = 0.f; }
;     QK_LD(fa0, fa1, 0); FA_SBAR();
;     QK_LD(fb0, fb1, 1); FA_SBAR(); QK_MM(fa0, fa1, 0); FA_SBAR();
;     QK_LD(fa0, fa1, 2); FA_SBAR(); QK_MM(fb0, fb1, 1); FA_SBAR();
;     QK_LD(fb0, fb1, 3); FA_SBAR(); QK_MM(fa0, fa1, 2); FA_SBAR();
;     if constexpr (NG == 6) {
;         QK_LD(fa0, fa1, 4); FA_SBAR(); QK_MM(fb0, fb1, 3); FA_SBAR();
;         QK_LD(fb0, fb1, 5); FA_SBAR(); QK_MM(fa0, fa1, 4); FA_SBAR();
;         QK_MM(fb0, fb1, 5);
;     } else QK_MM(fb0, fb1, 3);
;     ...
; }
.LBB0_4815:
	s_and_b32 s10, s10, 1
	v_mov_b32_e32 v2, s10
	s_cmp_gt_i32 s24, s23
	s_cbranch_scc1 .LBB0_4822
	v_lshlrev_b32_e32 v2, 14, v2
	v_add_u32_e32 v4, v174, v2
	v_add_u32_e32 v16, v4, v175
	v_add_u32_e32 v17, v4, v176
	v_add_u32_e32 v183, v4, v177
	v_add_u32_e32 v192, v4, v178
	ds_read_b128 v[4:7], v16 offset:32768
	ds_read_b128 v[8:11], v16 offset:40960
	ds_read_b128 v[12:15], v17 offset:32768
	ds_read_b128 v[184:187], v17 offset:40960
	ds_read_b128 v[188:191], v183 offset:32768
	ds_read_b128 v[204:207], v183 offset:40960
	ds_read_b128 v[220:223], v192 offset:32768
	ds_read_b128 v[224:227], v192 offset:40960
	s_waitcnt lgkmcnt(7)
	v_mfma_f32_32x32x16_f16 v[98:113], v[4:7], v[130:133], 0
	s_waitcnt lgkmcnt(6)
	v_mfma_f32_32x32x16_f16 v[82:97], v[8:11], v[130:133], 0
	s_waitcnt lgkmcnt(5)
	v_mfma_f32_32x32x16_f16 v[98:113], v[12:15], v[134:137], v[98:113]
	s_waitcnt lgkmcnt(4)
	v_mfma_f32_32x32x16_f16 v[82:97], v[184:187], v[134:137], v[82:97]
	v_xor_b32_e32 v16, 0x80, v16
	ds_read_b128 v[4:7], v16 offset:32768
	ds_read_b128 v[8:11], v16 offset:40960
	v_xor_b32_e32 v17, 0x80, v17
	ds_read_b128 v[12:15], v17 offset:32768
	ds_read_b128 v[184:187], v17 offset:40960
	s_waitcnt lgkmcnt(7)
	v_mfma_f32_32x32x16_f16 v[98:113], v[188:191], v[138:141], v[98:113]
	s_waitcnt lgkmcnt(6)
	v_mfma_f32_32x32x16_f16 v[82:97], v[204:207], v[138:141], v[82:97]
	s_waitcnt lgkmcnt(5)
	v_mfma_f32_32x32x16_f16 v[98:113], v[220:223], v[142:145], v[98:113]
	s_waitcnt lgkmcnt(4)
	v_mfma_f32_32x32x16_f16 v[82:97], v[224:227], v[142:145], v[82:97]
	v_xor_b32_e32 v183, 0x80, v183
	ds_read_b128 v[188:191], v183 offset:32768
	ds_read_b128 v[204:207], v183 offset:40960
	v_xor_b32_e32 v192, 0x80, v192
	ds_read_b128 v[220:223], v192 offset:32768
	ds_read_b128 v[224:227], v192 offset:40960
	s_waitcnt lgkmcnt(7)
	v_mfma_f32_32x32x16_f16 v[98:113], v[4:7], v[146:149], v[98:113]
	s_waitcnt lgkmcnt(6)
	v_mfma_f32_32x32x16_f16 v[82:97], v[8:11], v[146:149], v[82:97]
	s_waitcnt lgkmcnt(5)
	v_mfma_f32_32x32x16_f16 v[98:113], v[12:15], v[150:153], v[98:113]
	s_waitcnt lgkmcnt(4)
	v_mfma_f32_32x32x16_f16 v[82:97], v[184:187], v[150:153], v[82:97]
	s_waitcnt lgkmcnt(3)
	v_mfma_f32_32x32x16_f16 v[98:113], v[188:191], v[154:157], v[98:113]
	v_add_u32_e32 v183, s25, v180
	v_cmp_gt_u32_e32 vcc, 2.0, v183
	v_subrev_u32_e32 v4, 32, v183
	v_add_u32_e32 v5, -1, v183
	v_add_u32_e32 v6, -2, v183
	v_add_u32_e32 v7, -3, v183
	v_add_u32_e32 v8, -8, v183
	s_waitcnt lgkmcnt(2)
	v_mfma_f32_32x32x16_f16 v[82:97], v[204:207], v[154:157], v[82:97]
	v_add_u32_e32 v9, -9, v183
	v_add_u32_e32 v10, -10, v183
	v_add_u32_e32 v11, -11, v183
	v_add_u32_e32 v12, -16, v183
	v_subrev_u32_e32 v13, 17, v183
	v_subrev_u32_e32 v14, 18, v183
	v_subrev_u32_e32 v15, 19, v183
	s_waitcnt lgkmcnt(1)
	v_mfma_f32_32x32x16_f16 v[98:113], v[220:223], v[158:161], v[98:113]
	v_subrev_u32_e32 v16, 24, v183
	v_subrev_u32_e32 v17, 25, v183
	s_waitcnt lgkmcnt(0)
	v_mfma_f32_32x32x16_f16 v[82:97], v[224:227], v[158:161], v[82:97]
	s_nop 7
	v_cndmask_b32_e32 v98, v218, v98, vcc
	v_cmp_gt_u32_e32 vcc, 2.0, v4
	s_nop 1
	v_cndmask_b32_e32 v4, v218, v82, vcc
	v_cmp_gt_u32_e32 vcc, 2.0, v5
	v_subrev_u32_e32 v5, 33, v183
	v_subrev_u32_e32 v82, 26, v183
	v_cndmask_b32_e32 v99, v218, v99, vcc
	v_cmp_gt_u32_e32 vcc, 2.0, v5
	s_nop 1
	v_cndmask_b32_e32 v5, v218, v83, vcc
	v_cmp_gt_u32_e32 vcc, 2.0, v6
	v_subrev_u32_e32 v6, 34, v183
	v_subrev_u32_e32 v83, 27, v183
	v_cndmask_b32_e32 v100, v218, v100, vcc
	v_cmp_gt_u32_e32 vcc, 2.0, v6
	s_nop 1
	v_cndmask_b32_e32 v6, v218, v84, vcc
	v_cmp_gt_u32_e32 vcc, 2.0, v7
	v_subrev_u32_e32 v7, 35, v183
	s_nop 0
	v_cndmask_b32_e32 v84, v218, v101, vcc
	v_cmp_gt_u32_e32 vcc, 2.0, v7
	s_nop 1
	v_cndmask_b32_e32 v7, v218, v85, vcc
	v_cmp_gt_u32_e32 vcc, 2.0, v8
	v_subrev_u32_e32 v8, 40, v183
	v_max_f32_e32 v85, v99, v99
	v_cndmask_b32_e32 v101, v218, v102, vcc
	v_cmp_gt_u32_e32 vcc, 2.0, v8
	s_nop 1
	v_cndmask_b32_e32 v8, v218, v86, vcc
	v_cmp_gt_u32_e32 vcc, 2.0, v9
	v_subrev_u32_e32 v9, 41, v183
	s_nop 0
	v_cndmask_b32_e32 v86, v218, v103, vcc
	v_cmp_gt_u32_e32 vcc, 2.0, v9
	s_nop 1
	v_cndmask_b32_e32 v9, v218, v87, vcc
	v_cmp_gt_u32_e32 vcc, 2.0, v10
	v_subrev_u32_e32 v10, 42, v183
	s_nop 0
	v_cndmask_b32_e32 v87, v218, v104, vcc
	v_cmp_gt_u32_e32 vcc, 2.0, v10
	s_nop 1
	v_cndmask_b32_e32 v10, v218, v88, vcc
	v_cmp_gt_u32_e32 vcc, 2.0, v11
	v_subrev_u32_e32 v11, 43, v183
	s_nop 0
	v_cndmask_b32_e32 v88, v218, v105, vcc
	v_cmp_gt_u32_e32 vcc, 2.0, v11
	s_nop 1
	v_cndmask_b32_e32 v11, v218, v89, vcc
	v_cmp_gt_u32_e32 vcc, 2.0, v12
	v_subrev_u32_e32 v12, 48, v183
	s_nop 0
	v_cndmask_b32_e32 v89, v218, v106, vcc
	v_cmp_gt_u32_e32 vcc, 2.0, v12
	s_nop 1
	v_cndmask_b32_e32 v12, v218, v90, vcc
	v_cmp_gt_u32_e32 vcc, 2.0, v13
	v_subrev_u32_e32 v13, 49, v183
	s_nop 0
	v_cndmask_b32_e32 v90, v218, v107, vcc
	v_cmp_gt_u32_e32 vcc, 2.0, v13
	s_nop 1
	v_cndmask_b32_e32 v13, v218, v91, vcc
	v_cmp_gt_u32_e32 vcc, 2.0, v14
	v_subrev_u32_e32 v14, 50, v183
	s_nop 0
	v_cndmask_b32_e32 v91, v218, v108, vcc
	v_cmp_gt_u32_e32 vcc, 2.0, v14
	s_nop 1
	v_cndmask_b32_e32 v14, v218, v92, vcc
	v_cmp_gt_u32_e32 vcc, 2.0, v15
	v_subrev_u32_e32 v15, 51, v183
	s_nop 0
	v_cndmask_b32_e32 v92, v218, v109, vcc
	v_cmp_gt_u32_e32 vcc, 2.0, v15
	s_nop 1
	v_cndmask_b32_e32 v15, v218, v93, vcc
	v_cmp_gt_u32_e32 vcc, 2.0, v16
	v_subrev_u32_e32 v16, 56, v183
	s_nop 0
	v_cndmask_b32_e32 v93, v218, v110, vcc
	v_cmp_gt_u32_e32 vcc, 2.0, v16
	s_nop 1
	v_cndmask_b32_e32 v16, v218, v94, vcc
	v_cmp_gt_u32_e32 vcc, 2.0, v17
	v_subrev_u32_e32 v17, 57, v183
	s_nop 0
	v_cndmask_b32_e32 v94, v218, v111, vcc
	v_cmp_gt_u32_e32 vcc, 2.0, v17
	s_nop 1
	v_cndmask_b32_e32 v17, v218, v95, vcc
	v_cmp_gt_u32_e32 vcc, 2.0, v82
	v_subrev_u32_e32 v82, 58, v183
	s_nop 0
	v_cndmask_b32_e32 v95, v218, v112, vcc
	v_cmp_gt_u32_e32 vcc, 2.0, v82
	s_nop 1
	v_cndmask_b32_e32 v82, v218, v96, vcc
	v_cmp_gt_u32_e32 vcc, 2.0, v83
	v_subrev_u32_e32 v83, 59, v183
	s_nop 0
	v_cndmask_b32_e32 v96, v218, v113, vcc
	v_cmp_gt_u32_e32 vcc, 2.0, v83
	s_nop 1
	v_cndmask_b32_e32 v83, v218, v97, vcc
	v_max_f32_e32 v97, v98, v98
	v_max_f32_e32 v85, v97, v85
	v_max3_f32 v85, v85, v100, v84
	v_max3_f32 v85, v85, v101, v86
	v_max3_f32 v85, v85, v87, v88
	v_max3_f32 v85, v85, v89, v90
	v_max3_f32 v85, v85, v91, v92
	v_max3_f32 v85, v85, v93, v94
	v_max3_f32 v85, v85, v95, v96
	v_max3_f32 v85, v85, v4, v5
	v_max3_f32 v85, v85, v6, v7
	v_max3_f32 v85, v85, v8, v9
	v_max3_f32 v85, v85, v10, v11
	v_max3_f32 v85, v85, v12, v13
	v_max3_f32 v85, v85, v14, v15
	v_max3_f32 v85, v85, v16, v17
	v_max3_f32 v85, v85, v82, v83
	v_mov_b32_e32 v97, v85
	s_nop 1
	v_permlane32_swap_b32_e32 v85, v97
	v_max_f32_e32 v97, v97, v97
	v_max_f32_e32 v85, v85, v85
	v_max_f32_e32 v97, v85, v97
	v_sub_f32_e32 v85, v97, v181
	v_mul_f32_e32 v85, 0x3db504f3, v85
	v_cmp_ge_f32_e32 vcc, s87, v85
	s_cmp_eq_u64 vcc, exec
	v_mov_b32_e32 v85, 1.0
	s_cbranch_scc0 .LBB0_4828
	v_cmp_gt_f32_e32 vcc, 1.0, v85
	s_cbranch_vccz .LBB0_4821

; #define NSX_LOADK(kd, ht) do { const h16* kp_ = kc + (size_t)((ht) * 32 + r32) * 128 + hi * 8; _Pragma("unroll") for (int d0 = 0; d0 < 8; ++d0) kd[d0] = *(const half8*)(kp_ + d0 * 16); } while (0)
; __device__ __forceinline__ void imp_select_pair(unsigned char* ws, LAS float* uL, const LAS float* uP, int unit, int hsel, int sub  , bool selw, int lane_in) {
;     ...
;     for (int ht = h_lo; ht < h_hi; ht += 2) {
;         if (ht + 1 < h_hi) NSX_LOADK(kn, ht + 1);
;         NSX_P1(kf, ht);
;         if (ht + 1 < h_hi) { if (ht + 2 < h_hi) NSX_LOADK(kf, ht + 2); NSX_P1(kn, ht + 1); }
;     }
.LBB0_4843:
	s_add_i32 s8, s15, 2
	s_movk_i32 s50, 0xf0
	v_add_u32_e32 v154, 64, v154
	s_cmp_ge_u32 s15, s13
	v_subrev_u32_e32 v166, 64, v166
	s_cbranch_scc1 .LBB0_4846
	s_mov_b32 s15, s8
	v_mov_b32_e32 v156, v168
	v_mov_b32_e32 v155, v167
	s_branch .LBB0_4837

; #define NSX_LOADK(kd, ht) do { const h16* kp_ = kc + (size_t)((ht) * 32 + r32) * 128 + hi * 8; _Pragma("unroll") for (int d0 = 0; d0 < 8; ++d0) kd[d0] = *(const half8*)(kp_ + d0 * 16); } while (0)
; __device__ __forceinline__ void imp_select_pair(unsigned char* ws, LAS float* uL, const LAS float* uP, int unit, int hsel, int sub  , bool selw, int lane_in) {
;     ...
;     for (int ht = h_lo; ht < h_hi; ht += 2) {
;         if (ht + 1 < h_hi) NSX_LOADK(kn, ht + 1);
;         NSX_P2(kf, ht);
;         if (ht + 1 < h_hi) { if (ht + 2 < h_hi) NSX_LOADK(kf, ht + 2); NSX_P2(kn, ht + 1); }
;     }
.LBB0_4859:
	s_add_i32 s6, s8, 2
	s_movk_i32 s50, 0xf0
	v_add_u32_e32 v152, 64, v152
	v_add_u32_e32 v159, 0x800, v159
	s_cmp_ge_u32 s8, s13
	v_subrev_u32_e32 v160, 64, v160
	s_cbranch_scc1 .LBB0_4861
	s_mov_b32 s8, s6
	s_branch .LBB0_4852

; __device__ __forceinline__ void fa_mixer_phase(Frame& F, int l) {
;     ...
;         const int u = fa_ticket(F, F.ctl + CW_QUEUE + 64 * l);
;         if (u >= 512) break;
;         const int qb = 31 - (u >> 4), type = (u >> 2) & 3, h = u & 3, P0 = qb * 256;
;         if (!((FA_MASK >> type) & 1)) continue;
;         fa::UnitArgs U; U.P0 = P0; U.j_lo = 0; U.j_hi = (P0 + 255) / 64 + 1; U.KR = nullptr; U.mk = nullptr; U.gate = nullptr; U.gidx = 0; U.ocmp = nullptr; U.epi = 0; U.old = DM;
;         if (type == 0) {
;             U.Q = (const h16*)(ws + WS_Q192) + ((size_t)h * S + P0) * 192; U.qld = 192; U.K = (const h16*)(ws + WS_KN + (size_t)h * HEADBUF); U.KR = (const h16*)(ws + WS_BKR); U.V = (const h16*)(ws + WS_BV + (size_t)h * HEADBUF);
;             U.O = (h16*)(ws + WS_OMIX) + (size_t)P0 * DM + 512 + h * 128;
;             fa::run_unit<fa::K_MLA>(lds, U, F.tid);
;         } else if (type == 1) {
;             U.Q = (const h16*)(ws + WS_CQROPE + (size_t)h * HEADBUF) + (size_t)P0 * 128; U.qld = 128; U.K = (const h16*)(ws + WS_KSLC); U.V = (const h16*)(ws + WS_VSLC);
;             U.O = (h16*)(ws + WS_OMIX) + (size_t)P0 * DM + 1024 + h * 128; U.mk = ws + WS_NSAMASK; U.gate = (const float*)(ws + WS_SMALL); U.gidx = h * 3 + 1; U.epi = 2;
;             fa::run_unit<fa::K_SLC>(lds, U, F.tid);
;             U.K = (const h16*)(ws + WS_KWIN); U.V = (const h16*)(ws + WS_VWIN); U.j_lo = P0 >= 511 ? (P0 - 511) / 64 : 0; U.gidx = h * 3 + 2; U.epi = 2;
;             fa::run_unit<fa::K_WIN>(lds, U, F.tid);
;         } else if (type == 2) {
;             U.Q = (const h16*)(ws + WS_AQ + (size_t)h * HEADBUF) + (size_t)P0 * 128; U.qld = 128; U.K = (const h16*)(ws + WS_AK + (size_t)h * HEADBUF); U.V = (const h16*)(ws + WS_AV + (size_t)h * HEADBUF);
;             U.O = (h16*)(ws + WS_OMIX) + (size_t)P0 * DM + h * 128; U.mk = (const int*)(ws + WS_MOBASEL) + h * 4;
;             fa::run_unit<fa::K_MOBA>(lds, U, F.tid);
;         } else {
;             U.Q = (const h16*)(ws + WS_DQ + (size_t)h * HEADBUF) + (size_t)P0 * 128; U.qld = 128; U.K = (const h16*)(ws + WS_DK + (size_t)h * HEADBUF); U.V = (const h16*)(ws + WS_DV + (size_t)h * HEADBUF);
;             U.O = (h16*)(ws + WS_OMIX) + (size_t)P0 * DM + 1536 + h * 128; U.mk = ws + WS_DSAMASK;
;             fa::run_unit<fa::K_DSA>(lds, U, F.tid);
.LBB0_4927:
	s_or_b64 exec, exec, s[0:1]
	v_mov_b32_e32 v1, s83
	s_waitcnt vmcnt(0) lgkmcnt(0)
	s_barrier
	ds_read_b32 v1, v1
	s_movk_i32 s0, 0x1ff
	s_waitcnt lgkmcnt(0)
	s_barrier
	v_cmp_lt_i32_e32 vcc, s0, v1
	v_readfirstlane_b32 s2, v1
	s_mov_b64 s[0:1], -1
	s_cbranch_vccnz .LBB0_4922
	s_lshl_b32 s0, s2, 4
	s_and_b32 s12, s0, 0xffffff00
	s_sub_i32 s0, 0x1fc0, s12
	s_lshr_b32 s15, s0, 6
	s_bfe_u32 s10, s2, 0x20002
	s_and_b32 s14, s2, 3
	s_sub_i32 s2, 0x1f00, s12
	s_add_i32 s13, s15, 1
	s_cmp_lt_i32 s10, 2
	s_mov_b64 s[0:1], -1
	s_cbranch_scc1 .LBB0_4968
	s_cmp_gt_i32 s10, 2
	s_cbranch_scc0 .LBB0_4945
	s_lshl_b32 s8, s14, 21
	v_readlane_b32 s0, v253, 60
	s_add_u32 s6, s0, s8
	v_readlane_b32 s0, v253, 61
	s_addc_u32 s7, s0, 0
	s_lshl_b64 s[0:1], s[2:3], 8
	s_add_u32 s0, s6, s0
	s_addc_u32 s1, s7, s1
	v_readlane_b32 s6, v253, 62
	v_mov_b32_e32 v1, v0
	s_add_u32 s6, s6, s8
	v_readlane_b32 s7, v253, 63
	s_addc_u32 s7, s7, 0
	v_ashrrev_i32_e32 v162, 4, v1
	v_readlane_b32 s9, v251, 58
	v_lshlrev_b32_e32 v16, 3, v1
	v_add_u32_e32 v6, 32, v162
	v_ashrrev_i32_e32 v163, 31, v162
	s_add_u32 s8, s9, s8
	v_readlane_b32 s9, v251, 59
	v_and_b32_e32 v2, 0x78, v16
	v_lshlrev_b64 v[8:9], 8, v[162:163]
	v_ashrrev_i32_e32 v7, 31, v6
	s_addc_u32 s9, s9, 0
	v_lshlrev_b32_e32 v4, 1, v2
	v_lshl_add_u64 v[10:11], s[6:7], 0, v[8:9]
	v_mov_b32_e32 v5, v3
	v_lshlrev_b64 v[12:13], 8, v[6:7]
	v_lshl_add_u64 v[10:11], v[10:11], 0, v[4:5]
	v_lshl_add_u64 v[14:15], s[6:7], 0, v[12:13]
	v_lshl_add_u64 v[8:9], s[8:9], 0, v[8:9]
	v_lshl_add_u64 v[14:15], v[14:15], 0, v[4:5]
	global_load_dwordx4 v[114:117], v[10:11], off
	global_load_dwordx4 v[118:121], v[14:15], off
	v_lshl_add_u64 v[8:9], v[8:9], 0, v[4:5]
	v_lshl_add_u64 v[10:11], s[8:9], 0, v[12:13]
	v_lshl_add_u64 v[10:11], v[10:11], 0, v[4:5]
	global_load_dwordx4 v[122:125], v[8:9], off
	global_load_dwordx4 v[126:129], v[10:11], off
	v_readfirstlane_b32 s11, v1
	s_ashr_i32 s16, s11, 6
	v_and_b32_e32 v172, 31, v1
	s_lshl_b32 s11, s16, 5
	v_or_b32_e32 v8, s11, v172
	s_add_i32 s17, s11, s2
	v_ashrrev_i32_e32 v9, 31, v8
	v_bfe_u32 v163, v1, 5, 1
	v_or_b32_e32 v10, s17, v172
	v_lshlrev_b64 v[8:9], 8, v[8:9]
	v_lshlrev_b32_e32 v2, 4, v163
	v_ashrrev_i32_e32 v11, 31, v10
	v_lshl_add_u64 v[8:9], s[0:1], 0, v[8:9]
	v_lshlrev_b64 v[10:11], 10, v[10:11]
	v_lshl_add_u64 v[8:9], v[8:9], 0, v[2:3]
	v_lshl_add_u64 v[12:13], s[84:85], 0, v[10:11]
	global_load_dwordx4 v[130:133], v[8:9], off
	global_load_dwordx4 v[134:137], v[8:9], off offset:32
	global_load_dwordx4 v[138:141], v[8:9], off offset:64
	global_load_dwordx4 v[142:145], v[8:9], off offset:96
	global_load_dwordx2 v[164:165], v[12:13], off
	global_load_dwordx4 v[146:149], v[8:9], off offset:128
	global_load_dwordx4 v[150:153], v[8:9], off offset:160
	global_load_dwordx4 v[154:157], v[8:9], off offset:192
	global_load_dwordx4 v[158:161], v[8:9], off offset:224
	v_and_b32_e32 v7, 0xfffff0, v162
	v_lshlrev_b32_e32 v14, 1, v162
	v_and_or_b32 v7, v14, 8, v7
	v_and_b32_e32 v13, 0xfffff0, v6
	v_lshlrev_b32_e32 v6, 1, v6
	v_lshrrev_b32_e32 v15, 1, v162
	v_bfe_u32 v8, v16, 5, 2
	v_and_b32_e32 v9, 3, v162
	v_lshrrev_b32_e32 v7, 1, v7
	v_and_or_b32 v6, v6, 8, v13
	v_and_or_b32 v9, v15, 4, v9
	v_or_b32_e32 v7, v7, v8
	v_lshrrev_b32_e32 v6, 1, v6
	v_lshlrev_b32_e32 v9, 6, v9
	v_and_b32_e32 v13, 48, v4
	v_lshlrev_b32_e32 v7, 9, v7
	v_or_b32_e32 v6, v6, v8
	v_lshlrev_b32_e32 v12, 8, v162
	v_bitop3_b32 v14, v4, v1, s50 bitop3:0x78
	v_lshlrev_b32_e32 v6, 9, v6
	v_or3_b32 v177, v7, v9, v13
	v_add3_u32 v176, 0, v14, v12
	s_mul_i32 s0, s16, 0x180
	v_or3_b32 v178, v6, v9, v13
	v_add_u32_e32 v6, 0, v177
	s_add_i32 s0, s0, 0
	v_add_u32_e32 v7, 0, v178
	s_waitcnt vmcnt(0)
	v_lshlrev_b32_e32 v175, 4, v1
	v_and_b32_e32 v173, 63, v1
	s_add_i32 s22, s0, 0x14000
	v_lshl_add_u64 v[166:167], s[6:7], 0, v[4:5]
	s_movk_i32 s6, 0x118
	v_bitop3_b32 v181, v2, v175, s50 bitop3:0x78
	v_mov_b32_e32 v17, v3
	v_lshl_add_u64 v[168:169], s[8:9], 0, v[4:5]
	s_waitcnt vmcnt(12)
	ds_write_b128 v176, v[114:117] offset:32768
	s_waitcnt vmcnt(11)
	ds_write_b128 v176, v[118:121] offset:40960
	s_waitcnt vmcnt(10)
	ds_write_b128 v6, v[122:125]
	s_waitcnt vmcnt(9)
	ds_write_b128 v7, v[126:129]
	v_lshlrev_b32_e32 v6, 1, v1
	v_and_b32_e32 v6, 32, v6
	v_and_b32_e32 v1, 0xf0, v175
	v_bitop3_b32 v182, v2, v1, 32 bitop3:0x36
	v_bitop3_b32 v183, v2, v1, 64 bitop3:0x36
	v_bitop3_b32 v184, v2, v1, s77 bitop3:0x36
	v_add_u32_e32 v1, s22, v2
	v_and_or_b32 v2, v16, s6, v6
	v_readlane_b32 s6, v255, 2
	v_and_b32_e32 v7, 0xc0, v175
	v_readlane_b32 s7, v255, 3
	v_mov_b32_e32 v16, v3
	v_add3_u32 v185, v7, 0, v2
	v_lshl_add_u64 v[170:171], s[6:7], 0, v[10:11]
	v_mov_b32_e32 v2, v3
	v_mov_b32_e32 v4, v3
	v_mov_b32_e32 v6, v3
	v_mov_b32_e32 v7, v3
	v_mov_b32_e32 v8, v3
	v_mov_b32_e32 v9, v3
	v_mov_b32_e32 v10, v3
	v_mov_b32_e32 v11, v3
	v_mov_b32_e32 v12, v3
	v_mov_b32_e32 v13, v3
	v_mov_b32_e32 v14, v3
	v_mov_b32_e32 v15, v3
	v_mov_b64_e32 v[32:33], v[16:17]
	v_mov_b64_e32 v[48:49], v[16:17]
	v_mov_b64_e32 v[64:65], v[16:17]
	v_mov_b64_e32 v[80:81], v[16:17]
	s_or_b32 s17, s17, 31
	v_lshl_add_u32 v180, v172, 8, 0
	v_lshlrev_b32_e32 v174, 2, v163
	v_cmp_gt_u32_e64 s[0:1], 32, v173
	v_lshl_add_u32 v179, v172, 2, s22
	s_mov_b32 s22, 0
	v_mov_b32_e32 v187, 0
	v_mov_b32_e32 v186, 0xf149f2ca
	s_movk_i32 s23, 0x4000
	v_mov_b64_e32 v[30:31], v[14:15]
	v_mov_b64_e32 v[28:29], v[12:13]
	v_mov_b64_e32 v[26:27], v[10:11]
	v_mov_b64_e32 v[24:25], v[8:9]
	v_mov_b64_e32 v[22:23], v[6:7]
	v_mov_b64_e32 v[20:21], v[4:5]
	v_mov_b64_e32 v[18:19], v[2:3]
	v_mov_b64_e32 v[46:47], v[14:15]
	v_mov_b64_e32 v[44:45], v[12:13]
	v_mov_b64_e32 v[42:43], v[10:11]
	v_mov_b64_e32 v[40:41], v[8:9]
	v_mov_b64_e32 v[38:39], v[6:7]
	v_mov_b64_e32 v[36:37], v[4:5]
	v_mov_b64_e32 v[34:35], v[2:3]
	v_mov_b64_e32 v[62:63], v[14:15]
	v_mov_b64_e32 v[60:61], v[12:13]
	v_mov_b64_e32 v[58:59], v[10:11]
	v_mov_b64_e32 v[56:57], v[8:9]
	v_mov_b64_e32 v[54:55], v[6:7]
	v_mov_b64_e32 v[52:53], v[4:5]
	v_mov_b64_e32 v[50:51], v[2:3]
	v_mov_b64_e32 v[78:79], v[14:15]
	v_mov_b64_e32 v[76:77], v[12:13]
	v_mov_b64_e32 v[74:75], v[10:11]
	v_mov_b64_e32 v[72:73], v[8:9]
	v_mov_b64_e32 v[70:71], v[6:7]
	v_mov_b64_e32 v[68:69], v[4:5]
	v_mov_b64_e32 v[66:67], v[2:3]
	s_waitcnt vmcnt(4)
	v_mov_b32_e32 v4, v164
	v_mov_b32_e32 v5, v165
	s_mov_b32 s24, 0
	s_waitcnt lgkmcnt(0)
	s_barrier
	s_branch .LBB0_4932

; #define LAS __attribute__((address_space(3)))
; __device__ __forceinline__ void mask_bits(f32x16& p0, f32x16& p1, unsigned lo, unsigned hi_w, int hi) {
;     const unsigned a = lo >> (4 * hi), b = hi_w >> (4 * hi); const unsigned NEGB = 0xFF800000u;
; #pragma unroll
;     for (int r = 0; r < 16; ++r) { const int c = (r & 3) + 8 * (r >> 2);
;         const unsigned ma = (unsigned)__builtin_amdgcn_sbfe((int)a, c, 1), mb = (unsigned)__builtin_amdgcn_sbfe((int)b, c, 1);
;         const float x0 = p0[r], x1 = p1[r];
;         p0[r] = __uint_as_float((__float_as_uint(x0) & ma) | (NEGB & ~ma));
;         p1[r] = __uint_as_float((__float_as_uint(x1) & mb) | (NEGB & ~mb)); }
; }
; __device__ __forceinline__ float max3f(float a, float b, float c) { return __builtin_fmaxf(__builtin_fmaxf(a, b), c); }
; __device__ __forceinline__ void partialSM(f32x16& p0, f32x16& p1, float& m_reg, float& mn, float& alpha, const float sc, const float C2) {
;     float pmax = max3f(p0[0], p0[1], p0[2]);
; #pragma unroll
;     for (int r = 3; r < 15; r += 2) pmax = max3f(pmax, p0[r], p0[r + 1]);
;     pmax = max3f(pmax, p0[15], p1[0]);
; #pragma unroll
;     for (int r = 1; r < 15; r += 2) pmax = max3f(pmax, p1[r], p1[r + 1]);
;     pmax = fmaxf(pmax, p1[15]);
;     { auto rr = __builtin_amdgcn_permlane32_swap(__float_as_uint(pmax), __float_as_uint(pmax), false, false);
;       pmax = fmaxf(__uint_as_float(rr[0]), __uint_as_float(rr[1])); }
; template <bool MLA>
; __device__ __forceinline__ void qkt2(f32x16& p0, f32x16& p1, const LAS char* lds, int kboff, int kroff, int r32, int hi, const half8* qr) {
;     const LAS char* kb[4];
; #pragma unroll
;     for (int dd = 0; dd < 4; ++dd) kb[dd] = lds + OFF_K + kboff + FA_KSWZ(r32, (dd * 16 + hi * 8) * 2);
;     constexpr int NG = MLA ? 6 : 4;
;     half8 fa0[2], fa1[2], fb0[2], fb1[2];
;     ...
; #pragma unroll
;     for (int r = 0; r < 16; ++r) { p0[r] = 0.f; p1[r] = 0.f; }
;     QK_LD(fa0, fa1, 0); FA_SBAR();
;     QK_LD(fb0, fb1, 1); FA_SBAR(); QK_MM(fa0, fa1, 0); FA_SBAR();
;     QK_LD(fa0, fa1, 2); FA_SBAR(); QK_MM(fb0, fb1, 1); FA_SBAR();
;     QK_LD(fb0, fb1, 3); FA_SBAR(); QK_MM(fa0, fa1, 2); FA_SBAR();
;     if constexpr (NG == 6) {
;         QK_LD(fa0, fa1, 4); FA_SBAR(); QK_MM(fb0, fb1, 3); FA_SBAR();
;         QK_LD(fb0, fb1, 5); FA_SBAR(); QK_MM(fa0, fa1, 4); FA_SBAR();
;         QK_MM(fb0, fb1, 5);
;     } else QK_MM(fb0, fb1, 3);
;     ...
; }
.LBB0_4934:
	s_and_b32 s8, s24, 1
	v_mov_b32_e32 v2, s8
	s_cmp_gt_i32 s22, s17
	s_cbranch_scc1 .LBB0_4940
	v_lshlrev_b32_e32 v2, 14, v2
	v_add_u32_e32 v6, v180, v2
	v_add_u32_e32 v196, v6, v181
	v_add_u32_e32 v197, v6, v182
	v_add_u32_e32 v208, v6, v183
	v_add_u32_e32 v209, v6, v184
	ds_read_b128 v[6:9], v196 offset:32768
	ds_read_b128 v[10:13], v196 offset:40960
	ds_read_b128 v[14:17], v197 offset:32768
	ds_read_b128 v[188:191], v197 offset:40960
	ds_read_b128 v[192:195], v208 offset:32768
	ds_read_b128 v[204:207], v208 offset:40960
	ds_read_b128 v[220:223], v209 offset:32768
	ds_read_b128 v[224:227], v209 offset:40960
	s_waitcnt lgkmcnt(7)
	v_mfma_f32_32x32x16_f16 v[82:97], v[6:9], v[130:133], 0
	s_waitcnt lgkmcnt(6)
	v_mfma_f32_32x32x16_f16 v[98:113], v[10:13], v[130:133], 0
	s_waitcnt lgkmcnt(5)
	v_mfma_f32_32x32x16_f16 v[82:97], v[14:17], v[134:137], v[82:97]
	s_waitcnt lgkmcnt(4)
	v_mfma_f32_32x32x16_f16 v[98:113], v[188:191], v[134:137], v[98:113]
	v_xor_b32_e32 v196, 0x80, v196
	ds_read_b128 v[6:9], v196 offset:32768
	ds_read_b128 v[10:13], v196 offset:40960
	v_xor_b32_e32 v197, 0x80, v197
	ds_read_b128 v[14:17], v197 offset:32768
	ds_read_b128 v[188:191], v197 offset:40960
	s_waitcnt lgkmcnt(7)
	v_mfma_f32_32x32x16_f16 v[82:97], v[192:195], v[138:141], v[82:97]
	s_waitcnt lgkmcnt(6)
	v_mfma_f32_32x32x16_f16 v[98:113], v[204:207], v[138:141], v[98:113]
	s_waitcnt lgkmcnt(5)
	v_mfma_f32_32x32x16_f16 v[82:97], v[220:223], v[142:145], v[82:97]
	s_waitcnt lgkmcnt(4)
	v_mfma_f32_32x32x16_f16 v[98:113], v[224:227], v[142:145], v[98:113]
	v_xor_b32_e32 v208, 0x80, v208
	ds_read_b128 v[192:195], v208 offset:32768
	ds_read_b128 v[204:207], v208 offset:40960
	v_xor_b32_e32 v209, 0x80, v209
	ds_read_b128 v[220:223], v209 offset:32768
	ds_read_b128 v[224:227], v209 offset:40960
	s_waitcnt lgkmcnt(7)
	v_mfma_f32_32x32x16_f16 v[82:97], v[6:9], v[146:149], v[82:97]
	s_waitcnt lgkmcnt(6)
	v_mfma_f32_32x32x16_f16 v[98:113], v[10:13], v[146:149], v[98:113]
	s_waitcnt lgkmcnt(5)
	v_mfma_f32_32x32x16_f16 v[82:97], v[14:17], v[150:153], v[82:97]
	s_waitcnt lgkmcnt(4)
	v_mfma_f32_32x32x16_f16 v[98:113], v[188:191], v[150:153], v[98:113]
	s_waitcnt lgkmcnt(3)
	v_mfma_f32_32x32x16_f16 v[82:97], v[192:195], v[154:157], v[82:97]
	v_lshrrev_b32_e32 v189, v174, v164
	v_lshrrev_b32_e32 v190, v174, v165
	v_bfe_i32 v6, v189, 0, 1
	v_bfe_i32 v7, v190, 0, 1
	v_bfe_i32 v8, v190, 1, 1
	v_bfe_i32 v9, v190, 2, 1
	v_bfe_i32 v10, v190, 3, 1
	s_waitcnt lgkmcnt(2)
	v_mfma_f32_32x32x16_f16 v[98:113], v[204:207], v[154:157], v[98:113]
	v_bfe_i32 v11, v190, 8, 1
	v_bfe_i32 v12, v190, 9, 1
	v_bfe_i32 v13, v190, 10, 1
	v_bfe_i32 v14, v190, 11, 1
	v_bfe_i32 v15, v190, 16, 1
	v_bfe_i32 v16, v190, 17, 1
	v_bfe_i32 v17, v190, 18, 1
	s_waitcnt lgkmcnt(1)
	v_mfma_f32_32x32x16_f16 v[82:97], v[220:223], v[158:161], v[82:97]
	s_waitcnt lgkmcnt(0)
	v_mfma_f32_32x32x16_f16 v[98:113], v[224:227], v[158:161], v[98:113]
	s_nop 9
	v_bitop3_b32 v188, v82, s36, v6 bitop3:0xe4
	v_bfe_i32 v82, v190, 19, 1
	v_bitop3_b32 v6, v98, s36, v7 bitop3:0xe4
	v_bfe_i32 v7, v189, 1, 1
	v_bitop3_b32 v98, v83, s36, v7 bitop3:0xe4
	v_bitop3_b32 v7, v99, s36, v8 bitop3:0xe4
	v_bfe_i32 v8, v189, 2, 1
	v_bitop3_b32 v99, v84, s36, v8 bitop3:0xe4
	v_bitop3_b32 v8, v100, s36, v9 bitop3:0xe4
	v_bfe_i32 v9, v189, 3, 1
	v_bitop3_b32 v100, v85, s36, v9 bitop3:0xe4
	v_bitop3_b32 v9, v101, s36, v10 bitop3:0xe4
	v_bfe_i32 v10, v189, 8, 1
	v_bitop3_b32 v101, v86, s36, v10 bitop3:0xe4
	v_bitop3_b32 v10, v102, s36, v11 bitop3:0xe4
	v_bfe_i32 v11, v189, 9, 1
	v_bitop3_b32 v87, v87, s36, v11 bitop3:0xe4
	v_bitop3_b32 v11, v103, s36, v12 bitop3:0xe4
	v_bfe_i32 v12, v189, 10, 1
	v_bitop3_b32 v88, v88, s36, v12 bitop3:0xe4
	v_bitop3_b32 v12, v104, s36, v13 bitop3:0xe4
	v_bfe_i32 v13, v189, 11, 1
	v_bitop3_b32 v89, v89, s36, v13 bitop3:0xe4
	v_bitop3_b32 v13, v105, s36, v14 bitop3:0xe4
	v_bfe_i32 v14, v189, 16, 1
	v_bitop3_b32 v90, v90, s36, v14 bitop3:0xe4
	v_bitop3_b32 v14, v106, s36, v15 bitop3:0xe4
	v_bfe_i32 v15, v189, 17, 1
	v_bitop3_b32 v91, v91, s36, v15 bitop3:0xe4
	v_bitop3_b32 v15, v107, s36, v16 bitop3:0xe4
	v_bfe_i32 v16, v189, 18, 1
	v_bitop3_b32 v92, v92, s36, v16 bitop3:0xe4
	v_bitop3_b32 v16, v108, s36, v17 bitop3:0xe4
	v_bfe_i32 v17, v189, 19, 1
	v_bitop3_b32 v93, v93, s36, v17 bitop3:0xe4
	v_bitop3_b32 v17, v109, s36, v82 bitop3:0xe4
	v_bfe_i32 v82, v189, 24, 1
	v_bfe_i32 v83, v190, 24, 1
	v_bitop3_b32 v94, v94, s36, v82 bitop3:0xe4
	v_bitop3_b32 v82, v110, s36, v83 bitop3:0xe4
	v_bfe_i32 v83, v189, 25, 1
	v_bfe_i32 v84, v190, 25, 1
	v_bitop3_b32 v95, v95, s36, v83 bitop3:0xe4
	v_bitop3_b32 v83, v111, s36, v84 bitop3:0xe4
	v_bfe_i32 v84, v189, 26, 1
	v_bfe_i32 v85, v190, 26, 1
	v_bitop3_b32 v96, v96, s36, v84 bitop3:0xe4
	v_bitop3_b32 v84, v112, s36, v85 bitop3:0xe4
	v_bfe_i32 v85, v189, 27, 1
	v_bfe_i32 v86, v190, 27, 1
	v_bitop3_b32 v97, v97, s36, v85 bitop3:0xe4
	v_bitop3_b32 v85, v113, s36, v86 bitop3:0xe4
	v_max_f32_e32 v86, v98, v98
	v_max_f32_e32 v102, v188, v188
	v_max_f32_e32 v86, v102, v86
	v_max3_f32 v86, v86, v99, v100
	v_max3_f32 v86, v86, v101, v87
	v_max3_f32 v86, v86, v88, v89
	v_max3_f32 v86, v86, v90, v91
	v_max3_f32 v86, v86, v92, v93
	v_max3_f32 v86, v86, v94, v95
	v_max3_f32 v86, v86, v96, v97
	v_max3_f32 v86, v86, v6, v7
	v_max3_f32 v86, v86, v8, v9
	v_max3_f32 v86, v86, v10, v11
	v_max3_f32 v86, v86, v12, v13
	v_max3_f32 v86, v86, v14, v15
	v_max3_f32 v86, v86, v16, v17
	v_max3_f32 v86, v86, v82, v83
	v_max3_f32 v86, v86, v84, v85
	v_mov_b32_e32 v102, v86
	s_nop 1
	v_permlane32_swap_b32_e32 v86, v102
	v_max_f32_e32 v102, v102, v102
	v_max_f32_e32 v86, v86, v86
	v_max_f32_e32 v86, v86, v102
	v_sub_f32_e32 v102, v86, v186
	v_mul_f32_e32 v103, 0x3db504f3, v102
	v_max_f32_e32 v102, v186, v186
	v_max_f32_e32 v102, v102, v86
	v_sub_f32_e32 v86, v186, v102
	v_mul_f32_e32 v86, 0x3e0293ee, v86
	v_exp_f32_e32 v86, v86
	v_cmp_ge_f32_e32 vcc, s87, v103
	s_cmp_eq_u64 vcc, exec
	s_cselect_b64 s[38:39], -1, 0
	v_cndmask_b32_e64 v86, v86, 1.0, s[38:39]
	v_cmp_gt_f32_e32 vcc, 1.0, v86
	s_cbranch_vccz .LBB0_4939
	s_and_saveexec_b64 s[8:9], s[0:1]
	ds_write_b32 v179, v86 offset:128
	s_or_b64 exec, exec, s[8:9]
	s_waitcnt lgkmcnt(0)
	ds_read_b128 v[104:107], v1 offset:224
	ds_read_b128 v[108:111], v1 offset:192
	ds_read_b128 v[190:193], v1 offset:160
	ds_read_b128 v[194:197], v1 offset:128
	s_waitcnt lgkmcnt(3)
	v_pk_mul_f32 v[80:81], v[80:81], v[106:107]
	s_waitcnt lgkmcnt(2)
	v_pk_mul_f32 v[76:77], v[76:77], v[110:111]
	s_waitcnt lgkmcnt(1)
	v_pk_mul_f32 v[72:73], v[72:73], v[192:193]
	s_waitcnt lgkmcnt(0)
	v_pk_mul_f32 v[68:69], v[68:69], v[196:197]
	v_pk_mul_f32 v[78:79], v[78:79], v[104:105]
	v_pk_mul_f32 v[74:75], v[74:75], v[108:109]
	v_pk_mul_f32 v[70:71], v[70:71], v[190:191]
	v_pk_mul_f32 v[66:67], v[66:67], v[194:195]
	v_pk_mul_f32 v[64:65], v[64:65], v[106:107]
	v_pk_mul_f32 v[60:61], v[60:61], v[110:111]
	v_pk_mul_f32 v[56:57], v[56:57], v[192:193]
	v_pk_mul_f32 v[52:53], v[52:53], v[196:197]
	v_pk_mul_f32 v[62:63], v[62:63], v[104:105]
	v_pk_mul_f32 v[58:59], v[58:59], v[108:109]
	v_pk_mul_f32 v[54:55], v[54:55], v[190:191]
	v_pk_mul_f32 v[50:51], v[50:51], v[194:195]
	v_pk_mul_f32 v[48:49], v[48:49], v[106:107]
	v_pk_mul_f32 v[44:45], v[44:45], v[110:111]
	v_pk_mul_f32 v[40:41], v[40:41], v[192:193]
	v_pk_mul_f32 v[36:37], v[36:37], v[196:197]
	v_pk_mul_f32 v[46:47], v[46:47], v[104:105]
	v_pk_mul_f32 v[42:43], v[42:43], v[108:109]
	v_pk_mul_f32 v[38:39], v[38:39], v[190:191]
	v_pk_mul_f32 v[34:35], v[34:35], v[194:195]
	v_pk_mul_f32 v[32:33], v[32:33], v[106:107]
	v_pk_mul_f32 v[28:29], v[28:29], v[110:111]
	v_pk_mul_f32 v[24:25], v[24:25], v[192:193]
	v_pk_mul_f32 v[20:21], v[20:21], v[196:197]
	v_pk_mul_f32 v[30:31], v[30:31], v[104:105]
	v_pk_mul_f32 v[26:27], v[26:27], v[108:109]
	v_pk_mul_f32 v[22:23], v[22:23], v[190:191]
	v_pk_mul_f32 v[18:19], v[18:19], v[194:195]

; __device__ __forceinline__ int v_st(int k, int c) { const int kk = (k & ~0xC) | ((k & 4) << 1) | ((k & 8) >> 1); return ((kk >> 3) * 4 + (c >> 5)) * 512 + ((kk & 7) * 32 + (c & 31)) * 2; }
; __device__ __forceinline__ int v_rd_base(int lane) { return ((lane & 3) << 3) | (((lane >> 2) & 3) << 6) | (((lane >> 4) & 1) << 5) | (((lane >> 5) & 1) << 8); }
; template <int KIND>
; __device__ __forceinline__ void run_unit(LAS char* lds, const UnitArgs& U, int tid_in) {
;     ...
;     if constexpr (KIND == K_MOBA) { const int* s = (const int*)U.mk + (size_t)rowpos * 16;
; #pragma unroll
;         for (int i = 0; i < 3; ++i) { const int b = s[i]; if (b >= 0) mb0 |= 1u << b; } }
;     if constexpr (KIND == K_SLC) { const u32x4 m = *(const u32x4*)((const unsigned*)U.mk + (size_t)rowpos * 4); mb0 = m[0]; mb1 = m[1]; mb2 = m[2]; mb3 = m[3]; }
;     const int nvis_row = rowpos >= 31 ? ((rowpos - 31) >> 4) + 1 : 0;
;     const int NT = U.j_hi - U.j_lo;
;     half8 st_k0, st_k1, st_v0, st_v1, st_kr; unsigned dm_lo = 0, dm_hi = 0, dn_lo = 0, dn_hi = 0;
;     const int kws = FA_KSWZ(sr, sc * 2), vst0 = v_st(sr, sc), vst1 = v_st(32 + sr, sc), krw = FA_KRSWZ(tid >> 3, (tid & 7) * 16);
;     const int vb0 = (int)(unsigned)(size_t)(lds + OFF_V) + v_rd_base(lane);
;     ...
;     float m_reg = -1e30f, l_reg = 0.f; f32x16 o[4];
; #pragma unroll
;     for (int d = 0; d < 4; ++d)
; #pragma unroll
;         for (int r = 0; r < 16; ++r) o[d][r] = 0.f;
;     FA_LOADT(U.j_lo); asm volatile("s_waitcnt vmcnt(0)" ::: "memory"); FA_WRITET(0); dm_lo = dn_lo; dm_hi = dn_hi;
;     __syncthreads();
; __device__ __forceinline__ void fa_mixer_phase(Frame& F, int l) {
;     ...
;             U.Q = (const h16*)(ws + WS_AQ + (size_t)h * HEADBUF) + (size_t)P0 * 128; U.qld = 128; U.K = (const h16*)(ws + WS_AK + (size_t)h * HEADBUF); U.V = (const h16*)(ws + WS_AV + (size_t)h * HEADBUF);
;             U.O = (h16*)(ws + WS_OMIX) + (size_t)P0 * DM + h * 128; U.mk = (const int*)(ws + WS_MOBASEL) + h * 4;
;             fa::run_unit<fa::K_MOBA>(lds, U, F.tid);
.LBB0_4945:
	s_and_b64 vcc, exec, s[0:1]
	s_cbranch_vccz .LBB0_4967
	s_lshl_b32 s8, s14, 21
	v_readlane_b32 s0, v253, 38
	s_add_u32 s6, s0, s8
	v_readlane_b32 s0, v253, 39
	s_addc_u32 s7, s0, 0
	s_lshl_b64 s[0:1], s[2:3], 8
	s_add_u32 s0, s6, s0
	s_addc_u32 s1, s7, s1
	v_readlane_b32 s6, v253, 13
	s_add_u32 s6, s6, s8
	v_readlane_b32 s7, v253, 14
	s_addc_u32 s7, s7, 0
	v_readlane_b32 s9, v252, 4
	s_add_u32 s8, s9, s8
	v_readlane_b32 s9, v252, 5
	s_addc_u32 s9, s9, 0
	s_lshl_b32 s11, s14, 4
	v_readlane_b32 s16, v253, 36
	v_mov_b32_e32 v1, v0
	v_readlane_b32 s17, v253, 37
	s_add_u32 s22, s16, s11
	s_addc_u32 s23, s17, 0
	v_readfirstlane_b32 s11, v1
	s_ashr_i32 s11, s11, 6
	s_lshl_b32 s16, s11, 5
	v_and_b32_e32 v220, 31, v1
	s_add_i32 s17, s16, s2
	v_ashrrev_i32_e32 v204, 4, v1
	v_lshlrev_b32_e32 v7, 3, v1
	v_or_b32_e32 v4, s17, v220
	v_ashrrev_i32_e32 v205, 31, v204
	v_ashrrev_i32_e32 v5, 31, v4
	v_and_b32_e32 v2, 0x78, v7
	v_lshlrev_b64 v[12:13], 8, v[204:205]
	v_lshlrev_b64 v[4:5], 6, v[4:5]
	v_lshlrev_b32_e32 v8, 1, v2
	v_add_u32_e32 v10, 32, v204
	v_lshl_add_u64 v[14:15], s[6:7], 0, v[12:13]
	v_mov_b32_e32 v9, v3
	v_lshl_add_u64 v[4:5], s[22:23], 0, v[4:5]
	v_lshl_add_u64 v[14:15], v[14:15], 0, v[8:9]
	v_ashrrev_i32_e32 v11, 31, v10
	global_load_dwordx3 v[4:6], v[4:5], off
	v_lshl_add_u64 v[12:13], s[8:9], 0, v[12:13]
	global_load_dwordx4 v[146:149], v[14:15], off
	v_lshlrev_b64 v[14:15], 8, v[10:11]
	v_lshl_add_u64 v[16:17], s[6:7], 0, v[14:15]
	v_lshl_add_u64 v[16:17], v[16:17], 0, v[8:9]
	v_lshl_add_u64 v[12:13], v[12:13], 0, v[8:9]
	global_load_dwordx4 v[150:153], v[16:17], off
	global_load_dwordx4 v[154:157], v[12:13], off
	v_lshl_add_u64 v[12:13], s[8:9], 0, v[14:15]
	v_lshl_add_u64 v[12:13], v[12:13], 0, v[8:9]
	global_load_dwordx4 v[158:161], v[12:13], off
	v_and_b32_e32 v11, 0xfffff0, v204
	v_lshlrev_b32_e32 v12, 1, v204
	v_lshrrev_b32_e32 v13, 1, v204
	v_and_b32_e32 v15, 3, v204
	v_and_or_b32 v11, v12, 8, v11
	v_and_or_b32 v12, v13, 4, v15
	v_and_b32_e32 v13, 0xfffff0, v10
	v_lshlrev_b32_e32 v15, 1, v10
	v_or_b32_e32 v10, s16, v220
	v_lshrrev_b32_e32 v18, 1, v11
	v_ashrrev_i32_e32 v11, 31, v10
	v_bfe_u32 v205, v1, 5, 1
	v_lshlrev_b64 v[10:11], 8, v[10:11]
	v_lshlrev_b32_e32 v2, 4, v205
	v_lshl_add_u64 v[10:11], s[0:1], 0, v[10:11]
	v_lshl_add_u64 v[10:11], v[10:11], 0, v[2:3]
	global_load_dwordx4 v[162:165], v[10:11], off
	global_load_dwordx4 v[166:169], v[10:11], off offset:32
	global_load_dwordx4 v[170:173], v[10:11], off offset:64
	global_load_dwordx4 v[174:177], v[10:11], off offset:96
	global_load_dwordx4 v[178:181], v[10:11], off offset:128
	global_load_dwordx4 v[182:185], v[10:11], off offset:160
	global_load_dwordx4 v[186:189], v[10:11], off offset:192
	global_load_dwordx4 v[190:193], v[10:11], off offset:224
	v_and_or_b32 v10, v15, 8, v13
	v_bfe_u32 v14, v7, 5, 2
	v_lshrrev_b32_e32 v10, 1, v10
	v_or_b32_e32 v10, v10, v14
	v_lshlrev_b32_e32 v12, 6, v12
	v_and_b32_e32 v11, 48, v8
	v_or_b32_e32 v13, v18, v14
	v_lshlrev_b32_e32 v10, 9, v10
	v_lshlrev_b32_e32 v13, 9, v13
	v_or3_b32 v225, v10, v12, v11
	v_or3_b32 v224, v13, v12, v11
	v_lshlrev_b32_e32 v16, 8, v204
	v_bitop3_b32 v17, v8, v1, s50 bitop3:0x78
	v_add3_u32 v228, 0, v17, v16
	s_mul_i32 s0, s11, 0x180
	s_waitcnt vmcnt(0)
	s_add_i32 s0, s0, 0
	v_lshlrev_b32_e32 v223, 4, v1
	v_and_b32_e32 v221, 63, v1
	s_add_i32 s25, s0, 0x14000
	v_lshl_add_u64 v[206:207], s[6:7], 0, v[8:9]
	s_movk_i32 s6, 0x118
	v_bitop3_b32 v230, v2, v223, s50 bitop3:0x78
	v_lshlrev_b32_e32 v222, 2, v205
	v_mov_b32_e32 v16, v3
	v_mov_b32_e32 v17, v3
	v_lshl_add_u64 v[208:209], s[8:9], 0, v[8:9]
	v_mov_b32_e32 v8, v3
	s_waitcnt vmcnt(11)
	ds_write_b128 v228, v[146:149] offset:32768
	s_waitcnt vmcnt(10)
	ds_write_b128 v228, v[150:153] offset:40960
	v_lshlrev_b32_e64 v10, v5, 1
	v_cmp_lt_i32_e32 vcc, -1, v5
	v_lshlrev_b32_e64 v11, v6, 1
	v_lshlrev_b32_e64 v12, v4, 1
	v_cndmask_b32_e32 v5, 0, v10, vcc
	v_cmp_lt_i32_e32 vcc, -1, v6
	v_mov_b32_e32 v10, v3
	v_mov_b32_e32 v13, v3
	v_cndmask_b32_e32 v6, 0, v11, vcc
	v_cmp_lt_i32_e32 vcc, -1, v4
	v_mov_b32_e32 v11, v3
	v_mov_b32_e32 v14, v3
	v_cndmask_b32_e32 v4, 0, v12, vcc
	v_or3_b32 v227, v5, v4, v6
	v_add_u32_e32 v4, 0, v224
	s_waitcnt vmcnt(9)
	ds_write_b128 v4, v[154:157]
	v_add_u32_e32 v4, 0, v225
	s_waitcnt vmcnt(8)
	ds_write_b128 v4, v[158:161]
	v_lshlrev_b32_e32 v4, 1, v1
	v_and_b32_e32 v4, 32, v4
	v_and_b32_e32 v1, 0xf0, v223
	v_and_b32_e32 v5, 0xc0, v223
	v_bitop3_b32 v231, v2, v1, 32 bitop3:0x36
	v_bitop3_b32 v232, v2, v1, 64 bitop3:0x36
	v_bitop3_b32 v233, v2, v1, s77 bitop3:0x36
	v_add_u32_e32 v1, s25, v2
	v_and_or_b32 v2, v7, s6, v4
	s_add_i32 s6, s16, 0x1ec5
	v_add3_u32 v234, v5, 0, v2
	v_add_u32_e32 v2, s6, v220
	v_sub_u32_e32 v2, v2, v222
	v_subrev_u32_e32 v235, s12, v2
	v_mov_b32_e32 v2, v3
	v_mov_b32_e32 v4, v3
	v_mov_b32_e32 v5, v3
	v_mov_b32_e32 v6, v3
	v_mov_b32_e32 v7, v3
	v_mov_b32_e32 v12, v3
	v_mov_b32_e32 v15, v3
	v_mov_b64_e32 v[32:33], v[16:17]
	v_mov_b64_e32 v[48:49], v[16:17]
	v_mov_b64_e32 v[64:65], v[16:17]
	v_mov_b64_e32 v[80:81], v[16:17]
	s_mov_b32 s22, 63
	s_mov_b32 s23, 0
	s_or_b32 s24, s17, 31
	v_lshl_add_u32 v229, v220, 8, 0
	v_cmp_gt_u32_e64 s[0:1], 32, v221
	v_lshl_add_u32 v226, v220, 2, s25
	s_ashr_i32 s25, s2, 8
	v_mov_b32_e32 v237, 0
	v_mov_b32_e32 v236, 0xf149f2ca
	s_movk_i32 s37, 0x4000
	v_mov_b64_e32 v[30:31], v[14:15]
	v_mov_b64_e32 v[28:29], v[12:13]
	v_mov_b64_e32 v[26:27], v[10:11]
	v_mov_b64_e32 v[24:25], v[8:9]
	v_mov_b64_e32 v[22:23], v[6:7]
	v_mov_b64_e32 v[20:21], v[4:5]
	v_mov_b64_e32 v[18:19], v[2:3]
	v_mov_b64_e32 v[46:47], v[14:15]
	v_mov_b64_e32 v[44:45], v[12:13]
	v_mov_b64_e32 v[42:43], v[10:11]
	v_mov_b64_e32 v[40:41], v[8:9]
	v_mov_b64_e32 v[38:39], v[6:7]
	v_mov_b64_e32 v[36:37], v[4:5]
	v_mov_b64_e32 v[34:35], v[2:3]
	v_mov_b64_e32 v[62:63], v[14:15]
	v_mov_b64_e32 v[60:61], v[12:13]
	v_mov_b64_e32 v[58:59], v[10:11]
	v_mov_b64_e32 v[56:57], v[8:9]
	v_mov_b64_e32 v[54:55], v[6:7]
	v_mov_b64_e32 v[52:53], v[4:5]
	v_mov_b64_e32 v[50:51], v[2:3]
	v_mov_b64_e32 v[78:79], v[14:15]
	v_mov_b64_e32 v[76:77], v[12:13]
	v_mov_b64_e32 v[74:75], v[10:11]
	v_mov_b64_e32 v[72:73], v[8:9]
	v_mov_b64_e32 v[70:71], v[6:7]
	v_mov_b64_e32 v[68:69], v[4:5]
	v_mov_b64_e32 v[66:67], v[2:3]
	s_waitcnt lgkmcnt(0)
	s_barrier
	s_branch .LBB0_4948

; #define LAS __attribute__((address_space(3)))
; #define FA_SBAR() __builtin_amdgcn_sched_barrier(0)
; #define QK_MM(F0, F1, g) do { _Pragma("unroll") for (int e = 0; e < 2; ++e) { const int d0 = 2 * (g) + e; \
;         p0 = __builtin_amdgcn_mfma_f32_32x32x16_f16(F0[e], qr[d0], p0, 0, 0, 0); p1 = __builtin_amdgcn_mfma_f32_32x32x16_f16(F1[e], qr[d0], p1, 0, 0, 0); } } while (0)
; template <bool MLA>
; __device__ __forceinline__ void qkt2(f32x16& p0, f32x16& p1, const LAS char* lds, int kboff, int kroff, int r32, int hi, const half8* qr) {
;     const LAS char* kb[4];
; #pragma unroll
;     for (int dd = 0; dd < 4; ++dd) kb[dd] = lds + OFF_K + kboff + FA_KSWZ(r32, (dd * 16 + hi * 8) * 2);
;     constexpr int NG = MLA ? 6 : 4;
;     half8 fa0[2], fa1[2], fb0[2], fb1[2];
;     ...
; #pragma unroll
;     for (int r = 0; r < 16; ++r) { p0[r] = 0.f; p1[r] = 0.f; }
;     QK_LD(fa0, fa1, 0); FA_SBAR();
;     QK_LD(fb0, fb1, 1); FA_SBAR(); QK_MM(fa0, fa1, 0); FA_SBAR();
;     QK_LD(fa0, fa1, 2); FA_SBAR(); QK_MM(fb0, fb1, 1); FA_SBAR();
;     QK_LD(fb0, fb1, 3); FA_SBAR(); QK_MM(fa0, fa1, 2); FA_SBAR();
;     if constexpr (NG == 6) {
;         QK_LD(fa0, fa1, 4); FA_SBAR(); QK_MM(fb0, fb1, 3); FA_SBAR();
;         QK_LD(fb0, fb1, 5); FA_SBAR(); QK_MM(fa0, fa1, 4); FA_SBAR();
;         QK_MM(fb0, fb1, 5);
;     } else QK_MM(fb0, fb1, 3);
;     ...
; }
.LBB0_4950:
	s_sub_i32 s8, s22, 63
	s_and_b32 s9, s23, 1
	v_mov_b32_e32 v2, s9
	s_cmp_gt_i32 s8, s24
	s_cbranch_scc1 .LBB0_4962
	v_lshlrev_b32_e32 v2, 14, v2
	v_add_u32_e32 v4, v229, v2
	v_add_u32_e32 v16, v4, v230
	v_add_u32_e32 v17, v4, v231
	v_add_u32_e32 v102, v4, v232
	v_add_u32_e32 v103, v4, v233
	ds_read_b128 v[4:7], v16 offset:32768
	ds_read_b128 v[8:11], v16 offset:40960
	ds_read_b128 v[12:15], v17 offset:32768
	ds_read_b128 v[82:85], v17 offset:40960
	ds_read_b128 v[86:89], v102 offset:32768
	ds_read_b128 v[90:93], v102 offset:40960
	ds_read_b128 v[94:97], v103 offset:32768
	ds_read_b128 v[98:101], v103 offset:40960
	s_waitcnt lgkmcnt(7)
	v_mfma_f32_32x32x16_f16 v[114:129], v[4:7], v[162:165], 0
	s_waitcnt lgkmcnt(6)
	v_mfma_f32_32x32x16_f16 v[130:145], v[8:11], v[162:165], 0
	s_waitcnt lgkmcnt(5)
	v_mfma_f32_32x32x16_f16 v[114:129], v[12:15], v[166:169], v[114:129]
	s_waitcnt lgkmcnt(4)
	v_mfma_f32_32x32x16_f16 v[130:145], v[82:85], v[166:169], v[130:145]
	v_xor_b32_e32 v16, 0x80, v16
	ds_read_b128 v[4:7], v16 offset:32768
	ds_read_b128 v[8:11], v16 offset:40960
	v_xor_b32_e32 v17, 0x80, v17
	ds_read_b128 v[12:15], v17 offset:32768
	ds_read_b128 v[82:85], v17 offset:40960
	s_waitcnt lgkmcnt(7)
	v_mfma_f32_32x32x16_f16 v[114:129], v[86:89], v[170:173], v[114:129]
	s_waitcnt lgkmcnt(6)
	v_mfma_f32_32x32x16_f16 v[130:145], v[90:93], v[170:173], v[130:145]
	s_waitcnt lgkmcnt(5)
	v_mfma_f32_32x32x16_f16 v[114:129], v[94:97], v[174:177], v[114:129]
	s_waitcnt lgkmcnt(4)
	v_mfma_f32_32x32x16_f16 v[130:145], v[98:101], v[174:177], v[130:145]
	v_xor_b32_e32 v102, 0x80, v102
	ds_read_b128 v[86:89], v102 offset:32768
	ds_read_b128 v[90:93], v102 offset:40960
	v_xor_b32_e32 v103, 0x80, v103
	ds_read_b128 v[94:97], v103 offset:32768
	ds_read_b128 v[98:101], v103 offset:40960
	s_waitcnt lgkmcnt(7)
	v_mfma_f32_32x32x16_f16 v[114:129], v[4:7], v[178:181], v[114:129]
	s_waitcnt lgkmcnt(6)
	v_mfma_f32_32x32x16_f16 v[130:145], v[8:11], v[178:181], v[130:145]
	s_waitcnt lgkmcnt(5)
	v_mfma_f32_32x32x16_f16 v[114:129], v[12:15], v[182:185], v[114:129]
	s_waitcnt lgkmcnt(4)
	v_mfma_f32_32x32x16_f16 v[130:145], v[82:85], v[182:185], v[130:145]
	s_waitcnt lgkmcnt(3)
	v_mfma_f32_32x32x16_f16 v[114:129], v[86:89], v[186:189], v[114:129]
	s_lshr_b32 s38, s23, 2
	s_mov_b64 s[8:9], -1
	s_cmp_lg_u32 s38, s25
	s_waitcnt lgkmcnt(2)
	v_mfma_f32_32x32x16_f16 v[130:145], v[90:93], v[186:189], v[130:145]
	s_waitcnt lgkmcnt(1)
	v_mfma_f32_32x32x16_f16 v[114:129], v[94:97], v[190:193], v[114:129]
	s_waitcnt lgkmcnt(0)
	v_mfma_f32_32x32x16_f16 v[130:145], v[98:101], v[190:193], v[130:145]
	s_cbranch_scc0 .LBB0_4953
	v_bfe_u32 v4, v227, s38, 1
	v_cmp_eq_u32_e32 vcc, 0, v4
	s_mov_b64 s[8:9], 0
	s_nop 5
	v_cndmask_b32_e32 v98, v114, v218, vcc
	s_nop 0
	v_cndmask_b32_e32 v82, v130, v218, vcc
	v_cndmask_b32_e32 v99, v115, v218, vcc
	v_cndmask_b32_e32 v83, v131, v218, vcc
	v_cndmask_b32_e32 v100, v116, v218, vcc
	v_cndmask_b32_e32 v84, v132, v218, vcc
	v_cndmask_b32_e32 v101, v117, v218, vcc
	v_cndmask_b32_e32 v85, v133, v218, vcc
	v_cndmask_b32_e32 v102, v118, v218, vcc
	v_cndmask_b32_e32 v86, v134, v218, vcc
	v_cndmask_b32_e32 v103, v119, v218, vcc
	v_cndmask_b32_e32 v87, v135, v218, vcc
	v_cndmask_b32_e32 v104, v120, v218, vcc
	v_cndmask_b32_e32 v88, v136, v218, vcc
	v_cndmask_b32_e32 v105, v121, v218, vcc
	v_cndmask_b32_e32 v89, v137, v218, vcc
	v_cndmask_b32_e32 v106, v122, v218, vcc
	v_cndmask_b32_e32 v90, v138, v218, vcc
	v_cndmask_b32_e32 v107, v123, v218, vcc
	v_cndmask_b32_e32 v91, v139, v218, vcc
	v_cndmask_b32_e32 v108, v124, v218, vcc
	v_cndmask_b32_e32 v92, v140, v218, vcc
	v_cndmask_b32_e32 v109, v125, v218, vcc
	v_cndmask_b32_e32 v93, v141, v218, vcc
	v_cndmask_b32_e32 v110, v126, v218, vcc
	v_cndmask_b32_e32 v94, v142, v218, vcc
	v_cndmask_b32_e32 v111, v127, v218, vcc
	v_cndmask_b32_e32 v95, v143, v218, vcc
	v_cndmask_b32_e32 v112, v128, v218, vcc
	v_cndmask_b32_e32 v96, v144, v218, vcc
	v_cndmask_b32_e32 v113, v129, v218, vcc
	v_cndmask_b32_e32 v97, v145, v218, vcc

; template <int KIND>
; __device__ __forceinline__ void run_unit(LAS char* lds, const UnitArgs& U, int tid_in) {
;     ...
;     int tid = tid_in; asm volatile("" : "+v"(tid));
;     const int wid = __builtin_amdgcn_readfirstlane(tid >> 6), lane = tid & 63, r32 = lane & 31, hi = lane >> 5;
;     const int sr = tid >> 4, sc = (tid & 15) * 8;
;     const int qlo = U.P0 + wid * 32, rowpos = qlo + r32;
;     const float sc_ = MLA ? SC192 : SC128; const float C2 = 1.4426950408889634f * sc_;
;     LAS float* wsf = (LAS float*)(lds + OFF_WS) + wid * 96; LAS float* li_l = wsf; LAS float* al_l = wsf + 32; LAS float* g_l = wsf + 64;
;     half8 qr[MLA ? 12 : 8];
;     { const h16* qp = U.Q + (size_t)(wid * 32 + r32) * U.qld + hi * 8;
; #pragma unroll
;       for (int d0 = 0; d0 < (MLA ? 12 : 8); ++d0) qr[d0] = *(const half8*)(qp + d0 * 16); }
;     unsigned mb0 = 0, mb1 = 0, mb2 = 0, mb3 = 0;
;     if constexpr (KIND == K_MOBA) { const int* s = (const int*)U.mk + (size_t)rowpos * 16;
; #pragma unroll
;         for (int i = 0; i < 3; ++i) { const int b = s[i]; if (b >= 0) mb0 |= 1u << b; } }
;     if constexpr (KIND == K_SLC) { const u32x4 m = *(const u32x4*)((const unsigned*)U.mk + (size_t)rowpos * 4); mb0 = m[0]; mb1 = m[1]; mb2 = m[2]; mb3 = m[3]; }
;     const int nvis_row = rowpos >= 31 ? ((rowpos - 31) >> 4) + 1 : 0;
;     const int NT = U.j_hi - U.j_lo;
;     half8 st_k0, st_k1, st_v0, st_v1, st_kr; unsigned dm_lo = 0, dm_hi = 0, dn_lo = 0, dn_hi = 0;
;     const int kws = FA_KSWZ(sr, sc * 2), vst0 = v_st(sr, sc), vst1 = v_st(32 + sr, sc), krw = FA_KRSWZ(tid >> 3, (tid & 7) * 16);
;     const int vb0 = (int)(unsigned)(size_t)(lds + OFF_V) + v_rd_base(lane);
;     ...
;     float m_reg = -1e30f, l_reg = 0.f; f32x16 o[4];
; #pragma unroll
;     for (int d = 0; d < 4; ++d)
; #pragma unroll
;         for (int r = 0; r < 16; ++r) o[d][r] = 0.f;
;     FA_LOADT(U.j_lo); asm volatile("s_waitcnt vmcnt(0)" ::: "memory"); FA_WRITET(0); dm_lo = dn_lo; dm_hi = dn_hi;
;     __syncthreads();
; __device__ __forceinline__ void fa_mixer_phase(Frame& F, int l) {
;     ...
;         if (type == 0) {
;             U.Q = (const h16*)(ws + WS_Q192) + ((size_t)h * S + P0) * 192; U.qld = 192; U.K = (const h16*)(ws + WS_KN + (size_t)h * HEADBUF); U.KR = (const h16*)(ws + WS_BKR); U.V = (const h16*)(ws + WS_BV + (size_t)h * HEADBUF);
;             U.O = (h16*)(ws + WS_OMIX) + (size_t)P0 * DM + 512 + h * 128;
.LBB0_4968:
	s_andn2_b64 vcc, exec, s[0:1]
	s_cbranch_vccnz .LBB0_4921
	s_cmp_eq_u32 s10, 1
	s_mov_b64 s[0:1], -1
	s_cbranch_scc1 .LBB0_4987
	s_lshl_b32 s0, s14, 13
	s_add_i32 s0, s0, s2
	s_mul_hi_u32 s1, s0, 0x180
	s_mulk_i32 s0, 0x180
	v_readlane_b32 s6, v252, 30
	s_add_u32 s0, s6, s0
	v_readlane_b32 s6, v252, 31
	s_addc_u32 s1, s6, s1
	s_lshl_b32 s8, s14, 21
	v_readlane_b32 s6, v252, 24
	v_mov_b32_e32 v1, v0
	s_add_u32 s6, s6, s8
	v_readlane_b32 s7, v252, 25
	s_addc_u32 s7, s7, 0
	s_waitcnt vmcnt(10)
	v_ashrrev_i32_e32 v182, 4, v1
	v_readlane_b32 s9, v252, 26
	v_lshlrev_b32_e32 v18, 3, v1
	v_add_u32_e32 v6, 32, v182
	v_ashrrev_i32_e32 v183, 31, v182
	s_add_u32 s8, s9, s8
	v_readlane_b32 s9, v252, 27
	v_and_b32_e32 v2, 0x78, v18
	v_lshlrev_b64 v[10:11], 8, v[182:183]
	v_ashrrev_i32_e32 v7, 31, v6
	s_addc_u32 s9, s9, 0
	v_lshlrev_b32_e32 v4, 1, v2
	v_lshl_add_u64 v[12:13], s[6:7], 0, v[10:11]
	v_mov_b32_e32 v5, v3
	v_lshlrev_b64 v[14:15], 8, v[6:7]
	v_ashrrev_i32_e32 v8, 3, v1
	v_lshl_add_u64 v[12:13], v[12:13], 0, v[4:5]
	v_lshl_add_u64 v[16:17], s[6:7], 0, v[14:15]
	v_lshl_add_u64 v[10:11], s[8:9], 0, v[10:11]
	v_lshl_add_u64 v[16:17], v[16:17], 0, v[4:5]
	global_load_dwordx4 v[114:117], v[12:13], off
	global_load_dwordx4 v[118:121], v[16:17], off
	v_lshl_add_u64 v[10:11], v[10:11], 0, v[4:5]
	v_lshl_add_u64 v[12:13], s[8:9], 0, v[14:15]
	v_ashrrev_i32_e32 v9, 31, v8
	v_readlane_b32 s24, v252, 10
	v_lshl_add_u64 v[12:13], v[12:13], 0, v[4:5]
	global_load_dwordx4 v[122:125], v[10:11], off
	global_load_dwordx4 v[126:129], v[12:13], off
	v_lshlrev_b64 v[10:11], 7, v[8:9]
	v_readlane_b32 s25, v252, 11
	s_waitcnt vmcnt(12)
	v_lshlrev_b32_e32 v190, 4, v1
	v_readfirstlane_b32 s10, v1
	v_lshl_add_u64 v[10:11], s[24:25], 0, v[10:11]
	v_and_b32_e32 v12, 0x70, v190
	v_mov_b32_e32 v13, v3
	s_ashr_i32 s10, s10, 6
	v_lshl_add_u64 v[10:11], v[10:11], 0, v[12:13]
	v_and_b32_e32 v191, 31, v1
	s_lshl_b32 s11, s10, 5
	global_load_dwordx4 v[178:181], v[10:11], off
	v_bfe_u32 v183, v1, 5, 1
	v_or_b32_e32 v2, s11, v191
	v_mov_b64_e32 v[10:11], s[0:1]
	s_movk_i32 s0, 0x180
	v_mad_i64_i32 v[10:11], s[0:1], v2, s0, v[10:11]
	v_lshlrev_b32_e32 v2, 4, v183
	v_lshl_add_u64 v[10:11], v[10:11], 0, v[2:3]
	global_load_dwordx4 v[130:133], v[10:11], off
	global_load_dwordx4 v[134:137], v[10:11], off offset:32
	global_load_dwordx4 v[138:141], v[10:11], off offset:64
	global_load_dwordx4 v[142:145], v[10:11], off offset:96
	global_load_dwordx4 v[146:149], v[10:11], off offset:128
	global_load_dwordx4 v[150:153], v[10:11], off offset:160
	global_load_dwordx4 v[154:157], v[10:11], off offset:192
	global_load_dwordx4 v[158:161], v[10:11], off offset:224
	global_load_dwordx4 v[162:165], v[10:11], off offset:256
	global_load_dwordx4 v[166:169], v[10:11], off offset:288
	global_load_dwordx4 v[170:173], v[10:11], off offset:320
	global_load_dwordx4 v[174:177], v[10:11], off offset:352
	v_and_b32_e32 v9, 0xfffff0, v182
	v_lshlrev_b32_e32 v10, 1, v182
	v_and_or_b32 v9, v10, 8, v9
	v_lshrrev_b32_e32 v10, 1, v182
	v_and_b32_e32 v14, 3, v182
	v_and_or_b32 v10, v10, 4, v14
	v_and_b32_e32 v14, 0xfffff0, v6
	v_lshlrev_b32_e32 v6, 1, v6
	v_lshrrev_b32_e32 v9, 1, v9
	v_bfe_u32 v11, v18, 5, 2
	v_and_or_b32 v6, v6, 8, v14
	v_or_b32_e32 v9, v9, v11
	v_lshrrev_b32_e32 v6, 1, v6
	v_lshlrev_b32_e32 v9, 9, v9
	v_lshlrev_b32_e32 v10, 6, v10
	v_or_b32_e32 v6, v6, v11
	v_xor_b32_e32 v11, v8, v1
	v_and_b32_e32 v15, 48, v4
	s_mul_i32 s17, s10, 0x180
	v_bitop3_b32 v7, v4, v1, s50 bitop3:0x78
	v_lshlrev_b32_e32 v6, 9, v6
	v_lshlrev_b32_e32 v11, 4, v11
	v_lshlrev_b32_e32 v14, 8, v182
	v_or3_b32 v204, v9, v10, v15
	v_and_b32_e32 v192, 63, v1
	s_add_i32 s17, s17, 0
	v_and_b32_e32 v11, 0x70, v11
	v_or3_b32 v205, v6, v10, v15
	v_lshlrev_b32_e32 v6, 7, v8
	v_add3_u32 v207, 0, v7, v14
	v_add_u32_e32 v7, 0, v204
	s_add_i32 s0, 0, 0x10000
	v_lshlrev_b32_e32 v1, 1, v1
	s_add_i32 s22, s17, 0x14000
	s_waitcnt vmcnt(0)
	s_waitcnt vmcnt(16)
	ds_write_b128 v207, v[114:117] offset:32768
	s_waitcnt vmcnt(15)
	ds_write_b128 v207, v[118:121] offset:40960
	v_add3_u32 v208, s0, v11, v6
	v_and_b32_e32 v6, 32, v1
	v_lshl_add_u64 v[184:185], s[6:7], 0, v[4:5]
	s_movk_i32 s6, 0x118
	s_waitcnt vmcnt(14)
	ds_write_b128 v7, v[122:125]
	v_add_u32_e32 v7, 0, v205
	s_waitcnt vmcnt(13)
	ds_write_b128 v7, v[126:129]
	v_and_b32_e32 v7, 0xc0, v190
	v_xor_b32_e32 v220, v2, v12
	v_bitop3_b32 v221, v2, v12, 32 bitop3:0x36
	v_bitop3_b32 v222, v2, v12, 64 bitop3:0x36
	v_bitop3_b32 v223, v2, v12, s77 bitop3:0x36
	v_add_u32_e32 v1, s22, v2
	v_and_or_b32 v2, v18, s6, v6
	s_add_i32 s6, s11, 0x1ec5
	v_lshlrev_b32_e32 v193, 2, v183
	v_add3_u32 v225, v7, 0, v2
	v_add_u32_e32 v2, s6, v191
	v_sub_u32_e32 v2, v2, v193
	v_mov_b32_e32 v16, v3
	v_mov_b32_e32 v17, v3
	s_add_i32 s16, s11, s2
	v_lshl_add_u64 v[186:187], s[8:9], 0, v[4:5]
	v_lshl_add_u64 v[188:189], s[24:25], 0, v[12:13]
	v_subrev_u32_e32 v226, s12, v2
	v_add_u32_e32 v227, 64, v8
	v_mov_b32_e32 v2, v3
	v_mov_b32_e32 v4, v3
	v_mov_b32_e32 v6, v3
	v_mov_b32_e32 v7, v3
	v_mov_b32_e32 v8, v3
	v_mov_b32_e32 v9, v3
	v_mov_b32_e32 v10, v3
	v_mov_b32_e32 v11, v3
	v_mov_b32_e32 v12, v3
	v_mov_b32_e32 v14, v3
	v_mov_b32_e32 v15, v3
	v_mov_b64_e32 v[32:33], v[16:17]
	v_mov_b64_e32 v[48:49], v[16:17]
	v_mov_b64_e32 v[64:65], v[16:17]
	v_mov_b64_e32 v[80:81], v[16:17]
	s_or_b32 s17, s16, 31
	v_lshl_add_u32 v209, v191, 8, 0
	v_and_b32_e32 v229, 8, v191
	v_lshl_or_b32 v209, v229, 4, v209
	v_lshl_add_u32 v224, v191, 7, s0
	v_cmp_gt_u32_e64 s[0:1], 32, v192
	v_lshl_add_u32 v206, v191, 2, s22
	s_mov_b32 s22, 0
	v_mov_b32_e32 v229, 0
	v_mov_b32_e32 v228, 0xf149f2ca
	v_mov_b64_e32 v[30:31], v[14:15]
	v_mov_b64_e32 v[28:29], v[12:13]
	v_mov_b64_e32 v[26:27], v[10:11]
	v_mov_b64_e32 v[24:25], v[8:9]
	v_mov_b64_e32 v[22:23], v[6:7]
	v_mov_b64_e32 v[20:21], v[4:5]
	v_mov_b64_e32 v[18:19], v[2:3]
	v_mov_b64_e32 v[46:47], v[14:15]
	v_mov_b64_e32 v[44:45], v[12:13]
	v_mov_b64_e32 v[42:43], v[10:11]
	v_mov_b64_e32 v[40:41], v[8:9]
	v_mov_b64_e32 v[38:39], v[6:7]
	v_mov_b64_e32 v[36:37], v[4:5]
	v_mov_b64_e32 v[34:35], v[2:3]
	v_mov_b64_e32 v[62:63], v[14:15]
	v_mov_b64_e32 v[60:61], v[12:13]
	v_mov_b64_e32 v[58:59], v[10:11]
	v_mov_b64_e32 v[56:57], v[8:9]
	v_mov_b64_e32 v[54:55], v[6:7]
	v_mov_b64_e32 v[52:53], v[4:5]
	v_mov_b64_e32 v[50:51], v[2:3]
	v_mov_b64_e32 v[78:79], v[14:15]
	v_mov_b64_e32 v[76:77], v[12:13]
	v_mov_b64_e32 v[74:75], v[10:11]
	v_mov_b64_e32 v[72:73], v[8:9]
	v_mov_b64_e32 v[70:71], v[6:7]
	v_mov_b64_e32 v[68:69], v[4:5]
	v_mov_b64_e32 v[66:67], v[2:3]
	s_mov_b32 s23, 0
	s_waitcnt vmcnt(12)
	ds_write_b128 v208, v[178:181]
	s_waitcnt lgkmcnt(0)
	s_barrier
	s_branch .LBB0_4972

; #define LAS __attribute__((address_space(3)))
; #define FA_SBAR() __builtin_amdgcn_sched_barrier(0)
; #define QK_MM(F0, F1, g) do { _Pragma("unroll") for (int e = 0; e < 2; ++e) { const int d0 = 2 * (g) + e; \
;         p0 = __builtin_amdgcn_mfma_f32_32x32x16_f16(F0[e], qr[d0], p0, 0, 0, 0); p1 = __builtin_amdgcn_mfma_f32_32x32x16_f16(F1[e], qr[d0], p1, 0, 0, 0); } } while (0)
; template <bool MLA>
; __device__ __forceinline__ void qkt2(f32x16& p0, f32x16& p1, const LAS char* lds, int kboff, int kroff, int r32, int hi, const half8* qr) {
;     const LAS char* kb[4];
; #pragma unroll
;     for (int dd = 0; dd < 4; ++dd) kb[dd] = lds + OFF_K + kboff + FA_KSWZ(r32, (dd * 16 + hi * 8) * 2);
;     constexpr int NG = MLA ? 6 : 4;
;     half8 fa0[2], fa1[2], fb0[2], fb1[2];
;     ...
; #pragma unroll
;     for (int r = 0; r < 16; ++r) { p0[r] = 0.f; p1[r] = 0.f; }
;     QK_LD(fa0, fa1, 0); FA_SBAR();
;     QK_LD(fb0, fb1, 1); FA_SBAR(); QK_MM(fa0, fa1, 0); FA_SBAR();
;     QK_LD(fa0, fa1, 2); FA_SBAR(); QK_MM(fb0, fb1, 1); FA_SBAR();
;     QK_LD(fb0, fb1, 3); FA_SBAR(); QK_MM(fa0, fa1, 2); FA_SBAR();
;     if constexpr (NG == 6) {
;         QK_LD(fa0, fa1, 4); FA_SBAR(); QK_MM(fb0, fb1, 3); FA_SBAR();
;         QK_LD(fb0, fb1, 5); FA_SBAR(); QK_MM(fa0, fa1, 4); FA_SBAR();
;         QK_MM(fb0, fb1, 5);
;     } else QK_MM(fb0, fb1, 3);
;     ...
; }
.LBB0_4974:
	s_and_b32 s8, s23, 1
	v_mov_b32_e32 v4, s8
	s_cmp_gt_i32 s22, s17
	s_cbranch_scc1 .LBB0_4982
	v_lshlrev_b32_e32 v2, 14, v4
	v_add_u32_e32 v5, v209, v2
	v_add_u32_e32 v214, v5, v220
	v_add_u32_e32 v248, v5, v221
	ds_read_b128 v[6:9], v214 offset:32768
	ds_read_b128 v[10:13], v214 offset:40960
	ds_read_b128 v[14:17], v248 offset:32768
	ds_read_b128 v[230:233], v248 offset:40960
	v_add_u32_e32 v249, v5, v222
	v_add_u32_e32 v5, v5, v223
	ds_read_b128 v[234:237], v249 offset:32768
	ds_read_b128 v[240:243], v249 offset:40960
	ds_read_b128 v[244:247], v5 offset:32768
	ds_read_b128 v[194:197], v5 offset:40960
	s_waitcnt lgkmcnt(7)
	v_mfma_f32_32x32x16_f16 v[98:113], v[6:9], v[130:133], 0
	s_waitcnt lgkmcnt(6)
	v_mfma_f32_32x32x16_f16 v[82:97], v[10:13], v[130:133], 0
	s_waitcnt lgkmcnt(5)
	v_mfma_f32_32x32x16_f16 v[98:113], v[14:17], v[134:137], v[98:113]
	s_waitcnt lgkmcnt(4)
	v_mfma_f32_32x32x16_f16 v[82:97], v[230:233], v[134:137], v[82:97]
	v_xor_b32_e32 v214, 0x80, v214
	ds_read_b128 v[6:9], v214 offset:32768
	ds_read_b128 v[10:13], v214 offset:40960
	v_xor_b32_e32 v248, 0x80, v248
	ds_read_b128 v[14:17], v248 offset:32768
	ds_read_b128 v[230:233], v248 offset:40960
	s_waitcnt lgkmcnt(7)
	v_mfma_f32_32x32x16_f16 v[98:113], v[234:237], v[138:141], v[98:113]
	s_waitcnt lgkmcnt(6)
	v_mfma_f32_32x32x16_f16 v[82:97], v[240:243], v[138:141], v[82:97]
	s_waitcnt lgkmcnt(5)
	v_mfma_f32_32x32x16_f16 v[98:113], v[244:247], v[142:145], v[98:113]
	s_waitcnt lgkmcnt(4)
	v_mfma_f32_32x32x16_f16 v[82:97], v[194:197], v[142:145], v[82:97]
	v_xor_b32_e32 v249, 0x80, v249
	ds_read_b128 v[194:197], v249 offset:32768
	ds_read_b128 v[234:237], v249 offset:40960
	v_xor_b32_e32 v5, 0x80, v5
	ds_read_b128 v[240:243], v5 offset:32768
	ds_read_b128 v[244:247], v5 offset:40960
	s_waitcnt lgkmcnt(7)
	v_mfma_f32_32x32x16_f16 v[98:113], v[6:9], v[146:149], v[98:113]
	s_waitcnt lgkmcnt(6)
	v_mfma_f32_32x32x16_f16 v[82:97], v[10:13], v[146:149], v[82:97]
	s_waitcnt lgkmcnt(5)
	v_mfma_f32_32x32x16_f16 v[98:113], v[14:17], v[150:153], v[98:113]
	s_waitcnt lgkmcnt(4)
	v_mfma_f32_32x32x16_f16 v[82:97], v[230:233], v[150:153], v[82:97]
	v_lshl_add_u32 v16, v4, 13, v224
	v_add_u32_e32 v8, v16, v220
	v_add_u32_e32 v17, v16, v221
	ds_read_b128 v[4:7], v8
	ds_read_b128 v[8:11], v8 offset:4096
	ds_read_b128 v[12:15], v17
	ds_read_b128 v[230:233], v17 offset:4096
	s_waitcnt lgkmcnt(7)
	v_mfma_f32_32x32x16_f16 v[98:113], v[194:197], v[154:157], v[98:113]
	s_waitcnt lgkmcnt(6)
	v_mfma_f32_32x32x16_f16 v[82:97], v[234:237], v[154:157], v[82:97]
	s_waitcnt lgkmcnt(5)
	v_mfma_f32_32x32x16_f16 v[98:113], v[240:243], v[158:161], v[98:113]
	s_waitcnt lgkmcnt(4)
	v_mfma_f32_32x32x16_f16 v[82:97], v[244:247], v[158:161], v[82:97]
	v_add_u32_e32 v17, v16, v222
	v_add_u32_e32 v16, v16, v223
	ds_read_b128 v[194:197], v17
	ds_read_b128 v[234:237], v17 offset:4096
	ds_read_b128 v[240:243], v16
	ds_read_b128 v[244:247], v16 offset:4096
	s_waitcnt lgkmcnt(7)
	v_mfma_f32_32x32x16_f16 v[98:113], v[4:7], v[162:165], v[98:113]
	s_waitcnt lgkmcnt(6)
	v_mfma_f32_32x32x16_f16 v[82:97], v[8:11], v[162:165], v[82:97]
	s_waitcnt lgkmcnt(5)
	v_mfma_f32_32x32x16_f16 v[98:113], v[12:15], v[166:169], v[98:113]
	s_waitcnt lgkmcnt(4)
	v_mfma_f32_32x32x16_f16 v[82:97], v[230:233], v[166:169], v[82:97]
	s_waitcnt lgkmcnt(3)
	v_mfma_f32_32x32x16_f16 v[98:113], v[194:197], v[170:173], v[98:113]
	s_add_i32 s8, s22, 63
	s_cmp_le_i32 s8, s16
	s_waitcnt lgkmcnt(2)
	v_mfma_f32_32x32x16_f16 v[82:97], v[234:237], v[170:173], v[82:97]
	s_waitcnt lgkmcnt(1)
	v_mfma_f32_32x32x16_f16 v[98:113], v[240:243], v[174:177], v[98:113]
	s_waitcnt lgkmcnt(0)
	v_mfma_f32_32x32x16_f16 v[82:97], v[244:247], v[174:177], v[82:97]
	s_cbranch_scc1 .LBB0_4977
; __device__ __forceinline__ void mask_tile(f32x16& p0, f32x16& p1, int dq, unsigned W) {
;     const float NEG = -__builtin_inff();
; #pragma unroll
;     for (int r = 0; r < 16; ++r) { const int c = (r & 3) + 8 * (r >> 2);
;         if ((unsigned)(dq - c) >= W) p0[r] = NEG;
;         if ((unsigned)(dq - c - 32) >= W) p1[r] = NEG; }
; }
	v_add_u32_e32 v4, 59, v226
	v_cmp_gt_u32_e32 vcc, 2.0, v4
	v_add_u32_e32 v4, 27, v226
	s_nop 5
	v_cndmask_b32_e32 v98, v218, v98, vcc
	v_cmp_gt_u32_e32 vcc, 2.0, v4
	v_add_u32_e32 v4, 58, v226
	s_nop 0
	v_cndmask_b32_e32 v82, v218, v82, vcc
	v_cmp_gt_u32_e32 vcc, 2.0, v4
	v_add_u32_e32 v4, 26, v226
	s_nop 0
	v_cndmask_b32_e32 v99, v218, v99, vcc
	v_cmp_gt_u32_e32 vcc, 2.0, v4
	v_add_u32_e32 v4, 57, v226
	s_nop 0
	v_cndmask_b32_e32 v83, v218, v83, vcc
	v_cmp_gt_u32_e32 vcc, 2.0, v4
	v_add_u32_e32 v4, 25, v226
	s_nop 0
	v_cndmask_b32_e32 v100, v218, v100, vcc
	v_cmp_gt_u32_e32 vcc, 2.0, v4
	v_add_u32_e32 v4, 56, v226
	s_nop 0
	v_cndmask_b32_e32 v84, v218, v84, vcc
	v_cmp_gt_u32_e32 vcc, 2.0, v4
	v_add_u32_e32 v4, 24, v226
	s_nop 0
	v_cndmask_b32_e32 v101, v218, v101, vcc
	v_cmp_gt_u32_e32 vcc, 2.0, v4
	v_add_u32_e32 v4, 51, v226
	s_nop 0
	v_cndmask_b32_e32 v85, v218, v85, vcc
	v_cmp_gt_u32_e32 vcc, 2.0, v4
	v_add_u32_e32 v4, 19, v226
	s_nop 0
	v_cndmask_b32_e32 v102, v218, v102, vcc
	v_cmp_gt_u32_e32 vcc, 2.0, v4
	v_add_u32_e32 v4, 50, v226
	s_nop 0
	v_cndmask_b32_e32 v86, v218, v86, vcc
	v_cmp_gt_u32_e32 vcc, 2.0, v4
	v_add_u32_e32 v4, 18, v226
	s_nop 0
	v_cndmask_b32_e32 v103, v218, v103, vcc
	v_cmp_gt_u32_e32 vcc, 2.0, v4
	v_add_u32_e32 v4, 49, v226
	s_nop 0
	v_cndmask_b32_e32 v87, v218, v87, vcc
	v_cmp_gt_u32_e32 vcc, 2.0, v4
	v_add_u32_e32 v4, 17, v226
	s_nop 0
	v_cndmask_b32_e32 v104, v218, v104, vcc
	v_cmp_gt_u32_e32 vcc, 2.0, v4
	v_add_u32_e32 v4, 48, v226
	s_nop 0
	v_cndmask_b32_e32 v88, v218, v88, vcc
	v_cmp_gt_u32_e32 vcc, 2.0, v4
	v_add_u32_e32 v4, 16, v226
	s_nop 0
	v_cndmask_b32_e32 v105, v218, v105, vcc
	v_cmp_gt_u32_e32 vcc, 2.0, v4
	v_add_u32_e32 v4, 43, v226
	s_nop 0
	v_cndmask_b32_e32 v89, v218, v89, vcc
	v_cmp_gt_u32_e32 vcc, 2.0, v4
	v_add_u32_e32 v4, 11, v226
	s_nop 0
	v_cndmask_b32_e32 v106, v218, v106, vcc
	v_cmp_gt_u32_e32 vcc, 2.0, v4
	v_add_u32_e32 v4, 42, v226
	s_nop 0
	v_cndmask_b32_e32 v90, v218, v90, vcc
	v_cmp_gt_u32_e32 vcc, 2.0, v4
	v_add_u32_e32 v4, 10, v226
	s_nop 0
	v_cndmask_b32_e32 v107, v218, v107, vcc
	v_cmp_gt_u32_e32 vcc, 2.0, v4
	v_add_u32_e32 v4, 41, v226
	s_nop 0
	v_cndmask_b32_e32 v91, v218, v91, vcc
	v_cmp_gt_u32_e32 vcc, 2.0, v4
	v_add_u32_e32 v4, 9, v226
	s_nop 0
	v_cndmask_b32_e32 v108, v218, v108, vcc
	v_cmp_gt_u32_e32 vcc, 2.0, v4
	v_add_u32_e32 v4, 40, v226
	s_nop 0
	v_cndmask_b32_e32 v92, v218, v92, vcc
	v_cmp_gt_u32_e32 vcc, 2.0, v4
	v_add_u32_e32 v4, 8, v226
	s_nop 0
	v_cndmask_b32_e32 v109, v218, v109, vcc
	v_cmp_gt_u32_e32 vcc, 2.0, v4
	v_add_u32_e32 v4, 35, v226
	s_nop 0
	v_cndmask_b32_e32 v93, v218, v93, vcc
	v_cmp_gt_u32_e32 vcc, 2.0, v4
	v_add_u32_e32 v4, 3, v226
	s_nop 0
	v_cndmask_b32_e32 v110, v218, v110, vcc
	v_cmp_gt_u32_e32 vcc, 2.0, v4
	v_add_u32_e32 v4, 34, v226
	s_nop 0
	v_cndmask_b32_e32 v94, v218, v94, vcc
	v_cmp_gt_u32_e32 vcc, 2.0, v4
	v_add_u32_e32 v4, 2, v226
	s_nop 0
	v_cndmask_b32_e32 v111, v218, v111, vcc
	v_cmp_gt_u32_e32 vcc, 2.0, v4
	v_add_u32_e32 v4, 33, v226
	s_nop 0
	v_cndmask_b32_e32 v95, v218, v95, vcc
	v_cmp_gt_u32_e32 vcc, 2.0, v4
	v_add_u32_e32 v4, 1, v226
	s_nop 0
	v_cndmask_b32_e32 v112, v218, v112, vcc
	v_cmp_gt_u32_e32 vcc, 2.0, v4
	v_add_u32_e32 v4, 32, v226
	s_nop 0
	v_cndmask_b32_e32 v96, v218, v96, vcc
	v_cmp_gt_u32_e32 vcc, 2.0, v4
	s_nop 1
	v_cndmask_b32_e32 v113, v218, v113, vcc
	v_cmp_gt_u32_e32 vcc, 2.0, v226
	s_nop 1
	v_cndmask_b32_e32 v97, v218, v97, vcc

; #define LAS __attribute__((address_space(3)))
; __device__ __forceinline__ int v_st(int k, int c) { const int kk = (k & ~0xC) | ((k & 4) << 1) | ((k & 8) >> 1); return ((kk >> 3) * 4 + (c >> 5)) * 512 + ((kk & 7) * 32 + (c & 31)) * 2; }
; __device__ __forceinline__ int v_rd_base(int lane) { return ((lane & 3) << 3) | (((lane >> 2) & 3) << 6) | (((lane >> 4) & 1) << 5) | (((lane >> 5) & 1) << 8); }
; template <int KIND>
; __device__ __forceinline__ void run_unit(LAS char* lds, const UnitArgs& U, int tid_in) {
;     ...
;     const int wid = __builtin_amdgcn_readfirstlane(tid >> 6), lane = tid & 63, r32 = lane & 31, hi = lane >> 5;
;     const int sr = tid >> 4, sc = (tid & 15) * 8;
;     const int qlo = U.P0 + wid * 32, rowpos = qlo + r32;
;     const float sc_ = MLA ? SC192 : SC128; const float C2 = 1.4426950408889634f * sc_;
;     LAS float* wsf = (LAS float*)(lds + OFF_WS) + wid * 96; LAS float* li_l = wsf; LAS float* al_l = wsf + 32; LAS float* g_l = wsf + 64;
;     half8 qr[MLA ? 12 : 8];
;     { const h16* qp = U.Q + (size_t)(wid * 32 + r32) * U.qld + hi * 8;
; #pragma unroll
;       for (int d0 = 0; d0 < (MLA ? 12 : 8); ++d0) qr[d0] = *(const half8*)(qp + d0 * 16); }
;     unsigned mb0 = 0, mb1 = 0, mb2 = 0, mb3 = 0;
;     if constexpr (KIND == K_MOBA) { const int* s = (const int*)U.mk + (size_t)rowpos * 16;
; #pragma unroll
;         for (int i = 0; i < 3; ++i) { const int b = s[i]; if (b >= 0) mb0 |= 1u << b; } }
;     if constexpr (KIND == K_SLC) { const u32x4 m = *(const u32x4*)((const unsigned*)U.mk + (size_t)rowpos * 4); mb0 = m[0]; mb1 = m[1]; mb2 = m[2]; mb3 = m[3]; }
;     const int nvis_row = rowpos >= 31 ? ((rowpos - 31) >> 4) + 1 : 0;
;     const int NT = U.j_hi - U.j_lo;
;     half8 st_k0, st_k1, st_v0, st_v1, st_kr; unsigned dm_lo = 0, dm_hi = 0, dn_lo = 0, dn_hi = 0;
;     const int kws = FA_KSWZ(sr, sc * 2), vst0 = v_st(sr, sc), vst1 = v_st(32 + sr, sc), krw = FA_KRSWZ(tid >> 3, (tid & 7) * 16);
;     const int vb0 = (int)(unsigned)(size_t)(lds + OFF_V) + v_rd_base(lane);
;     ...
;     float m_reg = -1e30f, l_reg = 0.f; f32x16 o[4];
; #pragma unroll
;     for (int d = 0; d < 4; ++d)
; #pragma unroll
;         for (int r = 0; r < 16; ++r) o[d][r] = 0.f;
;     FA_LOADT(U.j_lo); asm volatile("s_waitcnt vmcnt(0)" ::: "memory"); FA_WRITET(0); dm_lo = dn_lo; dm_hi = dn_hi;
;     __syncthreads();
.LBB0_4987:
	s_and_b64 vcc, exec, s[0:1]
	s_cbranch_vccz .LBB0_4921
	v_mov_b32_e32 v1, v0
	s_lshl_b32 s0, s14, 21
	s_waitcnt vmcnt(10)
	v_ashrrev_i32_e32 v166, 4, v1
	v_readlane_b32 s1, v254, 0
	v_lshlrev_b32_e32 v14, 3, v1
	v_ashrrev_i32_e32 v167, 31, v166
	v_readlane_b32 s40, v254, 2
	s_add_u32 s6, s1, s0
	v_readlane_b32 s0, v254, 1
	v_and_b32_e32 v2, 0x78, v14
	v_lshlrev_b64 v[8:9], 8, v[166:167]
	v_readlane_b32 s41, v254, 3
	s_addc_u32 s7, s0, 0
	s_lshl_b64 s[0:1], s[2:3], 8
	v_lshlrev_b32_e32 v4, 1, v2
	v_add_u32_e32 v6, 32, v166
	v_lshl_add_u64 v[10:11], s[40:41], 0, v[8:9]
	v_mov_b32_e32 v5, v3
	v_readfirstlane_b32 s10, v1
	s_add_u32 s8, s6, s0
	v_lshl_add_u64 v[10:11], v[10:11], 0, v[4:5]
	v_ashrrev_i32_e32 v7, 31, v6
	v_readlane_b32 s38, v251, 50
	s_addc_u32 s9, s7, s1
	s_ashr_i32 s16, s10, 6
	global_load_dwordx4 v[114:117], v[10:11], off
	v_lshlrev_b64 v[10:11], 8, v[6:7]
	v_readlane_b32 s39, v251, 51
	s_lshl_b32 s17, s16, 5
	v_lshl_add_u64 v[12:13], s[40:41], 0, v[10:11]
	v_lshl_add_u64 v[8:9], s[38:39], 0, v[8:9]
	s_waitcnt vmcnt(9)
	v_and_b32_e32 v174, 31, v1
	s_add_i32 s23, s17, s2
	v_lshl_add_u64 v[12:13], v[12:13], 0, v[4:5]
	v_lshl_add_u64 v[8:9], v[8:9], 0, v[4:5]
	v_or_b32_e32 v168, s23, v174
	v_readlane_b32 s0, v253, 58
	global_load_dwordx4 v[118:121], v[12:13], off
	global_load_dwordx4 v[122:125], v[8:9], off
	v_lshl_add_u64 v[8:9], s[38:39], 0, v[10:11]
	v_ashrrev_i32_e32 v169, 31, v168
	v_readlane_b32 s1, v253, 59
	v_lshl_add_u64 v[8:9], v[8:9], 0, v[4:5]
	global_load_dwordx4 v[126:129], v[8:9], off
	v_lshl_add_u64 v[10:11], v[168:169], 4, s[0:1]
	global_load_dwordx4 v[130:133], v[10:11], off
	v_or_b32_e32 v8, s17, v174
	v_ashrrev_i32_e32 v9, 31, v8
	v_bfe_u32 v167, v1, 5, 1
	v_lshlrev_b64 v[8:9], 8, v[8:9]
	v_lshlrev_b32_e32 v2, 4, v167
	v_lshl_add_u64 v[8:9], s[8:9], 0, v[8:9]
	v_lshl_add_u64 v[8:9], v[8:9], 0, v[2:3]
	global_load_dwordx4 v[134:137], v[8:9], off
	global_load_dwordx4 v[138:141], v[8:9], off offset:32
	global_load_dwordx4 v[142:145], v[8:9], off offset:64
	global_load_dwordx4 v[146:149], v[8:9], off offset:96
	global_load_dwordx4 v[150:153], v[8:9], off offset:128
	global_load_dwordx4 v[154:157], v[8:9], off offset:160
	global_load_dwordx4 v[158:161], v[8:9], off offset:192
	global_load_dwordx4 v[162:165], v[8:9], off offset:224
	v_and_b32_e32 v7, 0xfffff0, v166
	v_lshlrev_b32_e32 v12, 1, v166
	v_and_or_b32 v7, v12, 8, v7
	v_and_b32_e32 v11, 0xfffff0, v6
	v_lshlrev_b32_e32 v6, 1, v6
	v_lshrrev_b32_e32 v13, 1, v166
	v_bfe_u32 v8, v14, 5, 2
	v_and_b32_e32 v9, 3, v166
	v_lshrrev_b32_e32 v7, 1, v7
	v_and_or_b32 v6, v6, 8, v11
	v_and_or_b32 v9, v13, 4, v9
	v_or_b32_e32 v7, v7, v8
	v_lshrrev_b32_e32 v6, 1, v6
	v_lshlrev_b32_e32 v9, 6, v9
	v_and_b32_e32 v11, 48, v4
	v_lshlrev_b32_e32 v7, 9, v7
	v_or_b32_e32 v6, v6, v8
	v_lshlrev_b32_e32 v10, 8, v166
	s_mul_i32 s0, s16, 0x180
	v_bitop3_b32 v12, v4, v1, s50 bitop3:0x78
	v_lshlrev_b32_e32 v6, 9, v6
	v_or3_b32 v180, v7, v9, v11
	s_add_i32 s0, s0, 0
	v_add3_u32 v179, 0, v12, v10
	v_or3_b32 v181, v6, v9, v11
	v_add_u32_e32 v6, 0, v180
	v_lshlrev_b32_e32 v177, 4, v1
	v_and_b32_e32 v176, 63, v1
	s_add_i32 s6, s0, 0x14000
	v_add_u32_e32 v7, 0, v181
	s_waitcnt vmcnt(0)
	v_lshl_add_u32 v178, v174, 2, s6
	v_bitop3_b32 v183, v2, v177, s50 bitop3:0x78
	v_lshlrev_b32_e32 v175, 2, v167
	v_mov_b32_e32 v16, v3
	s_waitcnt vmcnt(12)
	ds_write_b128 v179, v[114:117] offset:32768
	s_waitcnt vmcnt(11)
	ds_write_b128 v179, v[118:121] offset:40960
	s_waitcnt vmcnt(10)
	ds_write_b128 v6, v[122:125]
	s_waitcnt vmcnt(9)
	ds_write_b128 v7, v[126:129]
	v_lshlrev_b32_e32 v6, 1, v1
	v_and_b32_e32 v1, 0xf0, v177
	v_and_b32_e32 v6, 32, v6
	v_bitop3_b32 v184, v2, v1, 32 bitop3:0x36
	v_bitop3_b32 v185, v2, v1, 64 bitop3:0x36
	v_bitop3_b32 v186, v2, v1, s77 bitop3:0x36
	v_add_u32_e32 v1, s6, v2
	s_movk_i32 s6, 0x118
	v_and_b32_e32 v7, 0xc0, v177
	v_and_or_b32 v2, v14, s6, v6
	s_add_i32 s6, s17, 0x1ec5
	v_add3_u32 v187, v7, 0, v2
	v_add_u32_e32 v2, s6, v174
	v_sub_u32_e32 v2, v2, v175
	v_mov_b32_e32 v17, v3
	v_lshl_add_u64 v[170:171], s[40:41], 0, v[4:5]
	v_lshl_add_u64 v[172:173], s[38:39], 0, v[4:5]
	v_subrev_u32_e32 v188, s12, v2
	v_mov_b32_e32 v2, v3
	v_mov_b32_e32 v4, v3
	v_mov_b32_e32 v6, v3
	v_mov_b32_e32 v7, v3
	v_mov_b32_e32 v8, v3
	v_mov_b32_e32 v9, v3
	v_mov_b32_e32 v10, v3
	v_mov_b32_e32 v11, v3
	v_mov_b32_e32 v12, v3
	v_mov_b32_e32 v13, v3
	v_mov_b32_e32 v14, v3
	v_mov_b32_e32 v15, v3
	v_mov_b64_e32 v[32:33], v[16:17]
	v_mov_b64_e32 v[48:49], v[16:17]
	v_mov_b64_e32 v[64:65], v[16:17]
	v_mov_b64_e32 v[80:81], v[16:17]
	s_mov_b32 s22, 63
	s_or_b32 s24, s23, 31
	v_lshl_add_u32 v182, v174, 8, 0
	v_cmp_gt_u32_e64 s[0:1], 32, v176
	s_mov_b32 s25, 0
	v_mov_b32_e32 v190, 0
	v_mov_b32_e32 v189, 0xf149f2ca
	s_movk_i32 s37, 0x4000
	v_mov_b64_e32 v[30:31], v[14:15]
	v_mov_b64_e32 v[28:29], v[12:13]
	v_mov_b64_e32 v[26:27], v[10:11]
	v_mov_b64_e32 v[24:25], v[8:9]
	v_mov_b64_e32 v[22:23], v[6:7]
	v_mov_b64_e32 v[20:21], v[4:5]
	v_mov_b64_e32 v[18:19], v[2:3]
	v_mov_b64_e32 v[46:47], v[14:15]
	v_mov_b64_e32 v[44:45], v[12:13]
	v_mov_b64_e32 v[42:43], v[10:11]
	v_mov_b64_e32 v[40:41], v[8:9]
	v_mov_b64_e32 v[38:39], v[6:7]
	v_mov_b64_e32 v[36:37], v[4:5]
	v_mov_b64_e32 v[34:35], v[2:3]
	v_mov_b64_e32 v[62:63], v[14:15]
	v_mov_b64_e32 v[60:61], v[12:13]
	v_mov_b64_e32 v[58:59], v[10:11]
	v_mov_b64_e32 v[56:57], v[8:9]
	v_mov_b64_e32 v[54:55], v[6:7]
	v_mov_b64_e32 v[52:53], v[4:5]
	v_mov_b64_e32 v[50:51], v[2:3]
	v_mov_b64_e32 v[78:79], v[14:15]
	v_mov_b64_e32 v[76:77], v[12:13]
	v_mov_b64_e32 v[74:75], v[10:11]
	v_mov_b64_e32 v[72:73], v[8:9]
	v_mov_b64_e32 v[70:71], v[6:7]
	v_mov_b64_e32 v[68:69], v[4:5]
	v_mov_b64_e32 v[66:67], v[2:3]
	s_waitcnt lgkmcnt(0)
	s_barrier
	s_branch .LBB0_4990

; #define LAS __attribute__((address_space(3)))
; #define FA_SBAR() __builtin_amdgcn_sched_barrier(0)
; #define QK_MM(F0, F1, g) do { _Pragma("unroll") for (int e = 0; e < 2; ++e) { const int d0 = 2 * (g) + e; \
;         p0 = __builtin_amdgcn_mfma_f32_32x32x16_f16(F0[e], qr[d0], p0, 0, 0, 0); p1 = __builtin_amdgcn_mfma_f32_32x32x16_f16(F1[e], qr[d0], p1, 0, 0, 0); } } while (0)
; template <bool MLA>
; __device__ __forceinline__ void qkt2(f32x16& p0, f32x16& p1, const LAS char* lds, int kboff, int kroff, int r32, int hi, const half8* qr) {
;     const LAS char* kb[4];
; #pragma unroll
;     for (int dd = 0; dd < 4; ++dd) kb[dd] = lds + OFF_K + kboff + FA_KSWZ(r32, (dd * 16 + hi * 8) * 2);
;     constexpr int NG = MLA ? 6 : 4;
;     half8 fa0[2], fa1[2], fb0[2], fb1[2];
;     ...
; #pragma unroll
;     for (int r = 0; r < 16; ++r) { p0[r] = 0.f; p1[r] = 0.f; }
;     QK_LD(fa0, fa1, 0); FA_SBAR();
;     QK_LD(fb0, fb1, 1); FA_SBAR(); QK_MM(fa0, fa1, 0); FA_SBAR();
;     QK_LD(fa0, fa1, 2); FA_SBAR(); QK_MM(fb0, fb1, 1); FA_SBAR();
;     QK_LD(fb0, fb1, 3); FA_SBAR(); QK_MM(fa0, fa1, 2); FA_SBAR();
;     if constexpr (NG == 6) {
;         QK_LD(fa0, fa1, 4); FA_SBAR(); QK_MM(fb0, fb1, 3); FA_SBAR();
;         QK_LD(fb0, fb1, 5); FA_SBAR(); QK_MM(fa0, fa1, 4); FA_SBAR();
;         QK_MM(fb0, fb1, 5);
;     } else QK_MM(fb0, fb1, 3);
;     ...
; }
.LBB0_4992:
	s_sub_i32 s10, s22, 63
	s_and_b32 s11, s25, 1
	v_mov_b32_e32 v2, s11
	s_cmp_gt_i32 s10, s24
	s_cbranch_scc1 .LBB0_5000
	v_lshlrev_b32_e32 v2, 14, v2
	v_add_u32_e32 v4, v182, v2
	v_add_u32_e32 v16, v4, v183
	v_add_u32_e32 v17, v4, v184
	v_add_u32_e32 v191, v4, v185
	v_add_u32_e32 v196, v4, v186
	ds_read_b128 v[4:7], v16 offset:32768
	ds_read_b128 v[8:11], v16 offset:40960
	ds_read_b128 v[12:15], v17 offset:32768
	ds_read_b128 v[192:195], v17 offset:40960
	ds_read_b128 v[204:207], v191 offset:32768
	ds_read_b128 v[220:223], v191 offset:40960
	ds_read_b128 v[224:227], v196 offset:32768
	ds_read_b128 v[228:231], v196 offset:40960
	s_waitcnt lgkmcnt(7)
	v_mfma_f32_32x32x16_f16 v[98:113], v[4:7], v[134:137], 0
	s_waitcnt lgkmcnt(6)
	v_mfma_f32_32x32x16_f16 v[82:97], v[8:11], v[134:137], 0
	s_waitcnt lgkmcnt(5)
	v_mfma_f32_32x32x16_f16 v[98:113], v[12:15], v[138:141], v[98:113]
	s_waitcnt lgkmcnt(4)
	v_mfma_f32_32x32x16_f16 v[82:97], v[192:195], v[138:141], v[82:97]
	v_xor_b32_e32 v16, 0x80, v16
	ds_read_b128 v[4:7], v16 offset:32768
	ds_read_b128 v[8:11], v16 offset:40960
	v_xor_b32_e32 v17, 0x80, v17
	ds_read_b128 v[12:15], v17 offset:32768
	ds_read_b128 v[192:195], v17 offset:40960
	s_waitcnt lgkmcnt(7)
	v_mfma_f32_32x32x16_f16 v[98:113], v[204:207], v[142:145], v[98:113]
	s_waitcnt lgkmcnt(6)
	v_mfma_f32_32x32x16_f16 v[82:97], v[220:223], v[142:145], v[82:97]
	s_waitcnt lgkmcnt(5)
	v_mfma_f32_32x32x16_f16 v[98:113], v[224:227], v[146:149], v[98:113]
	s_waitcnt lgkmcnt(4)
	v_mfma_f32_32x32x16_f16 v[82:97], v[228:231], v[146:149], v[82:97]
	v_xor_b32_e32 v191, 0x80, v191
	ds_read_b128 v[204:207], v191 offset:32768
	ds_read_b128 v[220:223], v191 offset:40960
	v_xor_b32_e32 v196, 0x80, v196
	ds_read_b128 v[224:227], v196 offset:32768
	ds_read_b128 v[228:231], v196 offset:40960
	s_waitcnt lgkmcnt(7)
	v_mfma_f32_32x32x16_f16 v[98:113], v[4:7], v[150:153], v[98:113]
	s_waitcnt lgkmcnt(6)
	v_mfma_f32_32x32x16_f16 v[82:97], v[8:11], v[150:153], v[82:97]
	s_waitcnt lgkmcnt(5)
	v_mfma_f32_32x32x16_f16 v[98:113], v[12:15], v[154:157], v[98:113]
	s_waitcnt lgkmcnt(4)
	v_mfma_f32_32x32x16_f16 v[82:97], v[192:195], v[154:157], v[82:97]
	s_waitcnt lgkmcnt(3)
	v_mfma_f32_32x32x16_f16 v[98:113], v[204:207], v[158:161], v[98:113]
	s_cmp_lt_u32 s25, 32
	s_cselect_b64 vcc, -1, 0
	s_cmp_lt_u32 s25, 64
	s_cselect_b64 s[38:39], -1, 0
	s_cmpk_lt_u32 s25, 0x60
	s_cselect_b64 s[40:41], -1, 0
	v_cndmask_b32_e64 v4, v133, v132, s[40:41]
	s_waitcnt lgkmcnt(2)
	v_mfma_f32_32x32x16_f16 v[82:97], v[220:223], v[158:161], v[82:97]
	v_cndmask_b32_e64 v4, v4, v131, s[38:39]
	v_cndmask_b32_e32 v4, v4, v130, vcc
	s_and_b32 s10, s25, 31
	v_bfe_u32 v4, v4, s10, 1
	v_cmp_eq_u32_e32 vcc, 0, v4
	s_cmp_le_i32 s22, s23
	s_waitcnt lgkmcnt(1)
	v_mfma_f32_32x32x16_f16 v[98:113], v[224:227], v[162:165], v[98:113]
	s_waitcnt lgkmcnt(0)
	v_mfma_f32_32x32x16_f16 v[82:97], v[228:231], v[162:165], v[82:97]
	s_nop 9
	v_cndmask_b32_e32 v193, v98, v218, vcc
	v_cndmask_b32_e32 v204, v99, v218, vcc
	v_cndmask_b32_e32 v191, v100, v218, vcc
	v_cndmask_b32_e32 v192, v101, v218, vcc
	v_cndmask_b32_e32 v101, v102, v218, vcc
	v_cndmask_b32_e32 v102, v103, v218, vcc
	v_cndmask_b32_e32 v99, v104, v218, vcc
	v_cndmask_b32_e32 v82, v82, v218, vcc
	v_cndmask_b32_e32 v83, v83, v218, vcc
	v_cndmask_b32_e32 v16, v84, v218, vcc
	v_cndmask_b32_e32 v17, v85, v218, vcc
	v_cndmask_b32_e32 v14, v86, v218, vcc
	v_cndmask_b32_e32 v15, v87, v218, vcc
	v_cndmask_b32_e32 v12, v88, v218, vcc
	v_cndmask_b32_e32 v100, v105, v218, vcc
	v_cndmask_b32_e32 v13, v89, v218, vcc
	v_cndmask_b32_e32 v98, v106, v218, vcc
	v_cndmask_b32_e32 v10, v90, v218, vcc
	v_cndmask_b32_e32 v90, v107, v218, vcc
	v_cndmask_b32_e32 v11, v91, v218, vcc
	v_cndmask_b32_e32 v88, v108, v218, vcc
	v_cndmask_b32_e32 v8, v92, v218, vcc
	v_cndmask_b32_e32 v89, v109, v218, vcc
	v_cndmask_b32_e32 v9, v93, v218, vcc
	v_cndmask_b32_e32 v86, v110, v218, vcc
	v_cndmask_b32_e32 v6, v94, v218, vcc
	v_cndmask_b32_e32 v87, v111, v218, vcc
	v_cndmask_b32_e32 v7, v95, v218, vcc
	v_cndmask_b32_e32 v84, v112, v218, vcc
	v_cndmask_b32_e32 v4, v96, v218, vcc
	v_cndmask_b32_e32 v85, v113, v218, vcc
	v_cndmask_b32_e32 v5, v97, v218, vcc
	s_cbranch_scc1 .LBB0_4995
; __device__ __forceinline__ void mask_tile(f32x16& p0, f32x16& p1, int dq, unsigned W) {
;     const float NEG = -__builtin_inff();
; #pragma unroll
;     for (int r = 0; r < 16; ++r) { const int c = (r & 3) + 8 * (r >> 2);
;         if ((unsigned)(dq - c) >= W) p0[r] = NEG;
;         if ((unsigned)(dq - c - 32) >= W) p1[r] = NEG; }
; }
	v_add_u32_e32 v91, 59, v188
	v_cmp_gt_u32_e32 vcc, 2.0, v91
	v_add_u32_e32 v91, 27, v188
	s_nop 0
	v_cndmask_b32_e32 v193, v218, v193, vcc
	v_cmp_gt_u32_e32 vcc, 2.0, v91
	v_add_u32_e32 v91, 58, v188
	s_nop 0
	v_cndmask_b32_e32 v82, v218, v82, vcc
	v_cmp_gt_u32_e32 vcc, 2.0, v91
	v_add_u32_e32 v91, 26, v188
	s_nop 0
	v_cndmask_b32_e32 v204, v218, v204, vcc
	v_cmp_gt_u32_e32 vcc, 2.0, v91
	v_add_u32_e32 v91, 57, v188
	s_nop 0
	v_cndmask_b32_e32 v83, v218, v83, vcc
	v_cmp_gt_u32_e32 vcc, 2.0, v91
	v_add_u32_e32 v91, 25, v188
	s_nop 0
	v_cndmask_b32_e32 v191, v218, v191, vcc
	v_cmp_gt_u32_e32 vcc, 2.0, v91
	v_add_u32_e32 v91, 56, v188
	s_nop 0
	v_cndmask_b32_e32 v16, v218, v16, vcc
	v_cmp_gt_u32_e32 vcc, 2.0, v91
	v_add_u32_e32 v91, 24, v188
	s_nop 0
	v_cndmask_b32_e32 v192, v218, v192, vcc
	v_cmp_gt_u32_e32 vcc, 2.0, v91
	v_add_u32_e32 v91, 51, v188
	s_nop 0
	v_cndmask_b32_e32 v17, v218, v17, vcc
	v_cmp_gt_u32_e32 vcc, 2.0, v91
	v_add_u32_e32 v91, 19, v188
	s_nop 0
	v_cndmask_b32_e32 v101, v218, v101, vcc
	v_cmp_gt_u32_e32 vcc, 2.0, v91
	v_add_u32_e32 v91, 50, v188
	s_nop 0
	v_cndmask_b32_e32 v14, v218, v14, vcc
	v_cmp_gt_u32_e32 vcc, 2.0, v91
	v_add_u32_e32 v91, 18, v188
	s_nop 0
	v_cndmask_b32_e32 v102, v218, v102, vcc
	v_cmp_gt_u32_e32 vcc, 2.0, v91
	v_add_u32_e32 v91, 49, v188
	s_nop 0
	v_cndmask_b32_e32 v15, v218, v15, vcc
	v_cmp_gt_u32_e32 vcc, 2.0, v91
	v_add_u32_e32 v91, 17, v188
	s_nop 0
	v_cndmask_b32_e32 v99, v218, v99, vcc
	v_cmp_gt_u32_e32 vcc, 2.0, v91
	v_add_u32_e32 v91, 48, v188
	s_nop 0
	v_cndmask_b32_e32 v12, v218, v12, vcc
	v_cmp_gt_u32_e32 vcc, 2.0, v91
	v_add_u32_e32 v91, 16, v188
	s_nop 0
	v_cndmask_b32_e32 v100, v218, v100, vcc
	v_cmp_gt_u32_e32 vcc, 2.0, v91
	v_add_u32_e32 v91, 43, v188
	s_nop 0
	v_cndmask_b32_e32 v13, v218, v13, vcc
	v_cmp_gt_u32_e32 vcc, 2.0, v91
	v_add_u32_e32 v91, 11, v188
	s_nop 0
	v_cndmask_b32_e32 v98, v218, v98, vcc
	v_cmp_gt_u32_e32 vcc, 2.0, v91
	v_add_u32_e32 v91, 42, v188
	s_nop 0
	v_cndmask_b32_e32 v10, v218, v10, vcc
	v_cmp_gt_u32_e32 vcc, 2.0, v91
	v_add_u32_e32 v91, 10, v188
	s_nop 0
	v_cndmask_b32_e32 v90, v218, v90, vcc
	v_cmp_gt_u32_e32 vcc, 2.0, v91
	v_add_u32_e32 v91, 41, v188
	s_nop 0
	v_cndmask_b32_e32 v11, v218, v11, vcc
	v_cmp_gt_u32_e32 vcc, 2.0, v91
	v_add_u32_e32 v91, 9, v188
	s_nop 0
	v_cndmask_b32_e32 v88, v218, v88, vcc
	v_cmp_gt_u32_e32 vcc, 2.0, v91
	v_add_u32_e32 v91, 40, v188
	s_nop 0
	v_cndmask_b32_e32 v8, v218, v8, vcc
	v_cmp_gt_u32_e32 vcc, 2.0, v91
	v_add_u32_e32 v91, 8, v188
	s_nop 0
	v_cndmask_b32_e32 v89, v218, v89, vcc
	v_cmp_gt_u32_e32 vcc, 2.0, v91
	v_add_u32_e32 v91, 35, v188
	s_nop 0
	v_cndmask_b32_e32 v9, v218, v9, vcc
	v_cmp_gt_u32_e32 vcc, 2.0, v91
	v_add_u32_e32 v91, 3, v188
	s_nop 0
	v_cndmask_b32_e32 v86, v218, v86, vcc
	v_cmp_gt_u32_e32 vcc, 2.0, v91
	v_add_u32_e32 v91, 34, v188
	s_nop 0
	v_cndmask_b32_e32 v6, v218, v6, vcc
	v_cmp_gt_u32_e32 vcc, 2.0, v91
	v_add_u32_e32 v91, 2, v188
	s_nop 0
	v_cndmask_b32_e32 v87, v218, v87, vcc
	v_cmp_gt_u32_e32 vcc, 2.0, v91
	v_add_u32_e32 v91, 33, v188
	s_nop 0
	v_cndmask_b32_e32 v7, v218, v7, vcc
	v_cmp_gt_u32_e32 vcc, 2.0, v91
	v_add_u32_e32 v91, 1, v188
	s_nop 0
	v_cndmask_b32_e32 v84, v218, v84, vcc
	v_cmp_gt_u32_e32 vcc, 2.0, v91
	v_add_u32_e32 v91, 32, v188
	s_nop 0
	v_cndmask_b32_e32 v4, v218, v4, vcc
	v_cmp_gt_u32_e32 vcc, 2.0, v91
	s_nop 1
	v_cndmask_b32_e32 v85, v218, v85, vcc
	v_cmp_gt_u32_e32 vcc, 2.0, v188
	s_nop 1
	v_cndmask_b32_e32 v5, v218, v5, vcc

; #define LAS __attribute__((address_space(3)))
; #define FA_SBAR() __builtin_amdgcn_sched_barrier(0)
; __device__ __forceinline__ int crow(int r, int hi) { return (r & 3) + 8 * (r >> 2) + 4 * hi; }
; template <int KIND>
; __device__ __forceinline__ void run_unit(LAS char* lds, const UnitArgs& U, int tid_in) {
;     ...
;     float rs = l_reg > 0.f ? 1.0f / l_reg : 0.f;
;     if (U.epi != 0) { const float gl = U.gate[(size_t)rowpos * 32 + U.gidx]; rs *= 1.0f / (1.0f + __expf(-gl));
;         if (U.epi == 1) { const float g0 = U.gate[(size_t)rowpos * 32 + U.gidx - 1]; if (hi == 0) g_l[r32] = 1.0f / (1.0f + __expf(-g0)); } }
;     if (hi == 0) li_l[r32] = rs;
;     asm volatile("s_waitcnt lgkmcnt(0)" ::: "memory");
;     LAS char* stg = lds + wid * 8192;
;     const int wrow = lane >> 4, wch = lane & 15;
;     h16* obase = U.O + (size_t)(wid * 32 + wrow) * U.old + wch * 8;
;     half8 pw[8];
;     if (U.epi == 2) {
; #pragma unroll
;         for (int i = 0; i < 8; ++i) pw[i] = *(const half8*)(obase + (size_t)(4 * i) * U.old);
;     }
;     FA_SBAR();
; #pragma unroll
;     for (int r = 0; r < 16; ++r) { const int row = crow(r, hi); const float rli = li_l[row];
; #pragma unroll
;         for (int d0 = 0; d0 < 4; ++d0) *(LAS h16*)(stg + row * 256 + (d0 * 32 + r32) * 2) = (h16)(o[d0][r] * rli); }
;     asm volatile("s_waitcnt lgkmcnt(0)" ::: "memory");
; #pragma unroll
;     for (int i = 0; i < 8; ++i) { half8 x = *(const LAS half8*)(stg + (4 * i + wrow) * 256 + wch * 16);
;         if (U.epi == 2) {
; #pragma unroll
;             for (int e = 0; e < 8; ++e) x[e] = (h16)((float)x[e] + (float)pw[i][e]); }
;         *(half8*)(obase + (size_t)(4 * i) * U.old) = x; }
.LBB0_5004:
	s_or_b64 exec, exec, s[6:7]
	s_lshl_b64 s[0:1], s[2:3], 12
	s_add_u32 s0, s74, s0
	s_addc_u32 s1, s75, s1
	s_lshl_b32 s6, s14, 8
	s_add_u32 s0, s0, s6
	s_waitcnt vmcnt(1)
	v_lshrrev_b32_e32 v124, 4, v176
	s_addc_u32 s1, s1, 0
	v_or_b32_e32 v4, s17, v124
	s_add_u32 s6, s0, 0x47a31800
	v_ashrrev_i32_e32 v5, 31, v4
	s_addc_u32 s7, s1, 0
	v_lshlrev_b64 v[4:5], 12, v[4:5]
	v_lshl_add_u64 v[4:5], s[6:7], 0, v[4:5]
	v_and_b32_e32 v2, 0xf0, v177
	v_lshl_add_u64 v[114:115], v[4:5], 0, v[2:3]
	v_add_co_u32_e32 v112, vcc, s21, v114
	s_mov_b32 s0, 0x8000
	s_nop 0
	v_addc_co_u32_e32 v113, vcc, 0, v115, vcc
	v_add_co_u32_e32 v110, vcc, s0, v114
	s_mov_b32 s0, 0xc000
	s_nop 0
	v_addc_co_u32_e32 v111, vcc, 0, v115, vcc
	v_add_co_u32_e32 v108, vcc, s0, v114
	s_mov_b32 s0, 0x10000
	s_nop 0
	v_addc_co_u32_e32 v109, vcc, 0, v115, vcc
	v_add_co_u32_e32 v106, vcc, s0, v114
	s_mov_b32 s0, 0x14000
	s_nop 0
	v_addc_co_u32_e32 v107, vcc, 0, v115, vcc
	v_add_co_u32_e32 v104, vcc, s0, v114
	s_mov_b32 s0, 0x18000
	s_nop 0
	v_addc_co_u32_e32 v105, vcc, 0, v115, vcc
	v_add_co_u32_e32 v102, vcc, s0, v114
	s_mov_b32 s0, 0x1c000
	s_nop 0
	v_addc_co_u32_e32 v103, vcc, 0, v115, vcc
	s_waitcnt lgkmcnt(0)
	v_add_co_u32_e32 v16, vcc, s0, v114
	global_load_dwordx4 v[98:101], v[114:115], off
	global_load_dwordx4 v[94:97], v[112:113], off
	global_load_dwordx4 v[90:93], v[110:111], off
	global_load_dwordx4 v[86:89], v[108:109], off
	global_load_dwordx4 v[82:85], v[106:107], off
	global_load_dwordx4 v[12:15], v[104:105], off
	v_addc_co_u32_e32 v17, vcc, 0, v115, vcc
	global_load_dwordx4 v[8:11], v[102:103], off
	global_load_dwordx4 v[4:7], v[16:17], off
	s_lshl_b32 s0, s16, 13
	s_add_i32 s0, s0, 0
	ds_read_b128 v[116:119], v1
	ds_read_b128 v[120:123], v1 offset:32
	v_lshl_add_u32 v125, v174, 1, s0
	s_waitcnt vmcnt(8)
	v_lshl_add_u32 v126, v167, 10, v125
	v_mov_b32_e32 v167, v0
	s_waitcnt lgkmcnt(1)
	v_fma_mixlo_f16 v66, v66, v116, 0
	v_fma_mixlo_f16 v34, v34, v116, 0
	v_fma_mixlo_f16 v18, v18, v116, 0
	v_fma_mixlo_f16 v50, v50, v116, 0
	ds_write_b16 v126, v66
	ds_write_b16 v126, v50 offset:64
	ds_write_b16 v126, v34 offset:128
	ds_write_b16 v126, v18 offset:192
	v_fma_mixlo_f16 v18, v67, v117, 0
	v_lshl_add_u32 v34, v175, 8, v125
	ds_write_b16 v34, v18 offset:256
	v_fma_mixlo_f16 v18, v51, v117, 0
	ds_write_b16 v34, v18 offset:320
	v_fma_mixlo_f16 v18, v35, v117, 0
	ds_write_b16 v34, v18 offset:384
	v_fma_mixlo_f16 v18, v19, v117, 0
	ds_write_b16 v34, v18 offset:448
	v_fma_mixlo_f16 v18, v68, v118, 0
	ds_write_b16 v34, v18 offset:512
	v_fma_mixlo_f16 v18, v52, v118, 0
	ds_write_b16 v34, v18 offset:576
	v_fma_mixlo_f16 v18, v36, v118, 0
	ds_write_b16 v34, v18 offset:640
	v_fma_mixlo_f16 v18, v20, v118, 0
	ds_write_b16 v34, v18 offset:704
	v_fma_mixlo_f16 v18, v69, v119, 0
	ds_write_b16 v34, v18 offset:768
	v_fma_mixlo_f16 v18, v53, v119, 0
	ds_write_b16 v34, v18 offset:832
	v_fma_mixlo_f16 v18, v37, v119, 0
	ds_write_b16 v34, v18 offset:896
	v_fma_mixlo_f16 v18, v21, v119, 0
	ds_write_b16 v34, v18 offset:960
	s_waitcnt lgkmcnt(14)
	v_fma_mixlo_f16 v18, v70, v120, 0
	ds_write_b16 v34, v18 offset:2048
	v_fma_mixlo_f16 v18, v54, v120, 0
	ds_write_b16 v34, v18 offset:2112
	v_fma_mixlo_f16 v18, v38, v120, 0
	ds_write_b16 v34, v18 offset:2176
	v_fma_mixlo_f16 v18, v22, v120, 0
	ds_write_b16 v34, v18 offset:2240
	v_fma_mixlo_f16 v18, v71, v121, 0
	ds_write_b16 v34, v18 offset:2304
	v_fma_mixlo_f16 v18, v55, v121, 0
	ds_write_b16 v34, v18 offset:2368
	v_fma_mixlo_f16 v18, v39, v121, 0
	ds_write_b16 v34, v18 offset:2432
	v_fma_mixlo_f16 v18, v23, v121, 0
	ds_write_b16 v34, v18 offset:2496
	v_fma_mixlo_f16 v18, v72, v122, 0
	ds_write_b16 v34, v18 offset:2560
	v_fma_mixlo_f16 v18, v56, v122, 0
	ds_write_b16 v34, v18 offset:2624
	v_fma_mixlo_f16 v18, v40, v122, 0
	ds_write_b16 v34, v18 offset:2688
	v_fma_mixlo_f16 v18, v24, v122, 0
	ds_write_b16 v34, v18 offset:2752
	v_fma_mixlo_f16 v18, v73, v123, 0
	ds_write_b16 v34, v18 offset:2816
	v_fma_mixlo_f16 v18, v57, v123, 0
	ds_write_b16 v34, v18 offset:2880
	ds_read_b128 v[18:21], v1 offset:64
	v_fma_mixlo_f16 v22, v41, v123, 0
	ds_write_b16 v34, v22 offset:2944
	v_fma_mixlo_f16 v22, v25, v123, 0
	ds_write_b16 v34, v22 offset:3008
	ds_read_b128 v[22:25], v1 offset:96
	s_waitcnt lgkmcnt(3)
	v_fma_mixlo_f16 v1, v74, v18, 0
	ds_write_b16 v34, v1 offset:4096
	v_fma_mixlo_f16 v1, v58, v18, 0
	ds_write_b16 v34, v1 offset:4160
	v_fma_mixlo_f16 v1, v42, v18, 0
	ds_write_b16 v34, v1 offset:4224
	v_fma_mixlo_f16 v1, v26, v18, 0
	ds_write_b16 v34, v1 offset:4288
	v_fma_mixlo_f16 v1, v75, v19, 0
	ds_write_b16 v34, v1 offset:4352
	v_fma_mixlo_f16 v1, v59, v19, 0
	ds_write_b16 v34, v1 offset:4416
	v_fma_mixlo_f16 v1, v43, v19, 0
	ds_write_b16 v34, v1 offset:4480
	v_fma_mixlo_f16 v1, v27, v19, 0
	ds_write_b16 v34, v1 offset:4544
	v_fma_mixlo_f16 v1, v76, v20, 0
	ds_write_b16 v34, v1 offset:4608
	v_fma_mixlo_f16 v1, v60, v20, 0
	ds_write_b16 v34, v1 offset:4672
	v_fma_mixlo_f16 v1, v44, v20, 0
	ds_write_b16 v34, v1 offset:4736
	v_fma_mixlo_f16 v1, v28, v20, 0
	ds_write_b16 v34, v1 offset:4800
	v_fma_mixlo_f16 v1, v77, v21, 0
	ds_write_b16 v34, v1 offset:4864
	v_fma_mixlo_f16 v1, v61, v21, 0
	ds_write_b16 v34, v1 offset:4928
	v_fma_mixlo_f16 v1, v45, v21, 0
	ds_write_b16 v34, v1 offset:4992
	v_fma_mixlo_f16 v1, v29, v21, 0
	ds_write_b16 v34, v1 offset:5056
	s_waitcnt lgkmcnt(14)
; #define LAS __attribute__((address_space(3)))
; __device__ __forceinline__ int crow(int r, int hi) { return (r & 3) + 8 * (r >> 2) + 4 * hi; }
; template <int KIND>
; __device__ __forceinline__ void run_unit(LAS char* lds, const UnitArgs& U, int tid_in) {
;     ...
;     for (int r = 0; r < 16; ++r) { const int row = crow(r, hi); const float rli = li_l[row];
; #pragma unroll
;         for (int d0 = 0; d0 < 4; ++d0) *(LAS h16*)(stg + row * 256 + (d0 * 32 + r32) * 2) = (h16)(o[d0][r] * rli); }
;     asm volatile("s_waitcnt lgkmcnt(0)" ::: "memory");
; #pragma unroll
;     for (int i = 0; i < 8; ++i) { half8 x = *(const LAS half8*)(stg + (4 * i + wrow) * 256 + wch * 16);
;         if (U.epi == 2) {
; #pragma unroll
;             for (int e = 0; e < 8; ++e) x[e] = (h16)((float)x[e] + (float)pw[i][e]); }
;         *(half8*)(obase + (size_t)(4 * i) * U.old) = x; }
;     __syncthreads();
; __device__ __forceinline__ void fa_mixer_phase(Frame& F, int l) {
;     ...
;             U.K = (const h16*)(ws + WS_KWIN); U.V = (const h16*)(ws + WS_VWIN); U.j_lo = P0 >= 511 ? (P0 - 511) / 64 : 0; U.gidx = h * 3 + 2; U.epi = 2;
	v_fma_mixlo_f16 v1, v78, v22, 0
	ds_write_b16 v34, v1 offset:6144
	v_fma_mixlo_f16 v1, v62, v22, 0
	ds_write_b16 v34, v1 offset:6208
	v_fma_mixlo_f16 v1, v46, v22, 0
	ds_write_b16 v34, v1 offset:6272
	v_fma_mixlo_f16 v1, v30, v22, 0
	ds_write_b16 v34, v1 offset:6336
	v_fma_mixlo_f16 v1, v79, v23, 0
	ds_write_b16 v34, v1 offset:6400
	v_fma_mixlo_f16 v1, v63, v23, 0
	ds_write_b16 v34, v1 offset:6464
	v_fma_mixlo_f16 v1, v47, v23, 0
	ds_write_b16 v34, v1 offset:6528
	v_fma_mixlo_f16 v1, v31, v23, 0
	ds_write_b16 v34, v1 offset:6592
	v_fma_mixlo_f16 v1, v80, v24, 0
	ds_write_b16 v34, v1 offset:6656
	v_fma_mixlo_f16 v1, v64, v24, 0
	ds_write_b16 v34, v1 offset:6720
	v_fma_mixlo_f16 v1, v48, v24, 0
	ds_write_b16 v34, v1 offset:6784
	v_fma_mixlo_f16 v1, v32, v24, 0
	ds_write_b16 v34, v1 offset:6848
	v_fma_mixlo_f16 v1, v81, v25, 0
	ds_write_b16 v34, v1 offset:6912
	v_fma_mixlo_f16 v1, v65, v25, 0
	ds_write_b16 v34, v1 offset:6976
	v_fma_mixlo_f16 v1, v49, v25, 0
	ds_write_b16 v34, v1 offset:7040
	v_fma_mixlo_f16 v1, v33, v25, 0
	ds_write_b16 v34, v1 offset:7104
	v_lshlrev_b32_e32 v1, 8, v124
	s_waitcnt lgkmcnt(0)
	v_add3_u32 v1, s0, v2, v1
	ds_read_b128 v[18:21], v1
	ds_read_b128 v[22:25], v1 offset:1024
	s_sub_i32 s0, 0x1d00, s12
	s_lshr_b32 s0, s0, 6
	s_cmpk_gt_i32 s2, 0x1fe
	s_waitcnt vmcnt(7) lgkmcnt(1)
	v_pk_add_f16 v21, v101, v21
	v_pk_add_f16 v20, v100, v20
	v_pk_add_f16 v19, v99, v19
	v_pk_add_f16 v18, v98, v18
	global_store_dwordx4 v[114:115], v[18:21], off
	s_cselect_b32 s0, s0, 0
	s_lshl_b32 s22, s0, 6
	s_waitcnt vmcnt(7) lgkmcnt(0)
	v_pk_add_f16 v21, v97, v25
	v_pk_add_f16 v20, v96, v24
	v_pk_add_f16 v19, v95, v23
	v_pk_add_f16 v18, v94, v22
	ds_read_b128 v[24:27], v1 offset:2048
	global_store_dwordx4 v[112:113], v[18:21], off
	ds_read_b128 v[18:21], v1 offset:3072
	v_readlane_b32 s10, v254, 4
	v_readlane_b32 s11, v254, 5
	s_waitcnt vmcnt(7) lgkmcnt(1)
	v_pk_add_f16 v27, v93, v27
	v_pk_add_f16 v26, v92, v26
	v_pk_add_f16 v25, v91, v25
	v_pk_add_f16 v24, v90, v24
	s_waitcnt vmcnt(6) lgkmcnt(0)
	v_pk_add_f16 v21, v89, v21
	v_pk_add_f16 v20, v88, v20
	v_pk_add_f16 v19, v87, v19
	v_pk_add_f16 v18, v86, v18
	global_store_dwordx4 v[110:111], v[24:27], off
	ds_read_b128 v[22:25], v1 offset:4096
	global_store_dwordx4 v[108:109], v[18:21], off
	ds_read_b128 v[18:21], v1 offset:5120
	s_sub_i32 s23, s13, s0
	s_waitcnt vmcnt(7) lgkmcnt(1)
	v_pk_add_f16 v25, v85, v25
	v_pk_add_f16 v24, v84, v24
	v_pk_add_f16 v23, v83, v23
	v_pk_add_f16 v22, v82, v22
	s_waitcnt vmcnt(6) lgkmcnt(0)
	v_pk_add_f16 v15, v15, v21
	v_pk_add_f16 v14, v14, v20
	v_pk_add_f16 v13, v13, v19
	v_pk_add_f16 v12, v12, v18
	global_store_dwordx4 v[106:107], v[22:25], off
	ds_read_b128 v[20:23], v1 offset:6144
	global_store_dwordx4 v[104:105], v[12:15], off
	ds_read_b128 v[12:15], v1 offset:7168
	s_waitcnt vmcnt(7) lgkmcnt(1)
	v_pk_add_f16 v11, v11, v23
	v_pk_add_f16 v10, v10, v22
	v_pk_add_f16 v9, v9, v21
	v_pk_add_f16 v8, v8, v20
	s_waitcnt vmcnt(6) lgkmcnt(0)
	v_pk_add_f16 v7, v7, v15
	v_pk_add_f16 v6, v6, v14
	v_pk_add_f16 v5, v5, v13
	v_pk_add_f16 v4, v4, v12
	global_store_dwordx4 v[102:103], v[8:11], off
	global_store_dwordx4 v[16:17], v[4:7], off
	s_barrier
; #define LAS __attribute__((address_space(3)))
; __device__ __forceinline__ int v_st(int k, int c) { const int kk = (k & ~0xC) | ((k & 4) << 1) | ((k & 8) >> 1); return ((kk >> 3) * 4 + (c >> 5)) * 512 + ((kk & 7) * 32 + (c & 31)) * 2; }
; __device__ __forceinline__ int v_rd_base(int lane) { return ((lane & 3) << 3) | (((lane >> 2) & 3) << 6) | (((lane >> 4) & 1) << 5) | (((lane >> 5) & 1) << 8); }
; template <int KIND>
; __device__ __forceinline__ void run_unit(LAS char* lds, const UnitArgs& U, int tid_in) {
;     ...
;     const int wid = __builtin_amdgcn_readfirstlane(tid >> 6), lane = tid & 63, r32 = lane & 31, hi = lane >> 5;
;     const int sr = tid >> 4, sc = (tid & 15) * 8;
;     const int qlo = U.P0 + wid * 32, rowpos = qlo + r32;
;     const float sc_ = MLA ? SC192 : SC128; const float C2 = 1.4426950408889634f * sc_;
;     LAS float* wsf = (LAS float*)(lds + OFF_WS) + wid * 96; LAS float* li_l = wsf; LAS float* al_l = wsf + 32; LAS float* g_l = wsf + 64;
;     half8 qr[MLA ? 12 : 8];
;     { const h16* qp = U.Q + (size_t)(wid * 32 + r32) * U.qld + hi * 8;
; #pragma unroll
;       for (int d0 = 0; d0 < (MLA ? 12 : 8); ++d0) qr[d0] = *(const half8*)(qp + d0 * 16); }
;     unsigned mb0 = 0, mb1 = 0, mb2 = 0, mb3 = 0;
;     if constexpr (KIND == K_MOBA) { const int* s = (const int*)U.mk + (size_t)rowpos * 16;
; #pragma unroll
;         for (int i = 0; i < 3; ++i) { const int b = s[i]; if (b >= 0) mb0 |= 1u << b; } }
;     if constexpr (KIND == K_SLC) { const u32x4 m = *(const u32x4*)((const unsigned*)U.mk + (size_t)rowpos * 4); mb0 = m[0]; mb1 = m[1]; mb2 = m[2]; mb3 = m[3]; }
;     const int nvis_row = rowpos >= 31 ? ((rowpos - 31) >> 4) + 1 : 0;
;     const int NT = U.j_hi - U.j_lo;
;     half8 st_k0, st_k1, st_v0, st_v1, st_kr; unsigned dm_lo = 0, dm_hi = 0, dn_lo = 0, dn_hi = 0;
;     const int kws = FA_KSWZ(sr, sc * 2), vst0 = v_st(sr, sc), vst1 = v_st(32 + sr, sc), krw = FA_KRSWZ(tid >> 3, (tid & 7) * 16);
;     const int vb0 = (int)(unsigned)(size_t)(lds + OFF_V) + v_rd_base(lane);
;     ...
;     float m_reg = -1e30f, l_reg = 0.f; f32x16 o[4];
; #pragma unroll
;     for (int d = 0; d < 4; ++d)
; #pragma unroll
;         for (int r = 0; r < 16; ++r) o[d][r] = 0.f;
;     FA_LOADT(U.j_lo); asm volatile("s_waitcnt vmcnt(0)" ::: "memory"); FA_WRITET(0); dm_lo = dn_lo; dm_hi = dn_hi;
;     __syncthreads();
	s_nop 0
	v_readfirstlane_b32 s1, v167
	s_ashr_i32 s14, s1, 6
	v_and_b32_e32 v166, 31, v167
	s_lshl_b32 s16, s14, 5
	v_or_b32_e32 v4, s16, v166
	v_ashrrev_i32_e32 v5, 31, v4
	v_bfe_u32 v1, v167, 5, 1
	v_lshlrev_b64 v[4:5], 8, v[4:5]
	v_lshl_add_u64 v[6:7], s[8:9], 0, v[4:5]
	v_lshlrev_b32_e32 v4, 4, v1
	v_mov_b32_e32 v5, v3
	v_ashrrev_i32_e32 v170, 4, v167
	v_lshl_add_u64 v[6:7], v[6:7], 0, v[4:5]
	v_add_u32_e32 v5, 32, v170
	v_add_u32_e32 v8, s22, v170
	v_lshlrev_b32_e32 v16, 3, v167
	v_ashrrev_i32_e32 v9, 31, v8
	v_add_u32_e32 v12, s22, v5
	v_and_b32_e32 v2, 0x78, v16
	v_lshlrev_b64 v[8:9], 8, v[8:9]
	v_ashrrev_i32_e32 v13, 31, v12
	v_lshlrev_b32_e32 v2, 1, v2
	v_lshl_add_u64 v[10:11], s[10:11], 0, v[8:9]
	v_lshlrev_b64 v[12:13], 8, v[12:13]
	v_lshl_add_u64 v[10:11], v[10:11], 0, v[2:3]
	v_lshl_add_u64 v[14:15], s[10:11], 0, v[12:13]
	v_lshl_add_u64 v[14:15], v[14:15], 0, v[2:3]
	global_load_dwordx4 v[134:137], v[10:11], off
	global_load_dwordx4 v[146:149], v[14:15], off
	v_readlane_b32 s8, v251, 52
	v_readlane_b32 s9, v251, 53
	s_mul_i32 s1, s14, 0x180
	s_add_i32 s17, s1, 0
	v_lshl_add_u64 v[8:9], s[8:9], 0, v[8:9]
	v_lshl_add_u64 v[8:9], v[8:9], 0, v[2:3]
	v_lshl_add_u64 v[10:11], s[8:9], 0, v[12:13]
	v_lshl_add_u64 v[10:11], v[10:11], 0, v[2:3]
	global_load_dwordx4 v[154:157], v[8:9], off
	global_load_dwordx4 v[158:161], v[10:11], off
	global_load_dwordx4 v[114:117], v[6:7], off
	global_load_dwordx4 v[118:121], v[6:7], off offset:32
	global_load_dwordx4 v[122:125], v[6:7], off offset:64
	global_load_dwordx4 v[126:129], v[6:7], off offset:96
	global_load_dwordx4 v[130:133], v[6:7], off offset:128
	global_load_dwordx4 v[138:141], v[6:7], off offset:160
	global_load_dwordx4 v[142:145], v[6:7], off offset:192
	global_load_dwordx4 v[150:153], v[6:7], off offset:224
	v_and_b32_e32 v7, 0xfffff0, v170
	v_lshlrev_b32_e32 v8, 1, v170
	v_and_or_b32 v7, v8, 8, v7
	v_lshrrev_b32_e32 v8, 1, v170
	v_and_b32_e32 v10, 3, v170
	v_and_or_b32 v8, v8, 4, v10
	v_and_b32_e32 v10, 0xfffff0, v5
	v_lshlrev_b32_e32 v5, 1, v5
	v_lshrrev_b32_e32 v7, 1, v7
	v_bfe_u32 v9, v16, 5, 2
	v_and_or_b32 v5, v5, 8, v10
	v_or_b32_e32 v7, v7, v9
	v_lshrrev_b32_e32 v5, 1, v5
	v_lshlrev_b32_e32 v7, 9, v7
	v_lshlrev_b32_e32 v8, 6, v8
	v_or_b32_e32 v5, v5, v9
	v_and_b32_e32 v10, 48, v2
	v_bitop3_b32 v6, v2, v167, s50 bitop3:0x78
	v_lshlrev_b32_e32 v5, 9, v5
	v_lshlrev_b32_e32 v9, 8, v170
	v_or3_b32 v171, v7, v8, v10
	s_waitcnt vmcnt(0)
	v_and_b32_e32 v168, 63, v167
	s_add_i32 s2, s16, s2
	s_add_i32 s17, s17, 0x14000
	v_or3_b32 v172, v5, v8, v10
	v_add3_u32 v173, 0, v6, v9
	v_add_u32_e32 v5, 0, v171
	s_waitcnt vmcnt(11)
	ds_write_b128 v173, v[134:137] offset:32768
	s_waitcnt vmcnt(10)
	ds_write_b128 v173, v[146:149] offset:40960
	s_waitcnt vmcnt(9)
	ds_write_b128 v5, v[154:157]
	v_add_u32_e32 v5, 0, v172
	s_cmp_lt_i32 s23, 1
	v_cmp_gt_u32_e64 s[0:1], 32, v168
	v_lshl_add_u32 v169, v166, 2, s17
	s_waitcnt vmcnt(8)
	ds_write_b128 v5, v[158:161]
	s_waitcnt lgkmcnt(0)
	s_barrier
	s_cbranch_scc1 .LBB0_5020
	v_lshlrev_b32_e32 v5, 1, v168
	v_and_b32_e32 v5, 32, v5
	v_lshlrev_b32_e32 v6, 4, v168
	v_lshlrev_b32_e32 v7, 3, v168
	v_lshl_add_u64 v[164:165], s[8:9], 0, v[2:3]
	s_movk_i32 s8, 0x118
	v_and_b32_e32 v6, 0xc0, v6
	v_lshlrev_b32_e32 v8, 4, v166
	v_lshl_add_u64 v[162:163], s[10:11], 0, v[2:3]
	v_and_or_b32 v2, v7, s8, v5
	s_add_i32 s8, s16, 0x1ec5
	v_and_b32_e32 v9, 0xf0, v8
	v_bitop3_b32 v175, v4, v8, s50 bitop3:0x78
	v_lshlrev_b32_e32 v8, 2, v1
	v_add3_u32 v180, v6, 0, v2
	v_add_u32_e32 v2, s8, v166
	v_sub_u32_e32 v2, v2, v8
	v_subrev_u32_e32 v2, s22, v2
	v_mov_b32_e32 v16, v3
	v_mov_b32_e32 v17, v3
	v_bitop3_b32 v176, v4, v9, 32 bitop3:0x36
	v_bitop3_b32 v177, v4, v9, 64 bitop3:0x36
	v_bitop3_b32 v178, v4, v9, s77 bitop3:0x36
	v_add_u32_e32 v179, s17, v4
	v_subrev_u32_e32 v181, s12, v2
	v_mov_b32_e32 v2, v3
	v_mov_b32_e32 v4, v3
	v_mov_b32_e32 v5, v3
	v_mov_b32_e32 v6, v3
	v_mov_b32_e32 v7, v3
	v_mov_b32_e32 v8, v3
	v_mov_b32_e32 v9, v3
	v_mov_b32_e32 v10, v3
	v_mov_b32_e32 v11, v3
	v_mov_b32_e32 v12, v3
	v_mov_b32_e32 v13, v3
	v_mov_b32_e32 v14, v3
	v_mov_b32_e32 v15, v3
	v_mov_b64_e32 v[32:33], v[16:17]
	v_mov_b64_e32 v[48:49], v[16:17]
	v_mov_b64_e32 v[64:65], v[16:17]
	v_mov_b64_e32 v[80:81], v[16:17]
	s_or_b32 s24, s2, 31
	s_add_i32 s25, s2, 0xfffffe01
	v_lshl_add_u32 v174, v166, 8, 0
	s_add_i32 s37, s2, 0xfffffe1f
	s_mov_b32 s12, 0
	v_mov_b32_e32 v183, 0
	v_mov_b32_e32 v182, 0xf149f2ca
	s_movk_i32 s40, 0x4000
	v_mov_b64_e32 v[30:31], v[14:15]
	v_mov_b64_e32 v[28:29], v[12:13]
	v_mov_b64_e32 v[26:27], v[10:11]
	v_mov_b64_e32 v[24:25], v[8:9]
	v_mov_b64_e32 v[22:23], v[6:7]
	v_mov_b64_e32 v[20:21], v[4:5]
	v_mov_b64_e32 v[18:19], v[2:3]
	v_mov_b64_e32 v[46:47], v[14:15]
	v_mov_b64_e32 v[44:45], v[12:13]
	v_mov_b64_e32 v[42:43], v[10:11]
	v_mov_b64_e32 v[40:41], v[8:9]
	v_mov_b64_e32 v[38:39], v[6:7]
	v_mov_b64_e32 v[36:37], v[4:5]
	v_mov_b64_e32 v[34:35], v[2:3]
	v_mov_b64_e32 v[62:63], v[14:15]
	v_mov_b64_e32 v[60:61], v[12:13]
	v_mov_b64_e32 v[58:59], v[10:11]
	v_mov_b64_e32 v[56:57], v[8:9]
	v_mov_b64_e32 v[54:55], v[6:7]
	v_mov_b64_e32 v[52:53], v[4:5]
	v_mov_b64_e32 v[50:51], v[2:3]
	v_mov_b64_e32 v[78:79], v[14:15]
	v_mov_b64_e32 v[76:77], v[12:13]
	v_mov_b64_e32 v[74:75], v[10:11]
	v_mov_b64_e32 v[72:73], v[8:9]
	v_mov_b64_e32 v[70:71], v[6:7]
	v_mov_b64_e32 v[68:69], v[4:5]
	v_mov_b64_e32 v[66:67], v[2:3]

; #define LAS __attribute__((address_space(3)))
; #define FA_SBAR() __builtin_amdgcn_sched_barrier(0)
; #define QK_MM(F0, F1, g) do { _Pragma("unroll") for (int e = 0; e < 2; ++e) { const int d0 = 2 * (g) + e; \
;         p0 = __builtin_amdgcn_mfma_f32_32x32x16_f16(F0[e], qr[d0], p0, 0, 0, 0); p1 = __builtin_amdgcn_mfma_f32_32x32x16_f16(F1[e], qr[d0], p1, 0, 0, 0); } } while (0)
; template <bool MLA>
; __device__ __forceinline__ void qkt2(f32x16& p0, f32x16& p1, const LAS char* lds, int kboff, int kroff, int r32, int hi, const half8* qr) {
;     const LAS char* kb[4];
; #pragma unroll
;     for (int dd = 0; dd < 4; ++dd) kb[dd] = lds + OFF_K + kboff + FA_KSWZ(r32, (dd * 16 + hi * 8) * 2);
;     constexpr int NG = MLA ? 6 : 4;
;     half8 fa0[2], fa1[2], fb0[2], fb1[2];
;     ...
; #pragma unroll
;     for (int r = 0; r < 16; ++r) { p0[r] = 0.f; p1[r] = 0.f; }
;     QK_LD(fa0, fa1, 0); FA_SBAR();
;     QK_LD(fb0, fb1, 1); FA_SBAR(); QK_MM(fa0, fa1, 0); FA_SBAR();
;     QK_LD(fa0, fa1, 2); FA_SBAR(); QK_MM(fb0, fb1, 1); FA_SBAR();
;     QK_LD(fb0, fb1, 3); FA_SBAR(); QK_MM(fa0, fa1, 2); FA_SBAR();
;     if constexpr (NG == 6) {
;         QK_LD(fa0, fa1, 4); FA_SBAR(); QK_MM(fb0, fb1, 3); FA_SBAR();
;         QK_LD(fb0, fb1, 5); FA_SBAR(); QK_MM(fa0, fa1, 4); FA_SBAR();
;         QK_MM(fb0, fb1, 5);
;     } else QK_MM(fb0, fb1, 3);
;     ...
; }
.LBB0_5008:
	s_and_b32 s12, s12, 1
	s_cmp_le_i32 s22, s24
	v_mov_b32_e32 v2, s12
	s_cselect_b64 s[38:39], -1, 0
	s_add_i32 s12, s22, 63
	s_cmp_ge_i32 s12, s25
	s_cselect_b64 s[48:49], -1, 0
	s_and_b64 s[38:39], s[38:39], s[48:49]
	s_andn2_b64 vcc, exec, s[38:39]
	s_cbranch_vccnz .LBB0_5016
	v_lshlrev_b32_e32 v2, 14, v2
	v_add_u32_e32 v4, v174, v2
	v_add_u32_e32 v16, v4, v175
	v_add_u32_e32 v17, v4, v176
	v_add_u32_e32 v196, v4, v177
	v_add_u32_e32 v197, v4, v178
	ds_read_b128 v[4:7], v16 offset:32768
	ds_read_b128 v[8:11], v16 offset:40960
	ds_read_b128 v[12:15], v17 offset:32768
	ds_read_b128 v[184:187], v17 offset:40960
	ds_read_b128 v[188:191], v196 offset:32768
	ds_read_b128 v[192:195], v196 offset:40960
	ds_read_b128 v[204:207], v197 offset:32768
	ds_read_b128 v[220:223], v197 offset:40960
	s_waitcnt lgkmcnt(7)
	v_mfma_f32_32x32x16_f16 v[98:113], v[4:7], v[114:117], 0
	s_waitcnt lgkmcnt(6)
	v_mfma_f32_32x32x16_f16 v[82:97], v[8:11], v[114:117], 0
	s_waitcnt lgkmcnt(5)
	v_mfma_f32_32x32x16_f16 v[98:113], v[12:15], v[118:121], v[98:113]
	s_waitcnt lgkmcnt(4)
	v_mfma_f32_32x32x16_f16 v[82:97], v[184:187], v[118:121], v[82:97]
	v_xor_b32_e32 v16, 0x80, v16
	ds_read_b128 v[4:7], v16 offset:32768
	ds_read_b128 v[8:11], v16 offset:40960
	v_xor_b32_e32 v17, 0x80, v17
	ds_read_b128 v[12:15], v17 offset:32768
	ds_read_b128 v[184:187], v17 offset:40960
	s_waitcnt lgkmcnt(7)
	v_mfma_f32_32x32x16_f16 v[98:113], v[188:191], v[122:125], v[98:113]
	s_waitcnt lgkmcnt(6)
	v_mfma_f32_32x32x16_f16 v[82:97], v[192:195], v[122:125], v[82:97]
	s_waitcnt lgkmcnt(5)
	v_mfma_f32_32x32x16_f16 v[98:113], v[204:207], v[126:129], v[98:113]
	s_waitcnt lgkmcnt(4)
	v_mfma_f32_32x32x16_f16 v[82:97], v[220:223], v[126:129], v[82:97]
	v_xor_b32_e32 v196, 0x80, v196
	ds_read_b128 v[188:191], v196 offset:32768
	ds_read_b128 v[192:195], v196 offset:40960
	v_xor_b32_e32 v197, 0x80, v197
	ds_read_b128 v[204:207], v197 offset:32768
	ds_read_b128 v[220:223], v197 offset:40960
	s_waitcnt lgkmcnt(7)
	v_mfma_f32_32x32x16_f16 v[98:113], v[4:7], v[130:133], v[98:113]
	s_waitcnt lgkmcnt(6)
	v_mfma_f32_32x32x16_f16 v[82:97], v[8:11], v[130:133], v[82:97]
	s_waitcnt lgkmcnt(5)
	v_mfma_f32_32x32x16_f16 v[98:113], v[12:15], v[138:141], v[98:113]
	s_waitcnt lgkmcnt(4)
	v_mfma_f32_32x32x16_f16 v[82:97], v[184:187], v[138:141], v[82:97]
	s_waitcnt lgkmcnt(3)
	v_mfma_f32_32x32x16_f16 v[98:113], v[188:191], v[142:145], v[98:113]
	s_cmp_le_i32 s12, s2
	s_cselect_b64 s[12:13], -1, 0
	s_cmp_gt_i32 s22, s37
	s_cselect_b64 s[38:39], -1, 0
	s_and_b64 s[12:13], s[12:13], s[38:39]
	s_and_b64 vcc, exec, s[12:13]
	s_waitcnt lgkmcnt(2)
	v_mfma_f32_32x32x16_f16 v[82:97], v[192:195], v[142:145], v[82:97]
	s_waitcnt lgkmcnt(1)
	v_mfma_f32_32x32x16_f16 v[98:113], v[204:207], v[150:153], v[98:113]
	s_waitcnt lgkmcnt(0)
	v_mfma_f32_32x32x16_f16 v[82:97], v[220:223], v[150:153], v[82:97]
	s_cbranch_vccnz .LBB0_5011
	v_add_u32_e32 v4, 59, v181
	v_cmp_gt_u32_e32 vcc, s18, v4
	v_add_u32_e32 v4, 27, v181
	s_nop 5
	v_cndmask_b32_e32 v98, v218, v98, vcc
	v_cmp_gt_u32_e32 vcc, s18, v4
	v_add_u32_e32 v4, 58, v181
	s_nop 0
	v_cndmask_b32_e32 v82, v218, v82, vcc
	v_cmp_gt_u32_e32 vcc, s18, v4
	v_add_u32_e32 v4, 26, v181
	s_nop 0
	v_cndmask_b32_e32 v99, v218, v99, vcc
	v_cmp_gt_u32_e32 vcc, s18, v4
	v_add_u32_e32 v4, 57, v181
	s_nop 0
	v_cndmask_b32_e32 v83, v218, v83, vcc
	v_cmp_gt_u32_e32 vcc, s18, v4
	v_add_u32_e32 v4, 25, v181
	s_nop 0
	v_cndmask_b32_e32 v100, v218, v100, vcc
	v_cmp_gt_u32_e32 vcc, s18, v4
	v_add_u32_e32 v4, 56, v181
	s_nop 0
	v_cndmask_b32_e32 v84, v218, v84, vcc
	v_cmp_gt_u32_e32 vcc, s18, v4
	v_add_u32_e32 v4, 24, v181
	s_nop 0
	v_cndmask_b32_e32 v101, v218, v101, vcc
	v_cmp_gt_u32_e32 vcc, s18, v4
	v_add_u32_e32 v4, 51, v181
	s_nop 0
	v_cndmask_b32_e32 v85, v218, v85, vcc
	v_cmp_gt_u32_e32 vcc, s18, v4
	v_add_u32_e32 v4, 19, v181
	s_nop 0
	v_cndmask_b32_e32 v102, v218, v102, vcc
	v_cmp_gt_u32_e32 vcc, s18, v4
	v_add_u32_e32 v4, 50, v181
	s_nop 0
	v_cndmask_b32_e32 v86, v218, v86, vcc
	v_cmp_gt_u32_e32 vcc, s18, v4
	v_add_u32_e32 v4, 18, v181
	s_nop 0
	v_cndmask_b32_e32 v103, v218, v103, vcc
	v_cmp_gt_u32_e32 vcc, s18, v4
	v_add_u32_e32 v4, 49, v181
	s_nop 0
	v_cndmask_b32_e32 v87, v218, v87, vcc
	v_cmp_gt_u32_e32 vcc, s18, v4
	v_add_u32_e32 v4, 17, v181
	s_nop 0
	v_cndmask_b32_e32 v104, v218, v104, vcc
	v_cmp_gt_u32_e32 vcc, s18, v4
	v_add_u32_e32 v4, 48, v181
	s_nop 0
	v_cndmask_b32_e32 v88, v218, v88, vcc
	v_cmp_gt_u32_e32 vcc, s18, v4
	v_add_u32_e32 v4, 16, v181
	s_nop 0
	v_cndmask_b32_e32 v105, v218, v105, vcc
	v_cmp_gt_u32_e32 vcc, s18, v4
	v_add_u32_e32 v4, 43, v181
	s_nop 0
	v_cndmask_b32_e32 v89, v218, v89, vcc
	v_cmp_gt_u32_e32 vcc, s18, v4
	v_add_u32_e32 v4, 11, v181
	s_nop 0
	v_cndmask_b32_e32 v106, v218, v106, vcc
	v_cmp_gt_u32_e32 vcc, s18, v4
	v_add_u32_e32 v4, 42, v181
	s_nop 0
	v_cndmask_b32_e32 v90, v218, v90, vcc
	v_cmp_gt_u32_e32 vcc, s18, v4
	v_add_u32_e32 v4, 10, v181
	s_nop 0
	v_cndmask_b32_e32 v107, v218, v107, vcc
	v_cmp_gt_u32_e32 vcc, s18, v4
	v_add_u32_e32 v4, 41, v181
	s_nop 0
	v_cndmask_b32_e32 v91, v218, v91, vcc
	v_cmp_gt_u32_e32 vcc, s18, v4
	v_add_u32_e32 v4, 9, v181
	s_nop 0
	v_cndmask_b32_e32 v108, v218, v108, vcc
	v_cmp_gt_u32_e32 vcc, s18, v4
	v_add_u32_e32 v4, 40, v181
	s_nop 0
	v_cndmask_b32_e32 v92, v218, v92, vcc
	v_cmp_gt_u32_e32 vcc, s18, v4
	v_add_u32_e32 v4, 8, v181
	s_nop 0
	v_cndmask_b32_e32 v109, v218, v109, vcc
	v_cmp_gt_u32_e32 vcc, s18, v4
	v_add_u32_e32 v4, 35, v181
	s_nop 0
	v_cndmask_b32_e32 v93, v218, v93, vcc
	v_cmp_gt_u32_e32 vcc, s18, v4
	v_add_u32_e32 v4, 3, v181
	s_nop 0
	v_cndmask_b32_e32 v110, v218, v110, vcc
	v_cmp_gt_u32_e32 vcc, s18, v4
	v_add_u32_e32 v4, 34, v181
	s_nop 0
	v_cndmask_b32_e32 v94, v218, v94, vcc
	v_cmp_gt_u32_e32 vcc, s18, v4
	v_add_u32_e32 v4, 2, v181
	s_nop 0
	v_cndmask_b32_e32 v111, v218, v111, vcc
	v_cmp_gt_u32_e32 vcc, s18, v4
	v_add_u32_e32 v4, 33, v181
	s_nop 0
	v_cndmask_b32_e32 v95, v218, v95, vcc
	v_cmp_gt_u32_e32 vcc, s18, v4
	v_add_u32_e32 v4, 1, v181
	s_nop 0
	v_cndmask_b32_e32 v112, v218, v112, vcc
	v_cmp_gt_u32_e32 vcc, s18, v4
	v_add_u32_e32 v4, 32, v181
	s_nop 0
	v_cndmask_b32_e32 v96, v218, v96, vcc
	v_cmp_gt_u32_e32 vcc, s18, v4
	s_nop 1
	v_cndmask_b32_e32 v113, v218, v113, vcc
	v_cmp_gt_u32_e32 vcc, s18, v181
	s_nop 1
	v_cndmask_b32_e32 v97, v218, v97, vcc
